# strategy 9 (7.11): GEMM K-loops' loop-back SALU block (counter, pointer bumps, exit compare) moved in front of the loop's last barrier (on top of v023)
# baseline (speedup 1.0000x reference)
; #define PG8_STAGE(bufoff, gbase, voff) do { _Pragma("unroll") for (int _i = 0; _i < 2; ++_i) \
;         __builtin_amdgcn_global_load_lds((const unsigned*)((const char*)(gbase) + (voff)[_i]), (PG8_LAS unsigned*)(lds + (bufoff) + ldsw + _i * 8192), 16, 0, 0); } while (0)
; #define PG8_LDA(dst, b, h) do { _Pragma("unroll") for (int m = 0; m < 4; ++m) _Pragma("unroll") for (int k = 0; k < 2; ++k) dst[m][k] = *(const PG8_LAS bf16x8*)(lds + PG8_SA(b, h) + aoff + m * 2048 + k * 1024); } while (0)
; #define PG8_LDB(dst, b, h) do { _Pragma("unroll") for (int n = 0; n < 2; ++n) _Pragma("unroll") for (int k = 0; k < 2; ++k) dst[n][k] = *(const PG8_LAS bf16x8*)(lds + PG8_SB(b, h) + boff + n * 2048 + k * 1024); } while (0)
; #define PG8_MMA(ai, bj, At, Bt) do { __builtin_amdgcn_s_setprio(1); _Pragma("unroll") for (int m = 0; m < 4; ++m) _Pragma("unroll") for (int n = 0; n < 2; ++n) _Pragma("unroll") for (int k = 0; k < 2; ++k) \
;         acc[ai][bj][m][n] = __builtin_amdgcn_mfma_f32_16x16x32_bf16(Bt[n][k], At[m][k], acc[ai][bj][m][n], 0, 0, 0); __builtin_amdgcn_s_setprio(0); } while (0)
; #define PG8_WAIT_V(n) asm volatile("s_waitcnt vmcnt(" #n ")" ::: "memory")
; #define PG8_WAIT_L(n) asm volatile("s_waitcnt lgkmcnt(" #n ")" ::: "memory")
; #define PG8_BAR __builtin_amdgcn_s_barrier()
; #define PG8_SCHED __builtin_amdgcn_sched_barrier(0)
; template <class Epi, class Sched, bool ALIGN_EPI = false, bool SP2 = false>
; __device__ __forceinline__ void gemm_phase(PG8_LAS unsigned char* lds, const Gemm g, const Sched& S, const Epi& E) {
;     ...
;             PG8_LDB(B0, 0, 0); PG8_LDB(B1, 0, 1); PG8_SCHED; PG8_LDA(At, 0, 0); PG8_STAGE(PG8_SA(1, 1), a1 + hstep, voffA);
;             PG8_WAIT_V(8); PG8_WAIT_L(0); PG8_BAR; PG8_MMA(0, 0, At, B0); PG8_MMA(0, 1, At, B1); PG8_BAR; PG8_SCHED;
;             PG8_LDA(At, 0, 1); PG8_STAGE(PG8_SB(0, 0), b2, voffB); PG8_STAGE(PG8_SB(0, 1), b2 + hstep, voffB); PG8_STAGE(PG8_SA(0, 0), a2, voffA);
.LBB0_351:
	ds_read_b128 v[146:149], v154
	ds_read_b128 v[158:161], v154 offset:1024
	ds_read_b128 v[162:165], v154 offset:2048
	ds_read_b128 v[166:169], v154 offset:3072
	ds_read_b128 v[170:173], v155
	ds_read_b128 v[174:177], v155 offset:1024
	ds_read_b128 v[178:181], v155 offset:2048
	ds_read_b128 v[182:185], v155 offset:3072
	s_add_u32 s22, s20, 0xfff80080
	s_addc_u32 s23, s21, -1
	s_cmp_eq_u32 s53, 28
	s_cselect_b32 s25, s13, s23
	s_cselect_b32 s24, s43, s22
	s_cselect_b32 s23, s11, s52
	s_cselect_b32 s22, s44, s45
	v_lshl_add_u64 v[218:219], s[20:21], 0, v[138:139]
	s_add_i32 m0, s19, 0xc000
	ds_read_b128 v[186:189], v156
	ds_read_b128 v[190:193], v156 offset:1024
	ds_read_b128 v[194:197], v156 offset:2048
	ds_read_b128 v[198:201], v156 offset:3072
	ds_read_b128 v[202:205], v156 offset:4096
	ds_read_b128 v[206:209], v156 offset:5120
	ds_read_b128 v[210:213], v156 offset:6144
	ds_read_b128 v[214:217], v156 offset:7168
	global_load_lds_dwordx4 v[218:219], off
	v_lshl_add_u64 v[218:219], s[20:21], 0, v[140:141]
	s_add_i32 m0, s19, 0xe000
	s_nop 0
	global_load_lds_dwordx4 v[218:219], off
	s_waitcnt vmcnt(8)
	s_waitcnt lgkmcnt(0)
	s_barrier
	s_setprio 1
	s_waitcnt lgkmcnt(0)
	v_mfma_f32_16x16x32_bf16 v[126:129], v[146:149], v[186:189], v[126:129]
	v_mfma_f32_16x16x32_bf16 v[122:125], v[162:165], v[186:189], v[122:125]
	v_mfma_f32_16x16x32_bf16 v[110:113], v[146:149], v[194:197], v[110:113]
	v_mfma_f32_16x16x32_bf16 v[106:109], v[162:165], v[194:197], v[106:109]
	v_mfma_f32_16x16x32_bf16 v[94:97], v[146:149], v[202:205], v[94:97]
	v_mfma_f32_16x16x32_bf16 v[90:93], v[162:165], v[202:205], v[90:93]
	v_mfma_f32_16x16x32_bf16 v[78:81], v[146:149], v[210:213], v[78:81]
	v_mfma_f32_16x16x32_bf16 v[74:77], v[162:165], v[210:213], v[74:77]
	v_mfma_f32_16x16x32_bf16 v[126:129], v[158:161], v[190:193], v[126:129]
	v_mfma_f32_16x16x32_bf16 v[122:125], v[166:169], v[190:193], v[122:125]
	v_mfma_f32_16x16x32_bf16 v[110:113], v[158:161], v[198:201], v[110:113]
	v_mfma_f32_16x16x32_bf16 v[106:109], v[166:169], v[198:201], v[106:109]
	v_mfma_f32_16x16x32_bf16 v[94:97], v[158:161], v[206:209], v[94:97]
	v_mfma_f32_16x16x32_bf16 v[90:93], v[166:169], v[206:209], v[90:93]
	v_mfma_f32_16x16x32_bf16 v[78:81], v[158:161], v[214:217], v[78:81]
	v_mfma_f32_16x16x32_bf16 v[74:77], v[166:169], v[214:217], v[74:77]
	s_setprio 0
	s_setprio 1
	v_mfma_f32_16x16x32_bf16 v[118:121], v[170:173], v[186:189], v[118:121]
	v_mfma_f32_16x16x32_bf16 v[114:117], v[178:181], v[186:189], v[114:117]
	v_mfma_f32_16x16x32_bf16 v[102:105], v[170:173], v[194:197], v[102:105]
	v_mfma_f32_16x16x32_bf16 v[98:101], v[178:181], v[194:197], v[98:101]
	v_mfma_f32_16x16x32_bf16 v[86:89], v[170:173], v[202:205], v[86:89]
	v_mfma_f32_16x16x32_bf16 v[82:85], v[178:181], v[202:205], v[82:85]
	v_mfma_f32_16x16x32_bf16 v[70:73], v[170:173], v[210:213], v[70:73]
	v_mfma_f32_16x16x32_bf16 v[66:69], v[178:181], v[210:213], v[66:69]
	v_mfma_f32_16x16x32_bf16 v[118:121], v[174:177], v[190:193], v[118:121]
	v_mfma_f32_16x16x32_bf16 v[114:117], v[182:185], v[190:193], v[114:117]
	v_mfma_f32_16x16x32_bf16 v[102:105], v[174:177], v[198:201], v[102:105]
	v_mfma_f32_16x16x32_bf16 v[98:101], v[182:185], v[198:201], v[98:101]
	v_mfma_f32_16x16x32_bf16 v[86:89], v[174:177], v[206:209], v[86:89]
	v_mfma_f32_16x16x32_bf16 v[82:85], v[182:185], v[206:209], v[82:85]
	v_mfma_f32_16x16x32_bf16 v[70:73], v[174:177], v[214:217], v[70:73]
	v_mfma_f32_16x16x32_bf16 v[66:69], v[182:185], v[214:217], v[66:69]
	s_setprio 0
	s_barrier
	s_add_i32 s54, s35, s2
	v_lshl_add_u64 v[218:219], s[22:23], 0, v[134:135]
	s_mov_b32 m0, s54
	ds_read_b128 v[186:189], v156 offset:16384
	ds_read_b128 v[190:193], v156 offset:17408
	ds_read_b128 v[194:197], v156 offset:18432
	ds_read_b128 v[198:201], v156 offset:19456
	ds_read_b128 v[202:205], v156 offset:20480
	ds_read_b128 v[206:209], v156 offset:21504
	ds_read_b128 v[210:213], v156 offset:22528
	ds_read_b128 v[214:217], v156 offset:23552
	global_load_lds_dwordx4 v[218:219], off
	s_add_i32 m0, s54, 0x2000
	s_add_u32 s54, s22, 0x80000
	v_lshl_add_u64 v[220:221], s[22:23], 0, v[130:131]
	s_addc_u32 s55, s23, 0
	s_add_i32 s56, s38, s2
	global_load_lds_dwordx4 v[220:221], off
	v_lshl_add_u64 v[222:223], s[54:55], 0, v[134:135]
	s_mov_b32 m0, s56
	v_lshl_add_u64 v[224:225], s[24:25], 0, v[132:133]
	global_load_lds_dwordx4 v[222:223], off
	v_lshl_add_u64 v[222:223], s[54:55], 0, v[130:131]
	s_add_i32 m0, s56, 0x2000
	s_nop 0
	global_load_lds_dwordx4 v[222:223], off
	v_lshl_add_u64 v[222:223], s[24:25], 0, v[136:137]
	s_mov_b32 m0, s19
	s_nop 0
	global_load_lds_dwordx4 v[222:223], off
	s_mov_b32 m0, s27
	s_nop 0
	global_load_lds_dwordx4 v[224:225], off
	s_waitcnt vmcnt(8)
	s_waitcnt lgkmcnt(0)
	s_barrier
; #define PG8_STAGE(bufoff, gbase, voff) do { _Pragma("unroll") for (int _i = 0; _i < 2; ++_i) \
;         __builtin_amdgcn_global_load_lds((const unsigned*)((const char*)(gbase) + (voff)[_i]), (PG8_LAS unsigned*)(lds + (bufoff) + ldsw + _i * 8192), 16, 0, 0); } while (0)
; #define PG8_LDA(dst, b, h) do { _Pragma("unroll") for (int m = 0; m < 4; ++m) _Pragma("unroll") for (int k = 0; k < 2; ++k) dst[m][k] = *(const PG8_LAS bf16x8*)(lds + PG8_SA(b, h) + aoff + m * 2048 + k * 1024); } while (0)
; #define PG8_LDB(dst, b, h) do { _Pragma("unroll") for (int n = 0; n < 2; ++n) _Pragma("unroll") for (int k = 0; k < 2; ++k) dst[n][k] = *(const PG8_LAS bf16x8*)(lds + PG8_SB(b, h) + boff + n * 2048 + k * 1024); } while (0)
; #define PG8_MMA(ai, bj, At, Bt) do { __builtin_amdgcn_s_setprio(1); _Pragma("unroll") for (int m = 0; m < 4; ++m) _Pragma("unroll") for (int n = 0; n < 2; ++n) _Pragma("unroll") for (int k = 0; k < 2; ++k) \
;         acc[ai][bj][m][n] = __builtin_amdgcn_mfma_f32_16x16x32_bf16(Bt[n][k], At[m][k], acc[ai][bj][m][n], 0, 0, 0); __builtin_amdgcn_s_setprio(0); } while (0)
; #define PG8_WAIT_V(n) asm volatile("s_waitcnt vmcnt(" #n ")" ::: "memory")
; #define PG8_WAIT_L(n) asm volatile("s_waitcnt lgkmcnt(" #n ")" ::: "memory")
; #define PG8_BAR __builtin_amdgcn_s_barrier()
; #define PG8_SCHED __builtin_amdgcn_sched_barrier(0)
; template <class Epi, class Sched, bool ALIGN_EPI = false, bool SP2 = false>
; __device__ __forceinline__ void gemm_phase(PG8_LAS unsigned char* lds, const Gemm g, const Sched& S, const Epi& E) {
;     ...
;             PG8_WAIT_V(8); PG8_WAIT_L(0); PG8_BAR; PG8_MMA(1, 0, At, B0); PG8_MMA(1, 1, At, B1); PG8_BAR; PG8_SCHED;
;             PG8_LDB(B0, 1, 0); PG8_LDB(B1, 1, 1); PG8_SCHED; PG8_LDA(At, 1, 0); PG8_STAGE(PG8_SA(0, 1), a2 + hstep, voffA);
;             PG8_WAIT_V(8); PG8_WAIT_L(0); PG8_BAR; PG8_MMA(0, 0, At, B0); PG8_MMA(0, 1, At, B1); PG8_BAR; PG8_SCHED;
	s_setprio 1
	s_waitcnt lgkmcnt(0)
	v_mfma_f32_16x16x32_bf16 v[62:65], v[146:149], v[186:189], v[62:65]
	v_mfma_f32_16x16x32_bf16 v[58:61], v[162:165], v[186:189], v[58:61]
	v_mfma_f32_16x16x32_bf16 v[46:49], v[146:149], v[194:197], v[46:49]
	v_mfma_f32_16x16x32_bf16 v[42:45], v[162:165], v[194:197], v[42:45]
	v_mfma_f32_16x16x32_bf16 v[30:33], v[146:149], v[202:205], v[30:33]
	v_mfma_f32_16x16x32_bf16 v[26:29], v[162:165], v[202:205], v[26:29]
	v_mfma_f32_16x16x32_bf16 v[14:17], v[146:149], v[210:213], v[14:17]
	v_mfma_f32_16x16x32_bf16 v[10:13], v[162:165], v[210:213], v[10:13]
	v_mfma_f32_16x16x32_bf16 v[62:65], v[158:161], v[190:193], v[62:65]
	v_mfma_f32_16x16x32_bf16 v[58:61], v[166:169], v[190:193], v[58:61]
	v_mfma_f32_16x16x32_bf16 v[46:49], v[158:161], v[198:201], v[46:49]
	v_mfma_f32_16x16x32_bf16 v[42:45], v[166:169], v[198:201], v[42:45]
	v_mfma_f32_16x16x32_bf16 v[30:33], v[158:161], v[206:209], v[30:33]
	v_mfma_f32_16x16x32_bf16 v[26:29], v[166:169], v[206:209], v[26:29]
	v_mfma_f32_16x16x32_bf16 v[14:17], v[158:161], v[214:217], v[14:17]
	v_mfma_f32_16x16x32_bf16 v[10:13], v[166:169], v[214:217], v[10:13]
	s_setprio 0
	s_setprio 1
	v_mfma_f32_16x16x32_bf16 v[54:57], v[170:173], v[186:189], v[54:57]
	v_mfma_f32_16x16x32_bf16 v[50:53], v[178:181], v[186:189], v[50:53]
	v_mfma_f32_16x16x32_bf16 v[38:41], v[170:173], v[194:197], v[38:41]
	v_mfma_f32_16x16x32_bf16 v[34:37], v[178:181], v[194:197], v[34:37]
	v_mfma_f32_16x16x32_bf16 v[22:25], v[170:173], v[202:205], v[22:25]
	v_mfma_f32_16x16x32_bf16 v[18:21], v[178:181], v[202:205], v[18:21]
	v_mfma_f32_16x16x32_bf16 v[6:9], v[170:173], v[210:213], v[6:9]
	v_mfma_f32_16x16x32_bf16 v[2:5], v[178:181], v[210:213], v[2:5]
	v_mfma_f32_16x16x32_bf16 v[54:57], v[174:177], v[190:193], v[54:57]
	v_mfma_f32_16x16x32_bf16 v[50:53], v[182:185], v[190:193], v[50:53]
	v_mfma_f32_16x16x32_bf16 v[38:41], v[174:177], v[198:201], v[38:41]
	v_mfma_f32_16x16x32_bf16 v[34:37], v[182:185], v[198:201], v[34:37]
	v_mfma_f32_16x16x32_bf16 v[22:25], v[174:177], v[206:209], v[22:25]
	v_mfma_f32_16x16x32_bf16 v[18:21], v[182:185], v[206:209], v[18:21]
	v_mfma_f32_16x16x32_bf16 v[6:9], v[174:177], v[214:217], v[6:9]
	v_mfma_f32_16x16x32_bf16 v[2:5], v[182:185], v[214:217], v[2:5]
	s_setprio 0
	s_barrier
	s_add_i32 s54, 0, 0x18000
	v_add_u32_e32 v157, s54, v150
	s_add_i32 s55, 0, 0x1c000
	ds_read_b128 v[146:149], v157
	ds_read_b128 v[158:161], v157 offset:1024
	ds_read_b128 v[162:165], v157 offset:2048
	ds_read_b128 v[166:169], v157 offset:3072
	v_add_u32_e32 v157, s55, v150
	ds_read_b128 v[170:173], v157
	ds_read_b128 v[174:177], v157 offset:1024
	ds_read_b128 v[178:181], v157 offset:2048
	ds_read_b128 v[182:185], v157 offset:3072
	s_add_u32 s24, s24, 0x80000
	s_addc_u32 s25, s25, 0
	s_mov_b32 m0, s28
	v_lshl_add_u64 v[226:227], s[24:25], 0, v[136:137]
	ds_read_b128 v[186:189], v156 offset:32768
	ds_read_b128 v[190:193], v156 offset:33792
	ds_read_b128 v[194:197], v156 offset:34816
	ds_read_b128 v[198:201], v156 offset:35840
	ds_read_b128 v[202:205], v156 offset:36864
	ds_read_b128 v[206:209], v156 offset:37888
	ds_read_b128 v[210:213], v156 offset:38912
	ds_read_b128 v[214:217], v156 offset:39936
	global_load_lds_dwordx4 v[226:227], off
	v_lshl_add_u64 v[226:227], s[24:25], 0, v[132:133]
	s_mov_b32 m0, s29
	s_nop 0
	global_load_lds_dwordx4 v[226:227], off
	s_waitcnt vmcnt(8)
	s_waitcnt lgkmcnt(0)
	s_barrier
	s_setprio 1
	s_waitcnt lgkmcnt(0)
	v_mfma_f32_16x16x32_bf16 v[126:129], v[146:149], v[186:189], v[126:129]
	v_mfma_f32_16x16x32_bf16 v[122:125], v[162:165], v[186:189], v[122:125]
	v_mfma_f32_16x16x32_bf16 v[110:113], v[146:149], v[194:197], v[110:113]
	v_mfma_f32_16x16x32_bf16 v[106:109], v[162:165], v[194:197], v[106:109]
	v_mfma_f32_16x16x32_bf16 v[94:97], v[146:149], v[202:205], v[94:97]
	v_mfma_f32_16x16x32_bf16 v[90:93], v[162:165], v[202:205], v[90:93]
	v_mfma_f32_16x16x32_bf16 v[78:81], v[146:149], v[210:213], v[78:81]
	v_mfma_f32_16x16x32_bf16 v[74:77], v[162:165], v[210:213], v[74:77]
	v_mfma_f32_16x16x32_bf16 v[126:129], v[158:161], v[190:193], v[126:129]
	v_mfma_f32_16x16x32_bf16 v[122:125], v[166:169], v[190:193], v[122:125]
	v_mfma_f32_16x16x32_bf16 v[110:113], v[158:161], v[198:201], v[110:113]
	v_mfma_f32_16x16x32_bf16 v[106:109], v[166:169], v[198:201], v[106:109]
	v_mfma_f32_16x16x32_bf16 v[94:97], v[158:161], v[206:209], v[94:97]
	v_mfma_f32_16x16x32_bf16 v[90:93], v[166:169], v[206:209], v[90:93]
	v_mfma_f32_16x16x32_bf16 v[78:81], v[158:161], v[214:217], v[78:81]
	v_mfma_f32_16x16x32_bf16 v[74:77], v[166:169], v[214:217], v[74:77]
	s_setprio 0
	s_setprio 1
	v_mfma_f32_16x16x32_bf16 v[118:121], v[170:173], v[186:189], v[118:121]
	v_mfma_f32_16x16x32_bf16 v[114:117], v[178:181], v[186:189], v[114:117]
	v_mfma_f32_16x16x32_bf16 v[102:105], v[170:173], v[194:197], v[102:105]
	v_mfma_f32_16x16x32_bf16 v[98:101], v[178:181], v[194:197], v[98:101]
	v_mfma_f32_16x16x32_bf16 v[86:89], v[170:173], v[202:205], v[86:89]
	v_mfma_f32_16x16x32_bf16 v[82:85], v[178:181], v[202:205], v[82:85]
	v_mfma_f32_16x16x32_bf16 v[70:73], v[170:173], v[210:213], v[70:73]
	v_mfma_f32_16x16x32_bf16 v[66:69], v[178:181], v[210:213], v[66:69]
	v_mfma_f32_16x16x32_bf16 v[118:121], v[174:177], v[190:193], v[118:121]
	v_mfma_f32_16x16x32_bf16 v[114:117], v[182:185], v[190:193], v[114:117]
	v_mfma_f32_16x16x32_bf16 v[102:105], v[174:177], v[198:201], v[102:105]
	v_mfma_f32_16x16x32_bf16 v[98:101], v[182:185], v[198:201], v[98:101]
	v_mfma_f32_16x16x32_bf16 v[86:89], v[174:177], v[206:209], v[86:89]
	v_mfma_f32_16x16x32_bf16 v[82:85], v[182:185], v[206:209], v[82:85]
	v_mfma_f32_16x16x32_bf16 v[70:73], v[174:177], v[214:217], v[70:73]
	v_mfma_f32_16x16x32_bf16 v[66:69], v[182:185], v[214:217], v[66:69]
	s_setprio 0
	s_barrier
; #define PG8_STAGE(bufoff, gbase, voff) do { _Pragma("unroll") for (int _i = 0; _i < 2; ++_i) \
;         __builtin_amdgcn_global_load_lds((const unsigned*)((const char*)(gbase) + (voff)[_i]), (PG8_LAS unsigned*)(lds + (bufoff) + ldsw + _i * 8192), 16, 0, 0); } while (0)
; #define PG8_LDA(dst, b, h) do { _Pragma("unroll") for (int m = 0; m < 4; ++m) _Pragma("unroll") for (int k = 0; k < 2; ++k) dst[m][k] = *(const PG8_LAS bf16x8*)(lds + PG8_SA(b, h) + aoff + m * 2048 + k * 1024); } while (0)
; #define PG8_MMA(ai, bj, At, Bt) do { __builtin_amdgcn_s_setprio(1); _Pragma("unroll") for (int m = 0; m < 4; ++m) _Pragma("unroll") for (int n = 0; n < 2; ++n) _Pragma("unroll") for (int k = 0; k < 2; ++k) \
;         acc[ai][bj][m][n] = __builtin_amdgcn_mfma_f32_16x16x32_bf16(Bt[n][k], At[m][k], acc[ai][bj][m][n], 0, 0, 0); __builtin_amdgcn_s_setprio(0); } while (0)
; #define PG8_WAIT_V(n) asm volatile("s_waitcnt vmcnt(" #n ")" ::: "memory")
; #define PG8_WAIT_L(n) asm volatile("s_waitcnt lgkmcnt(" #n ")" ::: "memory")
; #define PG8_BAR __builtin_amdgcn_s_barrier()
; #define PG8_SCHED __builtin_amdgcn_sched_barrier(0)
; template <class Epi, class Sched, bool ALIGN_EPI = false, bool SP2 = false>
; __device__ __forceinline__ void gemm_phase(PG8_LAS unsigned char* lds, const Gemm g, const Sched& S, const Epi& E) {
;     ...
;             PG8_LDA(At, 1, 1); PG8_STAGE(PG8_SB(1, 0), b3, voffB); PG8_STAGE(PG8_SB(1, 1), b3 + hstep, voffB); PG8_STAGE(PG8_SA(1, 0), a3, voffA);
;             PG8_WAIT_V(8); PG8_WAIT_L(0); PG8_BAR; PG8_MMA(1, 0, At, B0); PG8_MMA(1, 1, At, B1); PG8_BAR; PG8_SCHED;
	s_add_i32 s24, s54, s2
	v_lshl_add_u64 v[218:219], v[218:219], 0, s[6:7]
	s_mov_b32 m0, s24
	ds_read_b128 v[186:189], v156 offset:49152
	ds_read_b128 v[190:193], v156 offset:50176
	ds_read_b128 v[194:197], v156 offset:51200
	ds_read_b128 v[198:201], v156 offset:52224
	ds_read_b128 v[202:205], v156 offset:53248
	ds_read_b128 v[206:209], v156 offset:54272
	ds_read_b128 v[210:213], v156 offset:55296
	ds_read_b128 v[214:217], v156 offset:56320
	global_load_lds_dwordx4 v[218:219], off
	s_add_i32 m0, s24, 0x2000
	s_add_u32 s22, s22, 0x80080
	v_lshl_add_u64 v[218:219], v[220:221], 0, s[6:7]
	s_addc_u32 s23, s23, 0
	s_add_i32 s24, s55, s2
	global_load_lds_dwordx4 v[218:219], off
	v_lshl_add_u64 v[218:219], s[22:23], 0, v[134:135]
	s_mov_b32 m0, s24
	s_nop 0
	global_load_lds_dwordx4 v[218:219], off
	v_lshl_add_u64 v[218:219], s[22:23], 0, v[130:131]
	s_add_i32 m0, s24, 0x2000
	s_nop 0
	global_load_lds_dwordx4 v[218:219], off
	v_lshl_add_u64 v[218:219], v[222:223], 0, s[6:7]
	s_mov_b32 m0, s31
	s_nop 0
	global_load_lds_dwordx4 v[218:219], off
	v_lshl_add_u64 v[218:219], v[224:225], 0, s[6:7]
	s_mov_b32 m0, s33
	s_nop 0
	global_load_lds_dwordx4 v[218:219], off
	s_waitcnt vmcnt(8)
	s_waitcnt lgkmcnt(0)
	s_barrier
	s_setprio 1
	s_waitcnt lgkmcnt(0)
	v_mfma_f32_16x16x32_bf16 v[62:65], v[146:149], v[186:189], v[62:65]
	v_mfma_f32_16x16x32_bf16 v[58:61], v[162:165], v[186:189], v[58:61]
	v_mfma_f32_16x16x32_bf16 v[46:49], v[146:149], v[194:197], v[46:49]
	v_mfma_f32_16x16x32_bf16 v[42:45], v[162:165], v[194:197], v[42:45]
	v_mfma_f32_16x16x32_bf16 v[30:33], v[146:149], v[202:205], v[30:33]
	v_mfma_f32_16x16x32_bf16 v[26:29], v[162:165], v[202:205], v[26:29]
	v_mfma_f32_16x16x32_bf16 v[14:17], v[146:149], v[210:213], v[14:17]
	v_mfma_f32_16x16x32_bf16 v[10:13], v[162:165], v[210:213], v[10:13]
	v_mfma_f32_16x16x32_bf16 v[62:65], v[158:161], v[190:193], v[62:65]
	v_mfma_f32_16x16x32_bf16 v[58:61], v[166:169], v[190:193], v[58:61]
	v_mfma_f32_16x16x32_bf16 v[46:49], v[158:161], v[198:201], v[46:49]
	v_mfma_f32_16x16x32_bf16 v[42:45], v[166:169], v[198:201], v[42:45]
	v_mfma_f32_16x16x32_bf16 v[30:33], v[158:161], v[206:209], v[30:33]
	v_mfma_f32_16x16x32_bf16 v[26:29], v[166:169], v[206:209], v[26:29]
	v_mfma_f32_16x16x32_bf16 v[14:17], v[158:161], v[214:217], v[14:17]
	v_mfma_f32_16x16x32_bf16 v[10:13], v[166:169], v[214:217], v[10:13]
	s_setprio 0
	s_setprio 1
	v_mfma_f32_16x16x32_bf16 v[54:57], v[170:173], v[186:189], v[54:57]
	v_mfma_f32_16x16x32_bf16 v[50:53], v[178:181], v[186:189], v[50:53]
	v_mfma_f32_16x16x32_bf16 v[38:41], v[170:173], v[194:197], v[38:41]
	v_mfma_f32_16x16x32_bf16 v[34:37], v[178:181], v[194:197], v[34:37]
	v_mfma_f32_16x16x32_bf16 v[22:25], v[170:173], v[202:205], v[22:25]
	v_mfma_f32_16x16x32_bf16 v[18:21], v[178:181], v[202:205], v[18:21]
	v_mfma_f32_16x16x32_bf16 v[6:9], v[170:173], v[210:213], v[6:9]
	v_mfma_f32_16x16x32_bf16 v[2:5], v[178:181], v[210:213], v[2:5]
	v_mfma_f32_16x16x32_bf16 v[54:57], v[174:177], v[190:193], v[54:57]
	v_mfma_f32_16x16x32_bf16 v[50:53], v[182:185], v[190:193], v[50:53]
	v_mfma_f32_16x16x32_bf16 v[38:41], v[174:177], v[198:201], v[38:41]
	v_mfma_f32_16x16x32_bf16 v[34:37], v[182:185], v[198:201], v[34:37]
	v_mfma_f32_16x16x32_bf16 v[22:25], v[174:177], v[206:209], v[22:25]
	v_mfma_f32_16x16x32_bf16 v[18:21], v[182:185], v[206:209], v[18:21]
	v_mfma_f32_16x16x32_bf16 v[6:9], v[174:177], v[214:217], v[6:9]
	v_mfma_f32_16x16x32_bf16 v[2:5], v[182:185], v[214:217], v[2:5]
	s_setprio 0
	s_add_i32 s53, s53, 2
	s_add_u32 s20, s20, 0x100
	s_addc_u32 s21, s21, 0
	s_add_u32 s45, s45, 0x100
	s_addc_u32 s52, s52, 0
	s_cmp_gt_u32 s53, 29
	s_barrier
	s_cbranch_scc0 .LBB0_351
	s_and_b64 vcc, exec, s[8:9]
	s_cbranch_vccz .LBB0_354
	s_barrier

; #define PG8_STAGE(bufoff, gbase, voff) do { _Pragma("unroll") for (int _i = 0; _i < 2; ++_i) \
;         __builtin_amdgcn_global_load_lds((const unsigned*)((const char*)(gbase) + (voff)[_i]), (PG8_LAS unsigned*)(lds + (bufoff) + ldsw + _i * 8192), 16, 0, 0); } while (0)
; #define PG8_LDA(dst, b, h) do { _Pragma("unroll") for (int m = 0; m < 4; ++m) _Pragma("unroll") for (int k = 0; k < 2; ++k) dst[m][k] = *(const PG8_LAS bf16x8*)(lds + PG8_SA(b, h) + aoff + m * 2048 + k * 1024); } while (0)
; #define PG8_LDB(dst, b, h) do { _Pragma("unroll") for (int n = 0; n < 2; ++n) _Pragma("unroll") for (int k = 0; k < 2; ++k) dst[n][k] = *(const PG8_LAS bf16x8*)(lds + PG8_SB(b, h) + boff + n * 2048 + k * 1024); } while (0)
; #define PG8_MMA(ai, bj, At, Bt) do { __builtin_amdgcn_s_setprio(1); _Pragma("unroll") for (int m = 0; m < 4; ++m) _Pragma("unroll") for (int n = 0; n < 2; ++n) _Pragma("unroll") for (int k = 0; k < 2; ++k) \
;         acc[ai][bj][m][n] = __builtin_amdgcn_mfma_f32_16x16x32_bf16(Bt[n][k], At[m][k], acc[ai][bj][m][n], 0, 0, 0); __builtin_amdgcn_s_setprio(0); } while (0)
; #define PG8_WAIT_V(n) asm volatile("s_waitcnt vmcnt(" #n ")" ::: "memory")
; #define PG8_WAIT_L(n) asm volatile("s_waitcnt lgkmcnt(" #n ")" ::: "memory")
; #define PG8_BAR __builtin_amdgcn_s_barrier()
; #define PG8_SCHED __builtin_amdgcn_sched_barrier(0)
; template <class Epi, class Sched, bool ALIGN_EPI = false, bool SP2 = false>
; __device__ __forceinline__ void gemm_phase(PG8_LAS unsigned char* lds, const Gemm g, const Sched& S, const Epi& E) {
;     ...
;             PG8_LDB(B0, 0, 0); PG8_LDB(B1, 0, 1); PG8_SCHED; PG8_LDA(At, 0, 0); PG8_STAGE(PG8_SA(1, 1), a1 + hstep, voffA);
;             PG8_WAIT_V(8); PG8_WAIT_L(0); PG8_BAR; PG8_MMA(0, 0, At, B0); PG8_MMA(0, 1, At, B1); PG8_BAR; PG8_SCHED;
;             PG8_LDA(At, 0, 1); PG8_STAGE(PG8_SB(0, 0), b2, voffB); PG8_STAGE(PG8_SB(0, 1), b2 + hstep, voffB); PG8_STAGE(PG8_SA(0, 0), a2, voffA);
.LBB0_448:
	ds_read_b128 v[154:157], v150
	ds_read_b128 v[158:161], v150 offset:1024
	ds_read_b128 v[162:165], v150 offset:2048
	ds_read_b128 v[166:169], v150 offset:3072
	ds_read_b128 v[170:173], v151
	ds_read_b128 v[174:177], v151 offset:1024
	ds_read_b128 v[178:181], v151 offset:2048
	ds_read_b128 v[182:185], v151 offset:3072
	s_add_u32 s16, s14, 0x100
	s_addc_u32 s17, s15, 0
	s_cmpk_eq_i32 s43, 0x54
	s_cselect_b32 s21, s5, s17
	s_cselect_b32 s20, s4, s16
	s_cselect_b32 s19, s13, s42
	s_cselect_b32 s18, s12, s39
	v_lshl_add_u64 v[218:219], s[14:15], 0, v[138:139]
	s_add_i32 m0, s22, 0xc000
	ds_read_b128 v[186:189], v152
	ds_read_b128 v[190:193], v152 offset:1024
	ds_read_b128 v[194:197], v152 offset:2048
	ds_read_b128 v[198:201], v152 offset:3072
	ds_read_b128 v[202:205], v152 offset:4096
	ds_read_b128 v[206:209], v152 offset:5120
	ds_read_b128 v[210:213], v152 offset:6144
	ds_read_b128 v[214:217], v152 offset:7168
	global_load_lds_dwordx4 v[218:219], off
	v_lshl_add_u64 v[218:219], s[14:15], 0, v[140:141]
	s_add_i32 m0, s22, 0xe000
	s_nop 0
	global_load_lds_dwordx4 v[218:219], off
	s_waitcnt vmcnt(8)
	s_waitcnt lgkmcnt(0)
	s_barrier
	s_setprio 1
	s_waitcnt lgkmcnt(0)
	v_mfma_f32_16x16x32_bf16 v[126:129], v[154:157], v[186:189], v[126:129]
	v_mfma_f32_16x16x32_bf16 v[122:125], v[162:165], v[186:189], v[122:125]
	v_mfma_f32_16x16x32_bf16 v[114:117], v[154:157], v[194:197], v[114:117]
	v_mfma_f32_16x16x32_bf16 v[106:109], v[162:165], v[194:197], v[106:109]
	v_mfma_f32_16x16x32_bf16 v[102:105], v[154:157], v[202:205], v[102:105]
	v_mfma_f32_16x16x32_bf16 v[94:97], v[162:165], v[202:205], v[94:97]
	v_mfma_f32_16x16x32_bf16 v[86:89], v[154:157], v[210:213], v[86:89]
	v_mfma_f32_16x16x32_bf16 v[78:81], v[162:165], v[210:213], v[78:81]
	v_mfma_f32_16x16x32_bf16 v[126:129], v[158:161], v[190:193], v[126:129]
	v_mfma_f32_16x16x32_bf16 v[122:125], v[166:169], v[190:193], v[122:125]
	v_mfma_f32_16x16x32_bf16 v[114:117], v[158:161], v[198:201], v[114:117]
	v_mfma_f32_16x16x32_bf16 v[106:109], v[166:169], v[198:201], v[106:109]
	v_mfma_f32_16x16x32_bf16 v[102:105], v[158:161], v[206:209], v[102:105]
	v_mfma_f32_16x16x32_bf16 v[94:97], v[166:169], v[206:209], v[94:97]
	v_mfma_f32_16x16x32_bf16 v[86:89], v[158:161], v[214:217], v[86:89]
	v_mfma_f32_16x16x32_bf16 v[78:81], v[166:169], v[214:217], v[78:81]
	s_setprio 0
	s_setprio 1
	v_mfma_f32_16x16x32_bf16 v[118:121], v[170:173], v[186:189], v[118:121]
	v_mfma_f32_16x16x32_bf16 v[110:113], v[178:181], v[186:189], v[110:113]
	v_mfma_f32_16x16x32_bf16 v[98:101], v[170:173], v[194:197], v[98:101]
	v_mfma_f32_16x16x32_bf16 v[90:93], v[178:181], v[194:197], v[90:93]
	v_mfma_f32_16x16x32_bf16 v[82:85], v[170:173], v[202:205], v[82:85]
	v_mfma_f32_16x16x32_bf16 v[74:77], v[178:181], v[202:205], v[74:77]
	v_mfma_f32_16x16x32_bf16 v[70:73], v[170:173], v[210:213], v[70:73]
	v_mfma_f32_16x16x32_bf16 v[66:69], v[178:181], v[210:213], v[66:69]
	v_mfma_f32_16x16x32_bf16 v[118:121], v[174:177], v[190:193], v[118:121]
	v_mfma_f32_16x16x32_bf16 v[110:113], v[182:185], v[190:193], v[110:113]
	v_mfma_f32_16x16x32_bf16 v[98:101], v[174:177], v[198:201], v[98:101]
	v_mfma_f32_16x16x32_bf16 v[90:93], v[182:185], v[198:201], v[90:93]
	v_mfma_f32_16x16x32_bf16 v[82:85], v[174:177], v[206:209], v[82:85]
	v_mfma_f32_16x16x32_bf16 v[74:77], v[182:185], v[206:209], v[74:77]
	v_mfma_f32_16x16x32_bf16 v[70:73], v[174:177], v[214:217], v[70:73]
	v_mfma_f32_16x16x32_bf16 v[66:69], v[182:185], v[214:217], v[66:69]
	s_setprio 0
	s_barrier
	s_add_i32 s14, s30, s3
	v_lshl_add_u64 v[218:219], s[18:19], 0, v[132:133]
	s_mov_b32 m0, s14
	ds_read_b128 v[186:189], v152 offset:16384
	ds_read_b128 v[190:193], v152 offset:17408
	ds_read_b128 v[194:197], v152 offset:18432
	ds_read_b128 v[198:201], v152 offset:19456
	ds_read_b128 v[202:205], v152 offset:20480
	ds_read_b128 v[206:209], v152 offset:21504
	ds_read_b128 v[210:213], v152 offset:22528
	ds_read_b128 v[214:217], v152 offset:23552
	global_load_lds_dwordx4 v[218:219], off
	s_add_i32 m0, s14, 0x2000
	s_add_u32 s14, s18, 0x160000
	v_lshl_add_u64 v[220:221], s[18:19], 0, v[136:137]
	s_addc_u32 s15, s19, 0
	s_add_i32 s44, s31, s3
	global_load_lds_dwordx4 v[220:221], off
	v_lshl_add_u64 v[222:223], s[14:15], 0, v[132:133]
	s_mov_b32 m0, s44
	v_lshl_add_u64 v[224:225], s[20:21], 0, v[134:135]
	global_load_lds_dwordx4 v[222:223], off
	v_lshl_add_u64 v[222:223], s[14:15], 0, v[136:137]
	s_add_i32 m0, s44, 0x2000
	s_nop 0
	global_load_lds_dwordx4 v[222:223], off
	v_lshl_add_u64 v[222:223], s[20:21], 0, v[130:131]
	s_mov_b32 m0, s22
	s_nop 0
	global_load_lds_dwordx4 v[222:223], off
	s_mov_b32 m0, s23
	s_nop 0
	global_load_lds_dwordx4 v[224:225], off
	s_waitcnt vmcnt(8)
	s_waitcnt lgkmcnt(0)
	s_barrier
; #define PG8_STAGE(bufoff, gbase, voff) do { _Pragma("unroll") for (int _i = 0; _i < 2; ++_i) \
;         __builtin_amdgcn_global_load_lds((const unsigned*)((const char*)(gbase) + (voff)[_i]), (PG8_LAS unsigned*)(lds + (bufoff) + ldsw + _i * 8192), 16, 0, 0); } while (0)
; #define PG8_LDA(dst, b, h) do { _Pragma("unroll") for (int m = 0; m < 4; ++m) _Pragma("unroll") for (int k = 0; k < 2; ++k) dst[m][k] = *(const PG8_LAS bf16x8*)(lds + PG8_SA(b, h) + aoff + m * 2048 + k * 1024); } while (0)
; #define PG8_LDB(dst, b, h) do { _Pragma("unroll") for (int n = 0; n < 2; ++n) _Pragma("unroll") for (int k = 0; k < 2; ++k) dst[n][k] = *(const PG8_LAS bf16x8*)(lds + PG8_SB(b, h) + boff + n * 2048 + k * 1024); } while (0)
; #define PG8_MMA(ai, bj, At, Bt) do { __builtin_amdgcn_s_setprio(1); _Pragma("unroll") for (int m = 0; m < 4; ++m) _Pragma("unroll") for (int n = 0; n < 2; ++n) _Pragma("unroll") for (int k = 0; k < 2; ++k) \
;         acc[ai][bj][m][n] = __builtin_amdgcn_mfma_f32_16x16x32_bf16(Bt[n][k], At[m][k], acc[ai][bj][m][n], 0, 0, 0); __builtin_amdgcn_s_setprio(0); } while (0)
; #define PG8_WAIT_V(n) asm volatile("s_waitcnt vmcnt(" #n ")" ::: "memory")
; #define PG8_WAIT_L(n) asm volatile("s_waitcnt lgkmcnt(" #n ")" ::: "memory")
; #define PG8_BAR __builtin_amdgcn_s_barrier()
; #define PG8_SCHED __builtin_amdgcn_sched_barrier(0)
; template <class Epi, class Sched, bool ALIGN_EPI = false, bool SP2 = false>
; __device__ __forceinline__ void gemm_phase(PG8_LAS unsigned char* lds, const Gemm g, const Sched& S, const Epi& E) {
;     ...
;             PG8_WAIT_V(8); PG8_WAIT_L(0); PG8_BAR; PG8_MMA(1, 0, At, B0); PG8_MMA(1, 1, At, B1); PG8_BAR; PG8_SCHED;
;             PG8_LDB(B0, 1, 0); PG8_LDB(B1, 1, 1); PG8_SCHED; PG8_LDA(At, 1, 0); PG8_STAGE(PG8_SA(0, 1), a2 + hstep, voffA);
;             PG8_WAIT_V(8); PG8_WAIT_L(0); PG8_BAR; PG8_MMA(0, 0, At, B0); PG8_MMA(0, 1, At, B1); PG8_BAR; PG8_SCHED;
	s_setprio 1
	s_waitcnt lgkmcnt(0)
	v_mfma_f32_16x16x32_bf16 v[62:65], v[154:157], v[186:189], v[62:65]
	v_mfma_f32_16x16x32_bf16 v[58:61], v[162:165], v[186:189], v[58:61]
	v_mfma_f32_16x16x32_bf16 v[54:57], v[154:157], v[194:197], v[54:57]
	v_mfma_f32_16x16x32_bf16 v[46:49], v[162:165], v[194:197], v[46:49]
	v_mfma_f32_16x16x32_bf16 v[38:41], v[154:157], v[202:205], v[38:41]
	v_mfma_f32_16x16x32_bf16 v[30:33], v[162:165], v[202:205], v[30:33]
	v_mfma_f32_16x16x32_bf16 v[22:25], v[154:157], v[210:213], v[22:25]
	v_mfma_f32_16x16x32_bf16 v[14:17], v[162:165], v[210:213], v[14:17]
	v_mfma_f32_16x16x32_bf16 v[62:65], v[158:161], v[190:193], v[62:65]
	v_mfma_f32_16x16x32_bf16 v[58:61], v[166:169], v[190:193], v[58:61]
	v_mfma_f32_16x16x32_bf16 v[54:57], v[158:161], v[198:201], v[54:57]
	v_mfma_f32_16x16x32_bf16 v[46:49], v[166:169], v[198:201], v[46:49]
	v_mfma_f32_16x16x32_bf16 v[38:41], v[158:161], v[206:209], v[38:41]
	v_mfma_f32_16x16x32_bf16 v[30:33], v[166:169], v[206:209], v[30:33]
	v_mfma_f32_16x16x32_bf16 v[22:25], v[158:161], v[214:217], v[22:25]
	v_mfma_f32_16x16x32_bf16 v[14:17], v[166:169], v[214:217], v[14:17]
	s_setprio 0
	s_setprio 1
	v_mfma_f32_16x16x32_bf16 v[50:53], v[170:173], v[186:189], v[50:53]
	v_mfma_f32_16x16x32_bf16 v[42:45], v[178:181], v[186:189], v[42:45]
	v_mfma_f32_16x16x32_bf16 v[34:37], v[170:173], v[194:197], v[34:37]
	v_mfma_f32_16x16x32_bf16 v[26:29], v[178:181], v[194:197], v[26:29]
	v_mfma_f32_16x16x32_bf16 v[18:21], v[170:173], v[202:205], v[18:21]
	v_mfma_f32_16x16x32_bf16 v[10:13], v[178:181], v[202:205], v[10:13]
	v_mfma_f32_16x16x32_bf16 v[6:9], v[170:173], v[210:213], v[6:9]
	v_mfma_f32_16x16x32_bf16 v[2:5], v[178:181], v[210:213], v[2:5]
	v_mfma_f32_16x16x32_bf16 v[50:53], v[174:177], v[190:193], v[50:53]
	v_mfma_f32_16x16x32_bf16 v[42:45], v[182:185], v[190:193], v[42:45]
	v_mfma_f32_16x16x32_bf16 v[34:37], v[174:177], v[198:201], v[34:37]
	v_mfma_f32_16x16x32_bf16 v[26:29], v[182:185], v[198:201], v[26:29]
	v_mfma_f32_16x16x32_bf16 v[18:21], v[174:177], v[206:209], v[18:21]
	v_mfma_f32_16x16x32_bf16 v[10:13], v[182:185], v[206:209], v[10:13]
	v_mfma_f32_16x16x32_bf16 v[6:9], v[174:177], v[214:217], v[6:9]
	v_mfma_f32_16x16x32_bf16 v[2:5], v[182:185], v[214:217], v[2:5]
	s_setprio 0
	s_barrier
	s_add_i32 s44, 0, 0x18000
	v_add_u32_e32 v153, s44, v146
	s_add_i32 s45, 0, 0x1c000
	ds_read_b128 v[154:157], v153
	ds_read_b128 v[158:161], v153 offset:1024
	ds_read_b128 v[162:165], v153 offset:2048
	ds_read_b128 v[166:169], v153 offset:3072
	v_add_u32_e32 v153, s45, v146
	ds_read_b128 v[170:173], v153
	ds_read_b128 v[174:177], v153 offset:1024
	ds_read_b128 v[178:181], v153 offset:2048
	ds_read_b128 v[182:185], v153 offset:3072
	s_add_u32 s14, s20, 0x160000
	s_addc_u32 s15, s21, 0
	s_mov_b32 m0, s24
	v_lshl_add_u64 v[226:227], s[14:15], 0, v[130:131]
	ds_read_b128 v[186:189], v152 offset:32768
	ds_read_b128 v[190:193], v152 offset:33792
	ds_read_b128 v[194:197], v152 offset:34816
	ds_read_b128 v[198:201], v152 offset:35840
	ds_read_b128 v[202:205], v152 offset:36864
	ds_read_b128 v[206:209], v152 offset:37888
	ds_read_b128 v[210:213], v152 offset:38912
	ds_read_b128 v[214:217], v152 offset:39936
	global_load_lds_dwordx4 v[226:227], off
	v_lshl_add_u64 v[226:227], s[14:15], 0, v[134:135]
	s_mov_b32 m0, s25
	s_nop 0
	global_load_lds_dwordx4 v[226:227], off
	s_waitcnt vmcnt(8)
	s_waitcnt lgkmcnt(0)
	s_barrier
	s_setprio 1
	s_waitcnt lgkmcnt(0)
	v_mfma_f32_16x16x32_bf16 v[126:129], v[154:157], v[186:189], v[126:129]
	v_mfma_f32_16x16x32_bf16 v[122:125], v[162:165], v[186:189], v[122:125]
	v_mfma_f32_16x16x32_bf16 v[114:117], v[154:157], v[194:197], v[114:117]
	v_mfma_f32_16x16x32_bf16 v[106:109], v[162:165], v[194:197], v[106:109]
	v_mfma_f32_16x16x32_bf16 v[102:105], v[154:157], v[202:205], v[102:105]
	v_mfma_f32_16x16x32_bf16 v[94:97], v[162:165], v[202:205], v[94:97]
	v_mfma_f32_16x16x32_bf16 v[86:89], v[154:157], v[210:213], v[86:89]
	v_mfma_f32_16x16x32_bf16 v[78:81], v[162:165], v[210:213], v[78:81]
	v_mfma_f32_16x16x32_bf16 v[126:129], v[158:161], v[190:193], v[126:129]
	v_mfma_f32_16x16x32_bf16 v[122:125], v[166:169], v[190:193], v[122:125]
	v_mfma_f32_16x16x32_bf16 v[114:117], v[158:161], v[198:201], v[114:117]
	v_mfma_f32_16x16x32_bf16 v[106:109], v[166:169], v[198:201], v[106:109]
	v_mfma_f32_16x16x32_bf16 v[102:105], v[158:161], v[206:209], v[102:105]
	v_mfma_f32_16x16x32_bf16 v[94:97], v[166:169], v[206:209], v[94:97]
	v_mfma_f32_16x16x32_bf16 v[86:89], v[158:161], v[214:217], v[86:89]
	v_mfma_f32_16x16x32_bf16 v[78:81], v[166:169], v[214:217], v[78:81]
	s_setprio 0
	s_setprio 1
	v_mfma_f32_16x16x32_bf16 v[118:121], v[170:173], v[186:189], v[118:121]
	v_mfma_f32_16x16x32_bf16 v[110:113], v[178:181], v[186:189], v[110:113]
	v_mfma_f32_16x16x32_bf16 v[98:101], v[170:173], v[194:197], v[98:101]
	v_mfma_f32_16x16x32_bf16 v[90:93], v[178:181], v[194:197], v[90:93]
	v_mfma_f32_16x16x32_bf16 v[82:85], v[170:173], v[202:205], v[82:85]
	v_mfma_f32_16x16x32_bf16 v[74:77], v[178:181], v[202:205], v[74:77]
	v_mfma_f32_16x16x32_bf16 v[70:73], v[170:173], v[210:213], v[70:73]
	v_mfma_f32_16x16x32_bf16 v[66:69], v[178:181], v[210:213], v[66:69]
	v_mfma_f32_16x16x32_bf16 v[118:121], v[174:177], v[190:193], v[118:121]
	v_mfma_f32_16x16x32_bf16 v[110:113], v[182:185], v[190:193], v[110:113]
	v_mfma_f32_16x16x32_bf16 v[98:101], v[174:177], v[198:201], v[98:101]
	v_mfma_f32_16x16x32_bf16 v[90:93], v[182:185], v[198:201], v[90:93]
	v_mfma_f32_16x16x32_bf16 v[82:85], v[174:177], v[206:209], v[82:85]
	v_mfma_f32_16x16x32_bf16 v[74:77], v[182:185], v[206:209], v[74:77]
	v_mfma_f32_16x16x32_bf16 v[70:73], v[174:177], v[214:217], v[70:73]
	v_mfma_f32_16x16x32_bf16 v[66:69], v[182:185], v[214:217], v[66:69]
	s_setprio 0
	s_barrier
; #define PG8_STAGE(bufoff, gbase, voff) do { _Pragma("unroll") for (int _i = 0; _i < 2; ++_i) \
;         __builtin_amdgcn_global_load_lds((const unsigned*)((const char*)(gbase) + (voff)[_i]), (PG8_LAS unsigned*)(lds + (bufoff) + ldsw + _i * 8192), 16, 0, 0); } while (0)
; #define PG8_LDA(dst, b, h) do { _Pragma("unroll") for (int m = 0; m < 4; ++m) _Pragma("unroll") for (int k = 0; k < 2; ++k) dst[m][k] = *(const PG8_LAS bf16x8*)(lds + PG8_SA(b, h) + aoff + m * 2048 + k * 1024); } while (0)
; #define PG8_MMA(ai, bj, At, Bt) do { __builtin_amdgcn_s_setprio(1); _Pragma("unroll") for (int m = 0; m < 4; ++m) _Pragma("unroll") for (int n = 0; n < 2; ++n) _Pragma("unroll") for (int k = 0; k < 2; ++k) \
;         acc[ai][bj][m][n] = __builtin_amdgcn_mfma_f32_16x16x32_bf16(Bt[n][k], At[m][k], acc[ai][bj][m][n], 0, 0, 0); __builtin_amdgcn_s_setprio(0); } while (0)
; #define PG8_WAIT_V(n) asm volatile("s_waitcnt vmcnt(" #n ")" ::: "memory")
; #define PG8_WAIT_L(n) asm volatile("s_waitcnt lgkmcnt(" #n ")" ::: "memory")
; #define PG8_BAR __builtin_amdgcn_s_barrier()
; #define PG8_SCHED __builtin_amdgcn_sched_barrier(0)
; template <class Epi, class Sched, bool ALIGN_EPI = false, bool SP2 = false>
; __device__ __forceinline__ void gemm_phase(PG8_LAS unsigned char* lds, const Gemm g, const Sched& S, const Epi& E) {
;     ...
;         for (int t = 0; t < nt; t += 2) {
;             const bool last = (t == nt - 2);
;             const char* a1 = cA + (size_t)(t + 1) * kstep;
;             const char* a2 = last ? nA : cA + (size_t)(t + 2) * kstep; const char* b2 = last ? nB : cB + (size_t)(t + 2) * kstep;
;             const char* a3 = a2 + kstep; const char* b3 = b2 + kstep;
;     ...
;             PG8_LDA(At, 1, 1); PG8_STAGE(PG8_SB(1, 0), b3, voffB); PG8_STAGE(PG8_SB(1, 1), b3 + hstep, voffB); PG8_STAGE(PG8_SA(1, 0), a3, voffA);
;             PG8_WAIT_V(8); PG8_WAIT_L(0); PG8_BAR; PG8_MMA(1, 0, At, B0); PG8_MMA(1, 1, At, B1); PG8_BAR; PG8_SCHED;
	s_add_i32 s14, s44, s3
	v_lshl_add_u64 v[218:219], v[218:219], 0, s[8:9]
	s_mov_b32 m0, s14
	ds_read_b128 v[186:189], v152 offset:49152
	ds_read_b128 v[190:193], v152 offset:50176
	ds_read_b128 v[194:197], v152 offset:51200
	ds_read_b128 v[198:201], v152 offset:52224
	ds_read_b128 v[202:205], v152 offset:53248
	ds_read_b128 v[206:209], v152 offset:54272
	ds_read_b128 v[210:213], v152 offset:55296
	ds_read_b128 v[214:217], v152 offset:56320
	global_load_lds_dwordx4 v[218:219], off
	s_add_i32 m0, s14, 0x2000
	s_add_u32 s14, s18, 0x160080
	v_lshl_add_u64 v[218:219], v[220:221], 0, s[8:9]
	s_addc_u32 s15, s19, 0
	s_add_i32 s18, s45, s3
	global_load_lds_dwordx4 v[218:219], off
	v_lshl_add_u64 v[218:219], s[14:15], 0, v[132:133]
	s_mov_b32 m0, s18
	s_nop 0
	global_load_lds_dwordx4 v[218:219], off
	v_lshl_add_u64 v[218:219], s[14:15], 0, v[136:137]
	s_add_i32 m0, s18, 0x2000
	s_nop 0
	global_load_lds_dwordx4 v[218:219], off
	v_lshl_add_u64 v[218:219], v[222:223], 0, s[8:9]
	s_mov_b32 m0, s27
	s_nop 0
	global_load_lds_dwordx4 v[218:219], off
	v_lshl_add_u64 v[218:219], v[224:225], 0, s[8:9]
	s_mov_b32 m0, s28
	s_nop 0
	global_load_lds_dwordx4 v[218:219], off
	s_waitcnt vmcnt(8)
	s_waitcnt lgkmcnt(0)
	s_barrier
	s_setprio 1
	s_waitcnt lgkmcnt(0)
	v_mfma_f32_16x16x32_bf16 v[62:65], v[154:157], v[186:189], v[62:65]
	v_mfma_f32_16x16x32_bf16 v[58:61], v[162:165], v[186:189], v[58:61]
	v_mfma_f32_16x16x32_bf16 v[54:57], v[154:157], v[194:197], v[54:57]
	v_mfma_f32_16x16x32_bf16 v[46:49], v[162:165], v[194:197], v[46:49]
	v_mfma_f32_16x16x32_bf16 v[38:41], v[154:157], v[202:205], v[38:41]
	v_mfma_f32_16x16x32_bf16 v[30:33], v[162:165], v[202:205], v[30:33]
	v_mfma_f32_16x16x32_bf16 v[22:25], v[154:157], v[210:213], v[22:25]
	v_mfma_f32_16x16x32_bf16 v[14:17], v[162:165], v[210:213], v[14:17]
	v_mfma_f32_16x16x32_bf16 v[62:65], v[158:161], v[190:193], v[62:65]
	v_mfma_f32_16x16x32_bf16 v[58:61], v[166:169], v[190:193], v[58:61]
	v_mfma_f32_16x16x32_bf16 v[54:57], v[158:161], v[198:201], v[54:57]
	v_mfma_f32_16x16x32_bf16 v[46:49], v[166:169], v[198:201], v[46:49]
	v_mfma_f32_16x16x32_bf16 v[38:41], v[158:161], v[206:209], v[38:41]
	v_mfma_f32_16x16x32_bf16 v[30:33], v[166:169], v[206:209], v[30:33]
	v_mfma_f32_16x16x32_bf16 v[22:25], v[158:161], v[214:217], v[22:25]
	v_mfma_f32_16x16x32_bf16 v[14:17], v[166:169], v[214:217], v[14:17]
	s_setprio 0
	s_setprio 1
	v_mfma_f32_16x16x32_bf16 v[50:53], v[170:173], v[186:189], v[50:53]
	v_mfma_f32_16x16x32_bf16 v[42:45], v[178:181], v[186:189], v[42:45]
	v_mfma_f32_16x16x32_bf16 v[34:37], v[170:173], v[194:197], v[34:37]
	v_mfma_f32_16x16x32_bf16 v[26:29], v[178:181], v[194:197], v[26:29]
	v_mfma_f32_16x16x32_bf16 v[18:21], v[170:173], v[202:205], v[18:21]
	v_mfma_f32_16x16x32_bf16 v[10:13], v[178:181], v[202:205], v[10:13]
	v_mfma_f32_16x16x32_bf16 v[6:9], v[170:173], v[210:213], v[6:9]
	v_mfma_f32_16x16x32_bf16 v[2:5], v[178:181], v[210:213], v[2:5]
	v_mfma_f32_16x16x32_bf16 v[50:53], v[174:177], v[190:193], v[50:53]
	v_mfma_f32_16x16x32_bf16 v[42:45], v[182:185], v[190:193], v[42:45]
	v_mfma_f32_16x16x32_bf16 v[34:37], v[174:177], v[198:201], v[34:37]
	v_mfma_f32_16x16x32_bf16 v[26:29], v[182:185], v[198:201], v[26:29]
	v_mfma_f32_16x16x32_bf16 v[18:21], v[174:177], v[206:209], v[18:21]
	v_mfma_f32_16x16x32_bf16 v[10:13], v[182:185], v[206:209], v[10:13]
	v_mfma_f32_16x16x32_bf16 v[6:9], v[174:177], v[214:217], v[6:9]
	v_mfma_f32_16x16x32_bf16 v[2:5], v[182:185], v[214:217], v[2:5]
	s_setprio 0
	s_add_i32 s43, s43, 2
	s_add_u32 s39, s39, 0x100
	s_addc_u32 s42, s42, 0
	s_cmpk_gt_u32 s43, 0x55
	s_mov_b64 s[14:15], s[16:17]
	s_barrier
	s_cbranch_scc0 .LBB0_448
	s_and_b64 vcc, exec, s[10:11]
	s_cbranch_vccz .LBB0_451
	s_barrier

; #define PG8_STAGE(bufoff, gbase, voff) do { _Pragma("unroll") for (int _i = 0; _i < 2; ++_i) \
;         __builtin_amdgcn_global_load_lds((const unsigned*)((const char*)(gbase) + (voff)[_i]), (PG8_LAS unsigned*)(lds + (bufoff) + ldsw + _i * 8192), 16, 0, 0); } while (0)
; #define PG8_LDA(dst, b, h) do { _Pragma("unroll") for (int m = 0; m < 4; ++m) _Pragma("unroll") for (int k = 0; k < 2; ++k) dst[m][k] = *(const PG8_LAS bf16x8*)(lds + PG8_SA(b, h) + aoff + m * 2048 + k * 1024); } while (0)
; #define PG8_LDB(dst, b, h) do { _Pragma("unroll") for (int n = 0; n < 2; ++n) _Pragma("unroll") for (int k = 0; k < 2; ++k) dst[n][k] = *(const PG8_LAS bf16x8*)(lds + PG8_SB(b, h) + boff + n * 2048 + k * 1024); } while (0)
; #define PG8_MMA(ai, bj, At, Bt) do { __builtin_amdgcn_s_setprio(1); _Pragma("unroll") for (int m = 0; m < 4; ++m) _Pragma("unroll") for (int n = 0; n < 2; ++n) _Pragma("unroll") for (int k = 0; k < 2; ++k) \
;         acc[ai][bj][m][n] = __builtin_amdgcn_mfma_f32_16x16x32_bf16(Bt[n][k], At[m][k], acc[ai][bj][m][n], 0, 0, 0); __builtin_amdgcn_s_setprio(0); } while (0)
; #define PG8_WAIT_V(n) asm volatile("s_waitcnt vmcnt(" #n ")" ::: "memory")
; #define PG8_WAIT_L(n) asm volatile("s_waitcnt lgkmcnt(" #n ")" ::: "memory")
; #define PG8_BAR __builtin_amdgcn_s_barrier()
; #define PG8_SCHED __builtin_amdgcn_sched_barrier(0)
; template <class Epi, class Sched, bool ALIGN_EPI = false, bool SP2 = false>
; __device__ __forceinline__ void gemm_phase(PG8_LAS unsigned char* lds, const Gemm g, const Sched& S, const Epi& E) {
;     ...
;             if constexpr (SP2) {
;             PG8_LDB(B0, 0, 0); PG8_LDB(B1, 0, 1); PG8_SCHED; PG8_LDA(At, 0, 0); PG8_STAGE(PG8_SA(1, 1), a1 + hstep, voffA);
;             PG8_WAIT_V(8); PG8_WAIT_L(0); PG8_BAR; PG8_MMA(0, 0, At, B0); PG8_MMA(0, 1, At, B1); PG8_BAR; PG8_SCHED;
;             PG8_LDA(At, 0, 1); PG8_STAGE(PG8_SB(0, 0), b2, voffB); PG8_STAGE(PG8_SB(0, 1), b2 + hstep, voffB); PG8_STAGE(PG8_SA(0, 0), a2, voffA);
;             PG8_WAIT_V(8); PG8_WAIT_L(0); PG8_BAR; PG8_MMA(1, 0, At, B0); PG8_MMA(1, 1, At, B1); PG8_BAR; PG8_SCHED;
.LBB0_582:
	ds_read_b128 v[158:161], v177
	ds_read_b128 v[162:165], v177 offset:1024
	ds_read_b128 v[166:169], v177 offset:2048
	ds_read_b128 v[170:173], v177 offset:3072
	ds_read_b128 v[182:185], v178
	ds_read_b128 v[186:189], v178 offset:1024
	ds_read_b128 v[190:193], v178 offset:2048
	ds_read_b128 v[194:197], v178 offset:3072
	s_add_u32 s16, s0, 0xfff80080
	s_addc_u32 s17, s1, -1
	s_cmp_eq_u32 s23, 28
	s_cselect_b32 s19, s7, s17
	s_cselect_b32 s18, s11, s16
	s_cselect_b32 s17, s15, s22
	s_cselect_b32 s16, s20, s21
	v_lshl_add_u64 v[230:231], s[0:1], 0, v[150:151]
	s_add_i32 m0, s33, 0xc000
	ds_read_b128 v[198:201], v179
	ds_read_b128 v[202:205], v179 offset:1024
	ds_read_b128 v[206:209], v179 offset:2048
	ds_read_b128 v[210:213], v179 offset:3072
	ds_read_b128 v[214:217], v179 offset:4096
	ds_read_b128 v[218:221], v179 offset:5120
	ds_read_b128 v[222:225], v179 offset:6144
	ds_read_b128 v[226:229], v179 offset:7168
	global_load_lds_dwordx4 v[230:231], off
	v_lshl_add_u64 v[230:231], s[0:1], 0, v[152:153]
	s_add_i32 m0, s33, 0xe000
	s_nop 0
	global_load_lds_dwordx4 v[230:231], off
	s_waitcnt vmcnt(8)
	s_waitcnt lgkmcnt(0)
	s_barrier
	s_setprio 1
	s_waitcnt lgkmcnt(0)
	v_mfma_f32_16x16x32_bf16 v[126:129], v[158:161], v[198:201], v[126:129]
	v_mfma_f32_16x16x32_bf16 v[122:125], v[166:169], v[198:201], v[122:125]
	v_mfma_f32_16x16x32_bf16 v[110:113], v[158:161], v[206:209], v[110:113]
	v_mfma_f32_16x16x32_bf16 v[106:109], v[166:169], v[206:209], v[106:109]
	v_mfma_f32_16x16x32_bf16 v[94:97], v[158:161], v[214:217], v[94:97]
	v_mfma_f32_16x16x32_bf16 v[90:93], v[166:169], v[214:217], v[90:93]
	v_mfma_f32_16x16x32_bf16 v[78:81], v[158:161], v[222:225], v[78:81]
	v_mfma_f32_16x16x32_bf16 v[74:77], v[166:169], v[222:225], v[74:77]
	v_mfma_f32_16x16x32_bf16 v[126:129], v[162:165], v[202:205], v[126:129]
	v_mfma_f32_16x16x32_bf16 v[122:125], v[170:173], v[202:205], v[122:125]
	v_mfma_f32_16x16x32_bf16 v[110:113], v[162:165], v[210:213], v[110:113]
	v_mfma_f32_16x16x32_bf16 v[106:109], v[170:173], v[210:213], v[106:109]
	v_mfma_f32_16x16x32_bf16 v[94:97], v[162:165], v[218:221], v[94:97]
	v_mfma_f32_16x16x32_bf16 v[90:93], v[170:173], v[218:221], v[90:93]
	v_mfma_f32_16x16x32_bf16 v[78:81], v[162:165], v[226:229], v[78:81]
	v_mfma_f32_16x16x32_bf16 v[74:77], v[170:173], v[226:229], v[74:77]
	s_setprio 0
	s_setprio 1
	v_mfma_f32_16x16x32_bf16 v[118:121], v[182:185], v[198:201], v[118:121]
	v_mfma_f32_16x16x32_bf16 v[114:117], v[190:193], v[198:201], v[114:117]
	v_mfma_f32_16x16x32_bf16 v[102:105], v[182:185], v[206:209], v[102:105]
	v_mfma_f32_16x16x32_bf16 v[98:101], v[190:193], v[206:209], v[98:101]
	v_mfma_f32_16x16x32_bf16 v[86:89], v[182:185], v[214:217], v[86:89]
	v_mfma_f32_16x16x32_bf16 v[82:85], v[190:193], v[214:217], v[82:85]
	v_mfma_f32_16x16x32_bf16 v[70:73], v[182:185], v[222:225], v[70:73]
	v_mfma_f32_16x16x32_bf16 v[66:69], v[190:193], v[222:225], v[66:69]
	v_mfma_f32_16x16x32_bf16 v[118:121], v[186:189], v[202:205], v[118:121]
	v_mfma_f32_16x16x32_bf16 v[114:117], v[194:197], v[202:205], v[114:117]
	v_mfma_f32_16x16x32_bf16 v[102:105], v[186:189], v[210:213], v[102:105]
	v_mfma_f32_16x16x32_bf16 v[98:101], v[194:197], v[210:213], v[98:101]
	v_mfma_f32_16x16x32_bf16 v[86:89], v[186:189], v[218:221], v[86:89]
	v_mfma_f32_16x16x32_bf16 v[82:85], v[194:197], v[218:221], v[82:85]
	v_mfma_f32_16x16x32_bf16 v[70:73], v[186:189], v[226:229], v[70:73]
	v_mfma_f32_16x16x32_bf16 v[66:69], v[194:197], v[226:229], v[66:69]
	s_setprio 0
	s_barrier
	s_add_i32 s24, s83, s2
	v_lshl_add_u64 v[230:231], s[16:17], 0, v[132:133]
	s_mov_b32 m0, s24
	ds_read_b128 v[198:201], v179 offset:16384
	ds_read_b128 v[202:205], v179 offset:17408
	ds_read_b128 v[206:209], v179 offset:18432
	ds_read_b128 v[210:213], v179 offset:19456
	ds_read_b128 v[214:217], v179 offset:20480
	ds_read_b128 v[218:221], v179 offset:21504
	ds_read_b128 v[222:225], v179 offset:22528
	ds_read_b128 v[226:229], v179 offset:23552
	global_load_lds_dwordx4 v[230:231], off
	s_add_i32 m0, s24, 0x2000
	s_add_u32 s24, s16, 0x80000
	v_lshl_add_u64 v[232:233], s[16:17], 0, v[136:137]
	s_addc_u32 s25, s17, 0
	s_add_i32 s26, s28, s2
	global_load_lds_dwordx4 v[232:233], off
	v_lshl_add_u64 v[234:235], s[24:25], 0, v[132:133]
	s_mov_b32 m0, s26
	v_lshl_add_u64 v[236:237], s[18:19], 0, v[134:135]
	global_load_lds_dwordx4 v[234:235], off
	v_lshl_add_u64 v[234:235], s[24:25], 0, v[136:137]
	s_add_i32 m0, s26, 0x2000
	s_nop 0
	global_load_lds_dwordx4 v[234:235], off
	v_lshl_add_u64 v[234:235], s[18:19], 0, v[130:131]
	s_mov_b32 m0, s33
	s_nop 0
	global_load_lds_dwordx4 v[234:235], off
	s_mov_b32 m0, s34
	s_nop 0
	global_load_lds_dwordx4 v[236:237], off
	s_waitcnt vmcnt(8)
	s_waitcnt lgkmcnt(0)
	s_barrier
; #define PG8_STAGE(bufoff, gbase, voff) do { _Pragma("unroll") for (int _i = 0; _i < 2; ++_i) \
;         __builtin_amdgcn_global_load_lds((const unsigned*)((const char*)(gbase) + (voff)[_i]), (PG8_LAS unsigned*)(lds + (bufoff) + ldsw + _i * 8192), 16, 0, 0); } while (0)
; #define PG8_LDA(dst, b, h) do { _Pragma("unroll") for (int m = 0; m < 4; ++m) _Pragma("unroll") for (int k = 0; k < 2; ++k) dst[m][k] = *(const PG8_LAS bf16x8*)(lds + PG8_SA(b, h) + aoff + m * 2048 + k * 1024); } while (0)
; #define PG8_LDB(dst, b, h) do { _Pragma("unroll") for (int n = 0; n < 2; ++n) _Pragma("unroll") for (int k = 0; k < 2; ++k) dst[n][k] = *(const PG8_LAS bf16x8*)(lds + PG8_SB(b, h) + boff + n * 2048 + k * 1024); } while (0)
; #define PG8_MMA(ai, bj, At, Bt) do { __builtin_amdgcn_s_setprio(1); _Pragma("unroll") for (int m = 0; m < 4; ++m) _Pragma("unroll") for (int n = 0; n < 2; ++n) _Pragma("unroll") for (int k = 0; k < 2; ++k) \
;         acc[ai][bj][m][n] = __builtin_amdgcn_mfma_f32_16x16x32_bf16(Bt[n][k], At[m][k], acc[ai][bj][m][n], 0, 0, 0); __builtin_amdgcn_s_setprio(0); } while (0)
; #define PG8_WAIT_V(n) asm volatile("s_waitcnt vmcnt(" #n ")" ::: "memory")
; #define PG8_WAIT_L(n) asm volatile("s_waitcnt lgkmcnt(" #n ")" ::: "memory")
; #define PG8_BAR __builtin_amdgcn_s_barrier()
; #define PG8_SCHED __builtin_amdgcn_sched_barrier(0)
; template <class Epi, class Sched, bool ALIGN_EPI = false, bool SP2 = false>
; __device__ __forceinline__ void gemm_phase(PG8_LAS unsigned char* lds, const Gemm g, const Sched& S, const Epi& E) {
;     ...
;             PG8_WAIT_V(8); PG8_WAIT_L(0); PG8_BAR; PG8_MMA(1, 0, At, B0); PG8_MMA(1, 1, At, B1); PG8_BAR; PG8_SCHED;
;             PG8_LDB(B0, 1, 0); PG8_LDB(B1, 1, 1); PG8_SCHED; PG8_LDA(At, 1, 0); PG8_STAGE(PG8_SA(0, 1), a2 + hstep, voffA);
;             PG8_WAIT_V(8); PG8_WAIT_L(0); PG8_BAR; PG8_MMA(0, 0, At, B0); PG8_MMA(0, 1, At, B1); PG8_BAR; PG8_SCHED;
	s_setprio 1
	s_waitcnt lgkmcnt(0)
	v_mfma_f32_16x16x32_bf16 v[62:65], v[158:161], v[198:201], v[62:65]
	v_mfma_f32_16x16x32_bf16 v[58:61], v[166:169], v[198:201], v[58:61]
	v_mfma_f32_16x16x32_bf16 v[46:49], v[158:161], v[206:209], v[46:49]
	v_mfma_f32_16x16x32_bf16 v[42:45], v[166:169], v[206:209], v[42:45]
	v_mfma_f32_16x16x32_bf16 v[30:33], v[158:161], v[214:217], v[30:33]
	v_mfma_f32_16x16x32_bf16 v[26:29], v[166:169], v[214:217], v[26:29]
	v_mfma_f32_16x16x32_bf16 v[14:17], v[158:161], v[222:225], v[14:17]
	v_mfma_f32_16x16x32_bf16 v[10:13], v[166:169], v[222:225], v[10:13]
	v_mfma_f32_16x16x32_bf16 v[62:65], v[162:165], v[202:205], v[62:65]
	v_mfma_f32_16x16x32_bf16 v[58:61], v[170:173], v[202:205], v[58:61]
	v_mfma_f32_16x16x32_bf16 v[46:49], v[162:165], v[210:213], v[46:49]
	v_mfma_f32_16x16x32_bf16 v[42:45], v[170:173], v[210:213], v[42:45]
	v_mfma_f32_16x16x32_bf16 v[30:33], v[162:165], v[218:221], v[30:33]
	v_mfma_f32_16x16x32_bf16 v[26:29], v[170:173], v[218:221], v[26:29]
	v_mfma_f32_16x16x32_bf16 v[14:17], v[162:165], v[226:229], v[14:17]
	v_mfma_f32_16x16x32_bf16 v[10:13], v[170:173], v[226:229], v[10:13]
	s_setprio 0
	s_setprio 1
	v_mfma_f32_16x16x32_bf16 v[54:57], v[182:185], v[198:201], v[54:57]
	v_mfma_f32_16x16x32_bf16 v[50:53], v[190:193], v[198:201], v[50:53]
	v_mfma_f32_16x16x32_bf16 v[38:41], v[182:185], v[206:209], v[38:41]
	v_mfma_f32_16x16x32_bf16 v[34:37], v[190:193], v[206:209], v[34:37]
	v_mfma_f32_16x16x32_bf16 v[22:25], v[182:185], v[214:217], v[22:25]
	v_mfma_f32_16x16x32_bf16 v[18:21], v[190:193], v[214:217], v[18:21]
	v_mfma_f32_16x16x32_bf16 v[6:9], v[182:185], v[222:225], v[6:9]
	v_mfma_f32_16x16x32_bf16 v[2:5], v[190:193], v[222:225], v[2:5]
	v_mfma_f32_16x16x32_bf16 v[54:57], v[186:189], v[202:205], v[54:57]
	v_mfma_f32_16x16x32_bf16 v[50:53], v[194:197], v[202:205], v[50:53]
	v_mfma_f32_16x16x32_bf16 v[38:41], v[186:189], v[210:213], v[38:41]
	v_mfma_f32_16x16x32_bf16 v[34:37], v[194:197], v[210:213], v[34:37]
	v_mfma_f32_16x16x32_bf16 v[22:25], v[186:189], v[218:221], v[22:25]
	v_mfma_f32_16x16x32_bf16 v[18:21], v[194:197], v[218:221], v[18:21]
	v_mfma_f32_16x16x32_bf16 v[6:9], v[186:189], v[226:229], v[6:9]
	v_mfma_f32_16x16x32_bf16 v[2:5], v[194:197], v[226:229], v[2:5]
	s_setprio 0
	s_barrier
	s_add_i32 s24, 0, 0x18000
	v_add_u32_e32 v138, s24, v174
	s_add_i32 s25, 0, 0x1c000
	ds_read_b128 v[158:161], v138
	ds_read_b128 v[162:165], v138 offset:1024
	ds_read_b128 v[166:169], v138 offset:2048
	ds_read_b128 v[170:173], v138 offset:3072
	v_add_u32_e32 v138, s25, v174
	ds_read_b128 v[182:185], v138
	ds_read_b128 v[186:189], v138 offset:1024
	ds_read_b128 v[190:193], v138 offset:2048
	ds_read_b128 v[194:197], v138 offset:3072
	s_add_u32 s18, s18, 0x80000
	s_addc_u32 s19, s19, 0
	s_mov_b32 m0, s35
	v_lshl_add_u64 v[238:239], s[18:19], 0, v[130:131]
	ds_read_b128 v[198:201], v179 offset:32768
	ds_read_b128 v[202:205], v179 offset:33792
	ds_read_b128 v[206:209], v179 offset:34816
	ds_read_b128 v[210:213], v179 offset:35840
	ds_read_b128 v[214:217], v179 offset:36864
	ds_read_b128 v[218:221], v179 offset:37888
	ds_read_b128 v[222:225], v179 offset:38912
	ds_read_b128 v[226:229], v179 offset:39936
	global_load_lds_dwordx4 v[238:239], off
	v_lshl_add_u64 v[238:239], s[18:19], 0, v[134:135]
	s_mov_b32 m0, s36
	s_nop 0
	global_load_lds_dwordx4 v[238:239], off
	s_waitcnt vmcnt(8)
	s_waitcnt lgkmcnt(0)
	s_barrier
	s_setprio 1
	s_waitcnt lgkmcnt(0)
	v_mfma_f32_16x16x32_bf16 v[126:129], v[158:161], v[198:201], v[126:129]
	v_mfma_f32_16x16x32_bf16 v[122:125], v[166:169], v[198:201], v[122:125]
	v_mfma_f32_16x16x32_bf16 v[110:113], v[158:161], v[206:209], v[110:113]
	v_mfma_f32_16x16x32_bf16 v[106:109], v[166:169], v[206:209], v[106:109]
	v_mfma_f32_16x16x32_bf16 v[94:97], v[158:161], v[214:217], v[94:97]
	v_mfma_f32_16x16x32_bf16 v[90:93], v[166:169], v[214:217], v[90:93]
	v_mfma_f32_16x16x32_bf16 v[78:81], v[158:161], v[222:225], v[78:81]
	v_mfma_f32_16x16x32_bf16 v[74:77], v[166:169], v[222:225], v[74:77]
	v_mfma_f32_16x16x32_bf16 v[126:129], v[162:165], v[202:205], v[126:129]
	v_mfma_f32_16x16x32_bf16 v[122:125], v[170:173], v[202:205], v[122:125]
	v_mfma_f32_16x16x32_bf16 v[110:113], v[162:165], v[210:213], v[110:113]
	v_mfma_f32_16x16x32_bf16 v[106:109], v[170:173], v[210:213], v[106:109]
	v_mfma_f32_16x16x32_bf16 v[94:97], v[162:165], v[218:221], v[94:97]
	v_mfma_f32_16x16x32_bf16 v[90:93], v[170:173], v[218:221], v[90:93]
	v_mfma_f32_16x16x32_bf16 v[78:81], v[162:165], v[226:229], v[78:81]
	v_mfma_f32_16x16x32_bf16 v[74:77], v[170:173], v[226:229], v[74:77]
	s_setprio 0
	s_setprio 1
	v_mfma_f32_16x16x32_bf16 v[118:121], v[182:185], v[198:201], v[118:121]
	v_mfma_f32_16x16x32_bf16 v[114:117], v[190:193], v[198:201], v[114:117]
	v_mfma_f32_16x16x32_bf16 v[102:105], v[182:185], v[206:209], v[102:105]
	v_mfma_f32_16x16x32_bf16 v[98:101], v[190:193], v[206:209], v[98:101]
	v_mfma_f32_16x16x32_bf16 v[86:89], v[182:185], v[214:217], v[86:89]
	v_mfma_f32_16x16x32_bf16 v[82:85], v[190:193], v[214:217], v[82:85]
	v_mfma_f32_16x16x32_bf16 v[70:73], v[182:185], v[222:225], v[70:73]
	v_mfma_f32_16x16x32_bf16 v[66:69], v[190:193], v[222:225], v[66:69]
	v_mfma_f32_16x16x32_bf16 v[118:121], v[186:189], v[202:205], v[118:121]
	v_mfma_f32_16x16x32_bf16 v[114:117], v[194:197], v[202:205], v[114:117]
	v_mfma_f32_16x16x32_bf16 v[102:105], v[186:189], v[210:213], v[102:105]
	v_mfma_f32_16x16x32_bf16 v[98:101], v[194:197], v[210:213], v[98:101]
	v_mfma_f32_16x16x32_bf16 v[86:89], v[186:189], v[218:221], v[86:89]
	v_mfma_f32_16x16x32_bf16 v[82:85], v[194:197], v[218:221], v[82:85]
	v_mfma_f32_16x16x32_bf16 v[70:73], v[186:189], v[226:229], v[70:73]
	v_mfma_f32_16x16x32_bf16 v[66:69], v[194:197], v[226:229], v[66:69]
	s_setprio 0
	s_barrier
; #define PG8_STAGE(bufoff, gbase, voff) do { _Pragma("unroll") for (int _i = 0; _i < 2; ++_i) \
;         __builtin_amdgcn_global_load_lds((const unsigned*)((const char*)(gbase) + (voff)[_i]), (PG8_LAS unsigned*)(lds + (bufoff) + ldsw + _i * 8192), 16, 0, 0); } while (0)
; #define PG8_LDA(dst, b, h) do { _Pragma("unroll") for (int m = 0; m < 4; ++m) _Pragma("unroll") for (int k = 0; k < 2; ++k) dst[m][k] = *(const PG8_LAS bf16x8*)(lds + PG8_SA(b, h) + aoff + m * 2048 + k * 1024); } while (0)
; #define PG8_MMA(ai, bj, At, Bt) do { __builtin_amdgcn_s_setprio(1); _Pragma("unroll") for (int m = 0; m < 4; ++m) _Pragma("unroll") for (int n = 0; n < 2; ++n) _Pragma("unroll") for (int k = 0; k < 2; ++k) \
;         acc[ai][bj][m][n] = __builtin_amdgcn_mfma_f32_16x16x32_bf16(Bt[n][k], At[m][k], acc[ai][bj][m][n], 0, 0, 0); __builtin_amdgcn_s_setprio(0); } while (0)
; #define PG8_WAIT_V(n) asm volatile("s_waitcnt vmcnt(" #n ")" ::: "memory")
; #define PG8_WAIT_L(n) asm volatile("s_waitcnt lgkmcnt(" #n ")" ::: "memory")
; #define PG8_BAR __builtin_amdgcn_s_barrier()
; #define PG8_SCHED __builtin_amdgcn_sched_barrier(0)
; template <class Epi, class Sched, bool ALIGN_EPI = false, bool SP2 = false>
; __device__ __forceinline__ void gemm_phase(PG8_LAS unsigned char* lds, const Gemm g, const Sched& S, const Epi& E) {
;     ...
;         for (int t = 0; t < nt; t += 2) {
;             const bool last = (t == nt - 2);
;             const char* a1 = cA + (size_t)(t + 1) * kstep;
;             const char* a2 = last ? nA : cA + (size_t)(t + 2) * kstep; const char* b2 = last ? nB : cB + (size_t)(t + 2) * kstep;
;             const char* a3 = a2 + kstep; const char* b3 = b2 + kstep;
;     ...
;             PG8_LDA(At, 1, 1); PG8_STAGE(PG8_SB(1, 0), b3, voffB); PG8_STAGE(PG8_SB(1, 1), b3 + hstep, voffB); PG8_STAGE(PG8_SA(1, 0), a3, voffA);
;             PG8_WAIT_V(8); PG8_WAIT_L(0); PG8_BAR; PG8_MMA(1, 0, At, B0); PG8_MMA(1, 1, At, B1); PG8_BAR; PG8_SCHED;
	s_add_i32 s18, s24, s2
	v_lshl_add_u64 v[230:231], v[230:231], 0, s[42:43]
	s_mov_b32 m0, s18
	ds_read_b128 v[198:201], v179 offset:49152
	ds_read_b128 v[202:205], v179 offset:50176
	ds_read_b128 v[206:209], v179 offset:51200
	ds_read_b128 v[210:213], v179 offset:52224
	ds_read_b128 v[214:217], v179 offset:53248
	ds_read_b128 v[218:221], v179 offset:54272
	ds_read_b128 v[222:225], v179 offset:55296
	ds_read_b128 v[226:229], v179 offset:56320
	global_load_lds_dwordx4 v[230:231], off
	s_add_i32 m0, s18, 0x2000
	s_add_u32 s16, s16, 0x80080
	v_lshl_add_u64 v[230:231], v[232:233], 0, s[42:43]
	s_addc_u32 s17, s17, 0
	s_add_i32 s18, s25, s2
	global_load_lds_dwordx4 v[230:231], off
	v_lshl_add_u64 v[230:231], s[16:17], 0, v[132:133]
	s_mov_b32 m0, s18
	s_nop 0
	global_load_lds_dwordx4 v[230:231], off
	v_lshl_add_u64 v[230:231], s[16:17], 0, v[136:137]
	s_add_i32 m0, s18, 0x2000
	s_nop 0
	global_load_lds_dwordx4 v[230:231], off
	v_lshl_add_u64 v[230:231], v[234:235], 0, s[42:43]
	s_mov_b32 m0, s3
	s_nop 0
	global_load_lds_dwordx4 v[230:231], off
	v_lshl_add_u64 v[230:231], v[236:237], 0, s[42:43]
	s_mov_b32 m0, s82
	s_nop 0
	global_load_lds_dwordx4 v[230:231], off
	s_waitcnt vmcnt(8)
	s_waitcnt lgkmcnt(0)
	s_barrier
	s_setprio 1
	s_waitcnt lgkmcnt(0)
	v_mfma_f32_16x16x32_bf16 v[62:65], v[158:161], v[198:201], v[62:65]
	v_mfma_f32_16x16x32_bf16 v[58:61], v[166:169], v[198:201], v[58:61]
	v_mfma_f32_16x16x32_bf16 v[46:49], v[158:161], v[206:209], v[46:49]
	v_mfma_f32_16x16x32_bf16 v[42:45], v[166:169], v[206:209], v[42:45]
	v_mfma_f32_16x16x32_bf16 v[30:33], v[158:161], v[214:217], v[30:33]
	v_mfma_f32_16x16x32_bf16 v[26:29], v[166:169], v[214:217], v[26:29]
	v_mfma_f32_16x16x32_bf16 v[14:17], v[158:161], v[222:225], v[14:17]
	v_mfma_f32_16x16x32_bf16 v[10:13], v[166:169], v[222:225], v[10:13]
	v_mfma_f32_16x16x32_bf16 v[62:65], v[162:165], v[202:205], v[62:65]
	v_mfma_f32_16x16x32_bf16 v[58:61], v[170:173], v[202:205], v[58:61]
	v_mfma_f32_16x16x32_bf16 v[46:49], v[162:165], v[210:213], v[46:49]
	v_mfma_f32_16x16x32_bf16 v[42:45], v[170:173], v[210:213], v[42:45]
	v_mfma_f32_16x16x32_bf16 v[30:33], v[162:165], v[218:221], v[30:33]
	v_mfma_f32_16x16x32_bf16 v[26:29], v[170:173], v[218:221], v[26:29]
	v_mfma_f32_16x16x32_bf16 v[14:17], v[162:165], v[226:229], v[14:17]
	v_mfma_f32_16x16x32_bf16 v[10:13], v[170:173], v[226:229], v[10:13]
	s_setprio 0
	s_setprio 1
	v_mfma_f32_16x16x32_bf16 v[54:57], v[182:185], v[198:201], v[54:57]
	v_mfma_f32_16x16x32_bf16 v[50:53], v[190:193], v[198:201], v[50:53]
	v_mfma_f32_16x16x32_bf16 v[38:41], v[182:185], v[206:209], v[38:41]
	v_mfma_f32_16x16x32_bf16 v[34:37], v[190:193], v[206:209], v[34:37]
	v_mfma_f32_16x16x32_bf16 v[22:25], v[182:185], v[214:217], v[22:25]
	v_mfma_f32_16x16x32_bf16 v[18:21], v[190:193], v[214:217], v[18:21]
	v_mfma_f32_16x16x32_bf16 v[6:9], v[182:185], v[222:225], v[6:9]
	v_mfma_f32_16x16x32_bf16 v[2:5], v[190:193], v[222:225], v[2:5]
	v_mfma_f32_16x16x32_bf16 v[54:57], v[186:189], v[202:205], v[54:57]
	v_mfma_f32_16x16x32_bf16 v[50:53], v[194:197], v[202:205], v[50:53]
	v_mfma_f32_16x16x32_bf16 v[38:41], v[186:189], v[210:213], v[38:41]
	v_mfma_f32_16x16x32_bf16 v[34:37], v[194:197], v[210:213], v[34:37]
	v_mfma_f32_16x16x32_bf16 v[22:25], v[186:189], v[218:221], v[22:25]
	v_mfma_f32_16x16x32_bf16 v[18:21], v[194:197], v[218:221], v[18:21]
	v_mfma_f32_16x16x32_bf16 v[6:9], v[186:189], v[226:229], v[6:9]
	v_mfma_f32_16x16x32_bf16 v[2:5], v[194:197], v[226:229], v[2:5]
	s_setprio 0
	s_add_i32 s23, s23, 2
	s_add_u32 s0, s0, 0x100
	s_addc_u32 s1, s1, 0
	s_add_u32 s21, s21, 0x100
	s_addc_u32 s22, s22, 0
	s_cmp_gt_u32 s23, 29
	s_barrier
	s_cbranch_scc0 .LBB0_582
	s_and_b64 vcc, exec, s[84:85]
	s_cbranch_vccz .LBB0_585
	s_barrier

; #define PG8_STAGE(bufoff, gbase, voff) do { _Pragma("unroll") for (int _i = 0; _i < 2; ++_i) \
;         __builtin_amdgcn_global_load_lds((const unsigned*)((const char*)(gbase) + (voff)[_i]), (PG8_LAS unsigned*)(lds + (bufoff) + ldsw + _i * 8192), 16, 0, 0); } while (0)
; #define PG8_LDA(dst, b, h) do { _Pragma("unroll") for (int m = 0; m < 4; ++m) _Pragma("unroll") for (int k = 0; k < 2; ++k) dst[m][k] = *(const PG8_LAS bf16x8*)(lds + PG8_SA(b, h) + aoff + m * 2048 + k * 1024); } while (0)
; #define PG8_LDB(dst, b, h) do { _Pragma("unroll") for (int n = 0; n < 2; ++n) _Pragma("unroll") for (int k = 0; k < 2; ++k) dst[n][k] = *(const PG8_LAS bf16x8*)(lds + PG8_SB(b, h) + boff + n * 2048 + k * 1024); } while (0)
; #define PG8_MMA(ai, bj, At, Bt) do { __builtin_amdgcn_s_setprio(1); _Pragma("unroll") for (int m = 0; m < 4; ++m) _Pragma("unroll") for (int n = 0; n < 2; ++n) _Pragma("unroll") for (int k = 0; k < 2; ++k) \
;         acc[ai][bj][m][n] = __builtin_amdgcn_mfma_f32_16x16x32_bf16(Bt[n][k], At[m][k], acc[ai][bj][m][n], 0, 0, 0); __builtin_amdgcn_s_setprio(0); } while (0)
; #define PG8_WAIT_V(n) asm volatile("s_waitcnt vmcnt(" #n ")" ::: "memory")
; #define PG8_WAIT_L(n) asm volatile("s_waitcnt lgkmcnt(" #n ")" ::: "memory")
; #define PG8_BAR __builtin_amdgcn_s_barrier()
; #define PG8_SCHED __builtin_amdgcn_sched_barrier(0)
; template <class Epi, class Sched, bool ALIGN_EPI = false, bool SP2 = false>
; __device__ __forceinline__ void gemm_phase(PG8_LAS unsigned char* lds, const Gemm g, const Sched& S, const Epi& E) {
;     ...
;             if constexpr (SP2) {
;             PG8_LDB(B0, 0, 0); PG8_LDB(B1, 0, 1); PG8_SCHED; PG8_LDA(At, 0, 0); PG8_STAGE(PG8_SA(1, 1), a1 + hstep, voffA);
;             PG8_WAIT_V(8); PG8_WAIT_L(0); PG8_BAR; PG8_MMA(0, 0, At, B0); PG8_MMA(0, 1, At, B1); PG8_BAR; PG8_SCHED;
;             PG8_LDA(At, 0, 1); PG8_STAGE(PG8_SB(0, 0), b2, voffB); PG8_STAGE(PG8_SB(0, 1), b2 + hstep, voffB); PG8_STAGE(PG8_SA(0, 0), a2, voffA);
;             PG8_WAIT_V(8); PG8_WAIT_L(0); PG8_BAR; PG8_MMA(1, 0, At, B0); PG8_MMA(1, 1, At, B1); PG8_BAR; PG8_SCHED;
.LBB0_1465:
	s_add_i32 s85, s84, 2
	s_add_u32 s94, s60, 0x80
	s_addc_u32 s95, s61, 0
	s_add_i32 s54, 0, 0x10000
	s_cmp_eq_u32 s52, s84
	s_cselect_b32 s95, s1, s95
	s_cselect_b32 s94, s0, s94
	s_cselect_b32 vcc_hi, s75, s63
	s_cselect_b32 vcc_lo, s74, s62
	s_add_i32 s55, 0, 0x14000
	v_add_u32_e32 v154, s54, v173
	v_add_u32_e32 v170, s55, v173
	ds_read_b128 v[130:133], v154
	ds_read_b128 v[134:137], v154 offset:1024
	ds_read_b128 v[150:153], v154 offset:2048
	ds_read_b128 v[154:157], v154 offset:3072
	ds_read_b128 v[158:161], v170
	ds_read_b128 v[162:165], v170 offset:1024
	ds_read_b128 v[166:169], v170 offset:2048
	ds_read_b128 v[188:191], v170 offset:3072
	v_lshl_add_u64 v[170:171], s[60:61], 0, v[146:147]
	s_add_i32 m0, s3, 0xc000
	ds_read_b128 v[192:195], v175
	ds_read_b128 v[196:199], v175 offset:1024
	ds_read_b128 v[200:203], v175 offset:2048
	ds_read_b128 v[204:207], v175 offset:3072
	ds_read_b128 v[208:211], v175 offset:4096
	ds_read_b128 v[212:215], v175 offset:5120
	ds_read_b128 v[216:219], v175 offset:6144
	ds_read_b128 v[220:223], v175 offset:7168
	global_load_lds_dwordx4 v[170:171], off
	v_lshl_add_u64 v[170:171], s[60:61], 0, v[148:149]
	s_add_i32 m0, s3, 0xe000
	s_nop 0
	global_load_lds_dwordx4 v[170:171], off
	s_waitcnt vmcnt(8)
	s_waitcnt lgkmcnt(0)
	s_barrier
	s_setprio 1
	s_waitcnt lgkmcnt(0)
	v_mfma_f32_16x16x32_bf16 v[126:129], v[130:133], v[192:195], v[126:129]
	v_mfma_f32_16x16x32_bf16 v[94:97], v[150:153], v[192:195], v[94:97]
	v_mfma_f32_16x16x32_bf16 v[122:125], v[130:133], v[200:203], v[122:125]
	v_mfma_f32_16x16x32_bf16 v[90:93], v[150:153], v[200:203], v[90:93]
	v_mfma_f32_16x16x32_bf16 v[118:121], v[130:133], v[208:211], v[118:121]
	v_mfma_f32_16x16x32_bf16 v[86:89], v[150:153], v[208:211], v[86:89]
	v_mfma_f32_16x16x32_bf16 v[114:117], v[130:133], v[216:219], v[114:117]
	v_mfma_f32_16x16x32_bf16 v[82:85], v[150:153], v[216:219], v[82:85]
	v_mfma_f32_16x16x32_bf16 v[126:129], v[134:137], v[196:199], v[126:129]
	v_mfma_f32_16x16x32_bf16 v[94:97], v[154:157], v[196:199], v[94:97]
	v_mfma_f32_16x16x32_bf16 v[122:125], v[134:137], v[204:207], v[122:125]
	v_mfma_f32_16x16x32_bf16 v[90:93], v[154:157], v[204:207], v[90:93]
	v_mfma_f32_16x16x32_bf16 v[118:121], v[134:137], v[212:215], v[118:121]
	v_mfma_f32_16x16x32_bf16 v[86:89], v[154:157], v[212:215], v[86:89]
	v_mfma_f32_16x16x32_bf16 v[114:117], v[134:137], v[220:223], v[114:117]
	v_mfma_f32_16x16x32_bf16 v[82:85], v[154:157], v[220:223], v[82:85]
	s_setprio 0
	s_setprio 1
	v_mfma_f32_16x16x32_bf16 v[62:65], v[158:161], v[192:195], v[62:65]
	v_mfma_f32_16x16x32_bf16 v[30:33], v[166:169], v[192:195], v[30:33]
	v_mfma_f32_16x16x32_bf16 v[58:61], v[158:161], v[200:203], v[58:61]
	v_mfma_f32_16x16x32_bf16 v[26:29], v[166:169], v[200:203], v[26:29]
	v_mfma_f32_16x16x32_bf16 v[54:57], v[158:161], v[208:211], v[54:57]
	v_mfma_f32_16x16x32_bf16 v[22:25], v[166:169], v[208:211], v[22:25]
	v_mfma_f32_16x16x32_bf16 v[50:53], v[158:161], v[216:219], v[50:53]
	v_mfma_f32_16x16x32_bf16 v[18:21], v[166:169], v[216:219], v[18:21]
	v_mfma_f32_16x16x32_bf16 v[62:65], v[162:165], v[196:199], v[62:65]
	v_mfma_f32_16x16x32_bf16 v[30:33], v[188:191], v[196:199], v[30:33]
	v_mfma_f32_16x16x32_bf16 v[58:61], v[162:165], v[204:207], v[58:61]
	v_mfma_f32_16x16x32_bf16 v[26:29], v[188:191], v[204:207], v[26:29]
	v_mfma_f32_16x16x32_bf16 v[54:57], v[162:165], v[212:215], v[54:57]
	v_mfma_f32_16x16x32_bf16 v[22:25], v[188:191], v[212:215], v[22:25]
	v_mfma_f32_16x16x32_bf16 v[50:53], v[162:165], v[220:223], v[50:53]
	v_mfma_f32_16x16x32_bf16 v[18:21], v[188:191], v[220:223], v[18:21]
	s_setprio 0
	s_barrier
	s_add_i32 s54, s54, s2
	v_lshl_add_u64 v[170:171], vcc, 0, v[142:143]
	s_mov_b32 m0, s54
	ds_read_b128 v[192:195], v175 offset:16384
	ds_read_b128 v[196:199], v175 offset:17408
	ds_read_b128 v[200:203], v175 offset:18432
	ds_read_b128 v[204:207], v175 offset:19456
	ds_read_b128 v[208:211], v175 offset:20480
	ds_read_b128 v[212:215], v175 offset:21504
	ds_read_b128 v[216:219], v175 offset:22528
	ds_read_b128 v[220:223], v175 offset:23552
	global_load_lds_dwordx4 v[170:171], off
	s_add_i32 m0, s54, 0x2000
	v_lshl_add_u64 v[176:177], vcc, 0, v[138:139]
	s_add_u32 vcc_lo, vcc_lo, s10
	s_addc_u32 vcc_hi, vcc_hi, s11
	s_add_i32 s54, s55, s2
	global_load_lds_dwordx4 v[176:177], off
	v_lshl_add_u64 v[224:225], vcc, 0, v[142:143]
	s_mov_b32 m0, s54
	v_lshl_add_u64 v[226:227], vcc, 0, v[138:139]
	global_load_lds_dwordx4 v[224:225], off
	s_add_i32 m0, s54, 0x2000
	v_lshl_add_u64 v[228:229], s[94:95], 0, v[144:145]
	global_load_lds_dwordx4 v[226:227], off
	s_mov_b32 m0, s3
	v_lshl_add_u64 v[230:231], s[94:95], 0, v[140:141]
	global_load_lds_dwordx4 v[228:229], off
	s_mov_b32 m0, s4
	s_nop 0
	global_load_lds_dwordx4 v[230:231], off
	s_waitcnt vmcnt(8)
	s_waitcnt lgkmcnt(0)
	s_barrier
; #define PG8_STAGE(bufoff, gbase, voff) do { _Pragma("unroll") for (int _i = 0; _i < 2; ++_i) \
;         __builtin_amdgcn_global_load_lds((const unsigned*)((const char*)(gbase) + (voff)[_i]), (PG8_LAS unsigned*)(lds + (bufoff) + ldsw + _i * 8192), 16, 0, 0); } while (0)
; #define PG8_LDA(dst, b, h) do { _Pragma("unroll") for (int m = 0; m < 4; ++m) _Pragma("unroll") for (int k = 0; k < 2; ++k) dst[m][k] = *(const PG8_LAS bf16x8*)(lds + PG8_SA(b, h) + aoff + m * 2048 + k * 1024); } while (0)
; #define PG8_LDB(dst, b, h) do { _Pragma("unroll") for (int n = 0; n < 2; ++n) _Pragma("unroll") for (int k = 0; k < 2; ++k) dst[n][k] = *(const PG8_LAS bf16x8*)(lds + PG8_SB(b, h) + boff + n * 2048 + k * 1024); } while (0)
; #define PG8_MMA(ai, bj, At, Bt) do { __builtin_amdgcn_s_setprio(1); _Pragma("unroll") for (int m = 0; m < 4; ++m) _Pragma("unroll") for (int n = 0; n < 2; ++n) _Pragma("unroll") for (int k = 0; k < 2; ++k) \
;         acc[ai][bj][m][n] = __builtin_amdgcn_mfma_f32_16x16x32_bf16(Bt[n][k], At[m][k], acc[ai][bj][m][n], 0, 0, 0); __builtin_amdgcn_s_setprio(0); } while (0)
; #define PG8_WAIT_V(n) asm volatile("s_waitcnt vmcnt(" #n ")" ::: "memory")
; #define PG8_WAIT_L(n) asm volatile("s_waitcnt lgkmcnt(" #n ")" ::: "memory")
; #define PG8_BAR __builtin_amdgcn_s_barrier()
; #define PG8_SCHED __builtin_amdgcn_sched_barrier(0)
; template <class Epi, class Sched, bool ALIGN_EPI = false, bool SP2 = false>
; __device__ __forceinline__ void gemm_phase(PG8_LAS unsigned char* lds, const Gemm g, const Sched& S, const Epi& E) {
;     ...
;             PG8_WAIT_V(8); PG8_WAIT_L(0); PG8_BAR; PG8_MMA(1, 0, At, B0); PG8_MMA(1, 1, At, B1); PG8_BAR; PG8_SCHED;
;             PG8_LDB(B0, 1, 0); PG8_LDB(B1, 1, 1); PG8_SCHED; PG8_LDA(At, 1, 0); PG8_STAGE(PG8_SA(0, 1), a2 + hstep, voffA);
;             PG8_WAIT_V(8); PG8_WAIT_L(0); PG8_BAR; PG8_MMA(0, 0, At, B0); PG8_MMA(0, 1, At, B1); PG8_BAR; PG8_SCHED;
	s_setprio 1
	s_waitcnt lgkmcnt(0)
	v_mfma_f32_16x16x32_bf16 v[110:113], v[130:133], v[192:195], v[110:113]
	v_mfma_f32_16x16x32_bf16 v[78:81], v[150:153], v[192:195], v[78:81]
	v_mfma_f32_16x16x32_bf16 v[106:109], v[130:133], v[200:203], v[106:109]
	v_mfma_f32_16x16x32_bf16 v[74:77], v[150:153], v[200:203], v[74:77]
	v_mfma_f32_16x16x32_bf16 v[102:105], v[130:133], v[208:211], v[102:105]
	v_mfma_f32_16x16x32_bf16 v[70:73], v[150:153], v[208:211], v[70:73]
	v_mfma_f32_16x16x32_bf16 v[98:101], v[130:133], v[216:219], v[98:101]
	v_mfma_f32_16x16x32_bf16 v[66:69], v[150:153], v[216:219], v[66:69]
	v_mfma_f32_16x16x32_bf16 v[110:113], v[134:137], v[196:199], v[110:113]
	v_mfma_f32_16x16x32_bf16 v[78:81], v[154:157], v[196:199], v[78:81]
	v_mfma_f32_16x16x32_bf16 v[106:109], v[134:137], v[204:207], v[106:109]
	v_mfma_f32_16x16x32_bf16 v[74:77], v[154:157], v[204:207], v[74:77]
	v_mfma_f32_16x16x32_bf16 v[102:105], v[134:137], v[212:215], v[102:105]
	v_mfma_f32_16x16x32_bf16 v[70:73], v[154:157], v[212:215], v[70:73]
	v_mfma_f32_16x16x32_bf16 v[98:101], v[134:137], v[220:223], v[98:101]
	v_mfma_f32_16x16x32_bf16 v[66:69], v[154:157], v[220:223], v[66:69]
	s_setprio 0
	s_setprio 1
	v_mfma_f32_16x16x32_bf16 v[46:49], v[158:161], v[192:195], v[46:49]
	v_mfma_f32_16x16x32_bf16 v[14:17], v[166:169], v[192:195], v[14:17]
	v_mfma_f32_16x16x32_bf16 v[42:45], v[158:161], v[200:203], v[42:45]
	v_mfma_f32_16x16x32_bf16 v[10:13], v[166:169], v[200:203], v[10:13]
	v_mfma_f32_16x16x32_bf16 v[38:41], v[158:161], v[208:211], v[38:41]
	v_mfma_f32_16x16x32_bf16 v[6:9], v[166:169], v[208:211], v[6:9]
	v_mfma_f32_16x16x32_bf16 v[34:37], v[158:161], v[216:219], v[34:37]
	v_mfma_f32_16x16x32_bf16 v[2:5], v[166:169], v[216:219], v[2:5]
	v_mfma_f32_16x16x32_bf16 v[46:49], v[162:165], v[196:199], v[46:49]
	v_mfma_f32_16x16x32_bf16 v[14:17], v[188:191], v[196:199], v[14:17]
	v_mfma_f32_16x16x32_bf16 v[42:45], v[162:165], v[204:207], v[42:45]
	v_mfma_f32_16x16x32_bf16 v[10:13], v[188:191], v[204:207], v[10:13]
	v_mfma_f32_16x16x32_bf16 v[38:41], v[162:165], v[212:215], v[38:41]
	v_mfma_f32_16x16x32_bf16 v[6:9], v[188:191], v[212:215], v[6:9]
	v_mfma_f32_16x16x32_bf16 v[34:37], v[162:165], v[220:223], v[34:37]
	v_mfma_f32_16x16x32_bf16 v[2:5], v[188:191], v[220:223], v[2:5]
	s_setprio 0
	s_barrier
	s_add_i32 s54, 0, 0x18000
	s_add_i32 s55, 0, 0x1c000
	v_add_u32_e32 v154, s54, v173
	v_add_u32_e32 v180, s55, v173
	ds_read_b128 v[130:133], v154
	ds_read_b128 v[134:137], v154 offset:1024
	ds_read_b128 v[150:153], v154 offset:2048
	ds_read_b128 v[154:157], v154 offset:3072
	ds_read_b128 v[158:161], v180
	ds_read_b128 v[162:165], v180 offset:1024
	ds_read_b128 v[166:169], v180 offset:2048
	ds_read_b128 v[188:191], v180 offset:3072
	s_add_u32 s94, s94, s10
	s_addc_u32 s95, s95, s11
	s_mov_b32 m0, s5
	v_lshl_add_u64 v[232:233], s[94:95], 0, v[144:145]
	ds_read_b128 v[192:195], v175 offset:32768
	ds_read_b128 v[196:199], v175 offset:33792
	ds_read_b128 v[200:203], v175 offset:34816
	ds_read_b128 v[204:207], v175 offset:35840
	ds_read_b128 v[208:211], v175 offset:36864
	ds_read_b128 v[212:215], v175 offset:37888
	ds_read_b128 v[216:219], v175 offset:38912
	ds_read_b128 v[220:223], v175 offset:39936
	global_load_lds_dwordx4 v[232:233], off
	v_lshl_add_u64 v[232:233], s[94:95], 0, v[140:141]
	s_mov_b32 m0, s19
	s_nop 0
	global_load_lds_dwordx4 v[232:233], off
	s_waitcnt vmcnt(8)
	s_waitcnt lgkmcnt(0)
	s_barrier
	s_setprio 1
	s_waitcnt lgkmcnt(0)
	v_mfma_f32_16x16x32_bf16 v[126:129], v[130:133], v[192:195], v[126:129]
	v_mfma_f32_16x16x32_bf16 v[94:97], v[150:153], v[192:195], v[94:97]
	v_mfma_f32_16x16x32_bf16 v[122:125], v[130:133], v[200:203], v[122:125]
	v_mfma_f32_16x16x32_bf16 v[90:93], v[150:153], v[200:203], v[90:93]
	v_mfma_f32_16x16x32_bf16 v[118:121], v[130:133], v[208:211], v[118:121]
	v_mfma_f32_16x16x32_bf16 v[86:89], v[150:153], v[208:211], v[86:89]
	v_mfma_f32_16x16x32_bf16 v[114:117], v[130:133], v[216:219], v[114:117]
	v_mfma_f32_16x16x32_bf16 v[82:85], v[150:153], v[216:219], v[82:85]
	v_mfma_f32_16x16x32_bf16 v[126:129], v[134:137], v[196:199], v[126:129]
	v_mfma_f32_16x16x32_bf16 v[94:97], v[154:157], v[196:199], v[94:97]
	v_mfma_f32_16x16x32_bf16 v[122:125], v[134:137], v[204:207], v[122:125]
	v_mfma_f32_16x16x32_bf16 v[90:93], v[154:157], v[204:207], v[90:93]
	v_mfma_f32_16x16x32_bf16 v[118:121], v[134:137], v[212:215], v[118:121]
	v_mfma_f32_16x16x32_bf16 v[86:89], v[154:157], v[212:215], v[86:89]
	v_mfma_f32_16x16x32_bf16 v[114:117], v[134:137], v[220:223], v[114:117]
	v_mfma_f32_16x16x32_bf16 v[82:85], v[154:157], v[220:223], v[82:85]
	s_setprio 0
	s_setprio 1
	v_mfma_f32_16x16x32_bf16 v[62:65], v[158:161], v[192:195], v[62:65]
	v_mfma_f32_16x16x32_bf16 v[30:33], v[166:169], v[192:195], v[30:33]
	v_mfma_f32_16x16x32_bf16 v[58:61], v[158:161], v[200:203], v[58:61]
	v_mfma_f32_16x16x32_bf16 v[26:29], v[166:169], v[200:203], v[26:29]
	v_mfma_f32_16x16x32_bf16 v[54:57], v[158:161], v[208:211], v[54:57]
	v_mfma_f32_16x16x32_bf16 v[22:25], v[166:169], v[208:211], v[22:25]
	v_mfma_f32_16x16x32_bf16 v[50:53], v[158:161], v[216:219], v[50:53]
	v_mfma_f32_16x16x32_bf16 v[18:21], v[166:169], v[216:219], v[18:21]
	v_mfma_f32_16x16x32_bf16 v[62:65], v[162:165], v[196:199], v[62:65]
	v_mfma_f32_16x16x32_bf16 v[30:33], v[188:191], v[196:199], v[30:33]
	v_mfma_f32_16x16x32_bf16 v[58:61], v[162:165], v[204:207], v[58:61]
	v_mfma_f32_16x16x32_bf16 v[26:29], v[188:191], v[204:207], v[26:29]
	v_mfma_f32_16x16x32_bf16 v[54:57], v[162:165], v[212:215], v[54:57]
	v_mfma_f32_16x16x32_bf16 v[22:25], v[188:191], v[212:215], v[22:25]
	v_mfma_f32_16x16x32_bf16 v[50:53], v[162:165], v[220:223], v[50:53]
	v_mfma_f32_16x16x32_bf16 v[18:21], v[188:191], v[220:223], v[18:21]
	s_setprio 0
	s_barrier
; #define PG8_STAGE(bufoff, gbase, voff) do { _Pragma("unroll") for (int _i = 0; _i < 2; ++_i) \
;         __builtin_amdgcn_global_load_lds((const unsigned*)((const char*)(gbase) + (voff)[_i]), (PG8_LAS unsigned*)(lds + (bufoff) + ldsw + _i * 8192), 16, 0, 0); } while (0)
; #define PG8_LDA(dst, b, h) do { _Pragma("unroll") for (int m = 0; m < 4; ++m) _Pragma("unroll") for (int k = 0; k < 2; ++k) dst[m][k] = *(const PG8_LAS bf16x8*)(lds + PG8_SA(b, h) + aoff + m * 2048 + k * 1024); } while (0)
; #define PG8_MMA(ai, bj, At, Bt) do { __builtin_amdgcn_s_setprio(1); _Pragma("unroll") for (int m = 0; m < 4; ++m) _Pragma("unroll") for (int n = 0; n < 2; ++n) _Pragma("unroll") for (int k = 0; k < 2; ++k) \
;         acc[ai][bj][m][n] = __builtin_amdgcn_mfma_f32_16x16x32_bf16(Bt[n][k], At[m][k], acc[ai][bj][m][n], 0, 0, 0); __builtin_amdgcn_s_setprio(0); } while (0)
; #define PG8_WAIT_V(n) asm volatile("s_waitcnt vmcnt(" #n ")" ::: "memory")
; #define PG8_WAIT_L(n) asm volatile("s_waitcnt lgkmcnt(" #n ")" ::: "memory")
; #define PG8_BAR __builtin_amdgcn_s_barrier()
; #define PG8_SCHED __builtin_amdgcn_sched_barrier(0)
; template <class Epi, class Sched, bool ALIGN_EPI = false, bool SP2 = false>
; __device__ __forceinline__ void gemm_phase(PG8_LAS unsigned char* lds, const Gemm g, const Sched& S, const Epi& E) {
;     ...
;         for (int t = 0; t < nt; t += 2) {
;             const bool last = (t == nt - 2);
;             const char* a1 = cA + (size_t)(t + 1) * kstep;
;             const char* a2 = last ? nA : cA + (size_t)(t + 2) * kstep; const char* b2 = last ? nB : cB + (size_t)(t + 2) * kstep;
;             const char* a3 = a2 + kstep; const char* b3 = b2 + kstep;
;     ...
;             PG8_LDA(At, 1, 1); PG8_STAGE(PG8_SB(1, 0), b3, voffB); PG8_STAGE(PG8_SB(1, 1), b3 + hstep, voffB); PG8_STAGE(PG8_SA(1, 0), a3, voffA);
;             PG8_WAIT_V(8); PG8_WAIT_L(0); PG8_BAR; PG8_MMA(1, 0, At, B0); PG8_MMA(1, 1, At, B1); PG8_BAR; PG8_SCHED;
	s_add_i32 s54, s54, s2
	v_lshl_add_u64 v[170:171], v[170:171], 0, s[42:43]
	s_mov_b32 m0, s54
	ds_read_b128 v[192:195], v175 offset:49152
	ds_read_b128 v[196:199], v175 offset:50176
	ds_read_b128 v[200:203], v175 offset:51200
	ds_read_b128 v[204:207], v175 offset:52224
	ds_read_b128 v[208:211], v175 offset:53248
	ds_read_b128 v[212:215], v175 offset:54272
	ds_read_b128 v[216:219], v175 offset:55296
	ds_read_b128 v[220:223], v175 offset:56320
	global_load_lds_dwordx4 v[170:171], off
	v_lshl_add_u64 v[170:171], v[176:177], 0, s[42:43]
	s_add_i32 m0, s54, 0x2000
	s_add_i32 s54, s55, s2
	global_load_lds_dwordx4 v[170:171], off
	v_lshl_add_u64 v[170:171], v[224:225], 0, s[42:43]
	s_mov_b32 m0, s54
	s_nop 0
	global_load_lds_dwordx4 v[170:171], off
	v_lshl_add_u64 v[170:171], v[226:227], 0, s[42:43]
	s_add_i32 m0, s54, 0x2000
	s_nop 0
	global_load_lds_dwordx4 v[170:171], off
	v_lshl_add_u64 v[170:171], v[228:229], 0, s[42:43]
	s_mov_b32 m0, s26
	s_nop 0
	global_load_lds_dwordx4 v[170:171], off
	v_lshl_add_u64 v[170:171], v[230:231], 0, s[42:43]
	s_mov_b32 m0, s45
	s_nop 0
	global_load_lds_dwordx4 v[170:171], off
	s_waitcnt vmcnt(8)
	s_waitcnt lgkmcnt(0)
	s_barrier
	s_setprio 1
	s_waitcnt lgkmcnt(0)
	v_mfma_f32_16x16x32_bf16 v[110:113], v[130:133], v[192:195], v[110:113]
	v_mfma_f32_16x16x32_bf16 v[78:81], v[150:153], v[192:195], v[78:81]
	v_mfma_f32_16x16x32_bf16 v[106:109], v[130:133], v[200:203], v[106:109]
	v_mfma_f32_16x16x32_bf16 v[74:77], v[150:153], v[200:203], v[74:77]
	v_mfma_f32_16x16x32_bf16 v[102:105], v[130:133], v[208:211], v[102:105]
	v_mfma_f32_16x16x32_bf16 v[70:73], v[150:153], v[208:211], v[70:73]
	v_mfma_f32_16x16x32_bf16 v[98:101], v[130:133], v[216:219], v[98:101]
	v_mfma_f32_16x16x32_bf16 v[66:69], v[150:153], v[216:219], v[66:69]
	v_mfma_f32_16x16x32_bf16 v[110:113], v[134:137], v[196:199], v[110:113]
	v_mfma_f32_16x16x32_bf16 v[78:81], v[154:157], v[196:199], v[78:81]
	v_mfma_f32_16x16x32_bf16 v[106:109], v[134:137], v[204:207], v[106:109]
	v_mfma_f32_16x16x32_bf16 v[74:77], v[154:157], v[204:207], v[74:77]
	v_mfma_f32_16x16x32_bf16 v[102:105], v[134:137], v[212:215], v[102:105]
	v_mfma_f32_16x16x32_bf16 v[70:73], v[154:157], v[212:215], v[70:73]
	v_mfma_f32_16x16x32_bf16 v[98:101], v[134:137], v[220:223], v[98:101]
	v_mfma_f32_16x16x32_bf16 v[66:69], v[154:157], v[220:223], v[66:69]
	s_setprio 0
	s_setprio 1
	v_mfma_f32_16x16x32_bf16 v[46:49], v[158:161], v[192:195], v[46:49]
	v_mfma_f32_16x16x32_bf16 v[14:17], v[166:169], v[192:195], v[14:17]
	v_mfma_f32_16x16x32_bf16 v[42:45], v[158:161], v[200:203], v[42:45]
	v_mfma_f32_16x16x32_bf16 v[10:13], v[166:169], v[200:203], v[10:13]
	v_mfma_f32_16x16x32_bf16 v[38:41], v[158:161], v[208:211], v[38:41]
	v_mfma_f32_16x16x32_bf16 v[6:9], v[166:169], v[208:211], v[6:9]
	v_mfma_f32_16x16x32_bf16 v[34:37], v[158:161], v[216:219], v[34:37]
	v_mfma_f32_16x16x32_bf16 v[2:5], v[166:169], v[216:219], v[2:5]
	v_mfma_f32_16x16x32_bf16 v[46:49], v[162:165], v[196:199], v[46:49]
	v_mfma_f32_16x16x32_bf16 v[14:17], v[188:191], v[196:199], v[14:17]
	v_mfma_f32_16x16x32_bf16 v[42:45], v[162:165], v[204:207], v[42:45]
	v_mfma_f32_16x16x32_bf16 v[10:13], v[188:191], v[204:207], v[10:13]
	v_mfma_f32_16x16x32_bf16 v[38:41], v[162:165], v[212:215], v[38:41]
	v_mfma_f32_16x16x32_bf16 v[6:9], v[188:191], v[212:215], v[6:9]
	v_mfma_f32_16x16x32_bf16 v[34:37], v[162:165], v[220:223], v[34:37]
	v_mfma_f32_16x16x32_bf16 v[2:5], v[188:191], v[220:223], v[2:5]
	s_setprio 0
	s_add_u32 s60, s60, 0x100
	s_addc_u32 s61, s61, 0
	s_add_u32 s62, s62, 0x100
	s_addc_u32 s63, s63, 0
	s_cmp_ge_i32 s85, s9
	s_mov_b32 s84, s85
	s_barrier
	s_cbranch_scc0 .LBB0_1465

; #define PG8_STAGE(bufoff, gbase, voff) do { _Pragma("unroll") for (int _i = 0; _i < 2; ++_i) \
;         __builtin_amdgcn_global_load_lds((const unsigned*)((const char*)(gbase) + (voff)[_i]), (PG8_LAS unsigned*)(lds + (bufoff) + ldsw + _i * 8192), 16, 0, 0); } while (0)
; #define PG8_LDA(dst, b, h) do { _Pragma("unroll") for (int m = 0; m < 4; ++m) _Pragma("unroll") for (int k = 0; k < 2; ++k) dst[m][k] = *(const PG8_LAS bf16x8*)(lds + PG8_SA(b, h) + aoff + m * 2048 + k * 1024); } while (0)
; #define PG8_LDB(dst, b, h) do { _Pragma("unroll") for (int n = 0; n < 2; ++n) _Pragma("unroll") for (int k = 0; k < 2; ++k) dst[n][k] = *(const PG8_LAS bf16x8*)(lds + PG8_SB(b, h) + boff + n * 2048 + k * 1024); } while (0)
; #define PG8_MMA(ai, bj, At, Bt) do { __builtin_amdgcn_s_setprio(1); _Pragma("unroll") for (int m = 0; m < 4; ++m) _Pragma("unroll") for (int n = 0; n < 2; ++n) _Pragma("unroll") for (int k = 0; k < 2; ++k) \
;         acc[ai][bj][m][n] = __builtin_amdgcn_mfma_f32_16x16x32_bf16(Bt[n][k], At[m][k], acc[ai][bj][m][n], 0, 0, 0); __builtin_amdgcn_s_setprio(0); } while (0)
; #define PG8_WAIT_V(n) asm volatile("s_waitcnt vmcnt(" #n ")" ::: "memory")
; #define PG8_WAIT_L(n) asm volatile("s_waitcnt lgkmcnt(" #n ")" ::: "memory")
; #define PG8_BAR __builtin_amdgcn_s_barrier()
; #define PG8_SCHED __builtin_amdgcn_sched_barrier(0)
; template <class Epi, class Sched, bool ALIGN_EPI = false, bool SP2 = false>
; __device__ __forceinline__ void gemm_phase(PG8_LAS unsigned char* lds, const Gemm g, const Sched& S, const Epi& E) {
;     ...
;             if constexpr (SP2) {
;             PG8_LDB(B0, 0, 0); PG8_LDB(B1, 0, 1); PG8_SCHED; PG8_LDA(At, 0, 0); PG8_STAGE(PG8_SA(1, 1), a1 + hstep, voffA);
;             PG8_WAIT_V(8); PG8_WAIT_L(0); PG8_BAR; PG8_MMA(0, 0, At, B0); PG8_MMA(0, 1, At, B1); PG8_BAR; PG8_SCHED;
;             PG8_LDA(At, 0, 1); PG8_STAGE(PG8_SB(0, 0), b2, voffB); PG8_STAGE(PG8_SB(0, 1), b2 + hstep, voffB); PG8_STAGE(PG8_SA(0, 0), a2, voffA);
;             PG8_WAIT_V(8); PG8_WAIT_L(0); PG8_BAR; PG8_MMA(1, 0, At, B0); PG8_MMA(1, 1, At, B1); PG8_BAR; PG8_SCHED;
.LBB0_2528:
	ds_read_b128 v[130:133], v147
	ds_read_b128 v[134:137], v147 offset:1024
	ds_read_b128 v[156:159], v147 offset:2048
	ds_read_b128 v[164:167], v147 offset:3072
	ds_read_b128 v[168:171], v162
	ds_read_b128 v[172:175], v162 offset:1024
	ds_read_b128 v[176:179], v162 offset:2048
	ds_read_b128 v[180:183], v162 offset:3072
	s_add_u32 s24, s22, 0xfffc0080
	s_addc_u32 s25, s23, -1
	s_cmp_eq_u32 s44, 12
	s_cselect_b32 s27, s15, s25
	s_cselect_b32 s26, s40, s24
	s_cselect_b32 s25, s13, s43
	s_cselect_b32 s24, s41, s42
	v_lshl_add_u64 v[160:161], s[22:23], 0, v[148:149]
	s_add_i32 m0, s21, 0xc000
	ds_read_b128 v[184:187], v163
	ds_read_b128 v[188:191], v163 offset:1024
	ds_read_b128 v[192:195], v163 offset:2048
	ds_read_b128 v[196:199], v163 offset:3072
	ds_read_b128 v[200:203], v163 offset:4096
	ds_read_b128 v[204:207], v163 offset:5120
	ds_read_b128 v[208:211], v163 offset:6144
	ds_read_b128 v[212:215], v163 offset:7168
	global_load_lds_dwordx4 v[160:161], off
	v_lshl_add_u64 v[160:161], s[22:23], 0, v[150:151]
	s_add_i32 m0, s21, 0xe000
	s_nop 0
	global_load_lds_dwordx4 v[160:161], off
	s_waitcnt vmcnt(8)
	s_waitcnt lgkmcnt(0)
	s_barrier
	s_setprio 1
	s_waitcnt lgkmcnt(0)
	v_mfma_f32_16x16x32_bf16 v[126:129], v[130:133], v[184:187], v[126:129]
	v_mfma_f32_16x16x32_bf16 v[122:125], v[156:159], v[184:187], v[122:125]
	v_mfma_f32_16x16x32_bf16 v[118:121], v[130:133], v[192:195], v[118:121]
	v_mfma_f32_16x16x32_bf16 v[114:117], v[156:159], v[192:195], v[114:117]
	v_mfma_f32_16x16x32_bf16 v[94:97], v[130:133], v[200:203], v[94:97]
	v_mfma_f32_16x16x32_bf16 v[90:93], v[156:159], v[200:203], v[90:93]
	v_mfma_f32_16x16x32_bf16 v[82:85], v[130:133], v[208:211], v[82:85]
	v_mfma_f32_16x16x32_bf16 v[74:77], v[156:159], v[208:211], v[74:77]
	v_mfma_f32_16x16x32_bf16 v[126:129], v[134:137], v[188:191], v[126:129]
	v_mfma_f32_16x16x32_bf16 v[122:125], v[164:167], v[188:191], v[122:125]
	v_mfma_f32_16x16x32_bf16 v[118:121], v[134:137], v[196:199], v[118:121]
	v_mfma_f32_16x16x32_bf16 v[114:117], v[164:167], v[196:199], v[114:117]
	v_mfma_f32_16x16x32_bf16 v[94:97], v[134:137], v[204:207], v[94:97]
	v_mfma_f32_16x16x32_bf16 v[90:93], v[164:167], v[204:207], v[90:93]
	v_mfma_f32_16x16x32_bf16 v[82:85], v[134:137], v[212:215], v[82:85]
	v_mfma_f32_16x16x32_bf16 v[74:77], v[164:167], v[212:215], v[74:77]
	s_setprio 0
	s_setprio 1
	v_mfma_f32_16x16x32_bf16 v[110:113], v[168:171], v[184:187], v[110:113]
	v_mfma_f32_16x16x32_bf16 v[106:109], v[176:179], v[184:187], v[106:109]
	v_mfma_f32_16x16x32_bf16 v[102:105], v[168:171], v[192:195], v[102:105]
	v_mfma_f32_16x16x32_bf16 v[98:101], v[176:179], v[192:195], v[98:101]
	v_mfma_f32_16x16x32_bf16 v[86:89], v[168:171], v[200:203], v[86:89]
	v_mfma_f32_16x16x32_bf16 v[78:81], v[176:179], v[200:203], v[78:81]
	v_mfma_f32_16x16x32_bf16 v[70:73], v[168:171], v[208:211], v[70:73]
	v_mfma_f32_16x16x32_bf16 v[66:69], v[176:179], v[208:211], v[66:69]
	v_mfma_f32_16x16x32_bf16 v[110:113], v[172:175], v[188:191], v[110:113]
	v_mfma_f32_16x16x32_bf16 v[106:109], v[180:183], v[188:191], v[106:109]
	v_mfma_f32_16x16x32_bf16 v[102:105], v[172:175], v[196:199], v[102:105]
	v_mfma_f32_16x16x32_bf16 v[98:101], v[180:183], v[196:199], v[98:101]
	v_mfma_f32_16x16x32_bf16 v[86:89], v[172:175], v[204:207], v[86:89]
	v_mfma_f32_16x16x32_bf16 v[78:81], v[180:183], v[204:207], v[78:81]
	v_mfma_f32_16x16x32_bf16 v[70:73], v[172:175], v[212:215], v[70:73]
	v_mfma_f32_16x16x32_bf16 v[66:69], v[180:183], v[212:215], v[66:69]
	s_setprio 0
	s_barrier
	s_add_i32 s45, s37, s28
	v_lshl_add_u64 v[160:161], s[24:25], 0, v[140:141]
	s_mov_b32 m0, s45
	ds_read_b128 v[184:187], v163 offset:16384
	ds_read_b128 v[188:191], v163 offset:17408
	ds_read_b128 v[192:195], v163 offset:18432
	ds_read_b128 v[196:199], v163 offset:19456
	ds_read_b128 v[200:203], v163 offset:20480
	ds_read_b128 v[204:207], v163 offset:21504
	ds_read_b128 v[208:211], v163 offset:22528
	ds_read_b128 v[212:215], v163 offset:23552
	global_load_lds_dwordx4 v[160:161], off
	s_add_i32 m0, s45, 0x2000
	s_add_u32 s46, s24, 0x40000
	v_lshl_add_u64 v[216:217], s[24:25], 0, v[144:145]
	s_addc_u32 s47, s25, 0
	s_add_i32 s45, s38, s28
	global_load_lds_dwordx4 v[216:217], off
	v_lshl_add_u64 v[218:219], s[46:47], 0, v[140:141]
	s_mov_b32 m0, s45
	v_lshl_add_u64 v[220:221], s[26:27], 0, v[142:143]
	global_load_lds_dwordx4 v[218:219], off
	v_lshl_add_u64 v[218:219], s[46:47], 0, v[144:145]
	s_add_i32 m0, s45, 0x2000
	s_nop 0
	global_load_lds_dwordx4 v[218:219], off
	v_lshl_add_u64 v[218:219], s[26:27], 0, v[138:139]
	s_mov_b32 m0, s21
	s_nop 0
	global_load_lds_dwordx4 v[218:219], off
	s_mov_b32 m0, s29
	s_nop 0
	global_load_lds_dwordx4 v[220:221], off
	s_waitcnt vmcnt(8)
	s_waitcnt lgkmcnt(0)
	s_barrier
; #define PG8_STAGE(bufoff, gbase, voff) do { _Pragma("unroll") for (int _i = 0; _i < 2; ++_i) \
;         __builtin_amdgcn_global_load_lds((const unsigned*)((const char*)(gbase) + (voff)[_i]), (PG8_LAS unsigned*)(lds + (bufoff) + ldsw + _i * 8192), 16, 0, 0); } while (0)
; #define PG8_LDA(dst, b, h) do { _Pragma("unroll") for (int m = 0; m < 4; ++m) _Pragma("unroll") for (int k = 0; k < 2; ++k) dst[m][k] = *(const PG8_LAS bf16x8*)(lds + PG8_SA(b, h) + aoff + m * 2048 + k * 1024); } while (0)
; #define PG8_LDB(dst, b, h) do { _Pragma("unroll") for (int n = 0; n < 2; ++n) _Pragma("unroll") for (int k = 0; k < 2; ++k) dst[n][k] = *(const PG8_LAS bf16x8*)(lds + PG8_SB(b, h) + boff + n * 2048 + k * 1024); } while (0)
; #define PG8_MMA(ai, bj, At, Bt) do { __builtin_amdgcn_s_setprio(1); _Pragma("unroll") for (int m = 0; m < 4; ++m) _Pragma("unroll") for (int n = 0; n < 2; ++n) _Pragma("unroll") for (int k = 0; k < 2; ++k) \
;         acc[ai][bj][m][n] = __builtin_amdgcn_mfma_f32_16x16x32_bf16(Bt[n][k], At[m][k], acc[ai][bj][m][n], 0, 0, 0); __builtin_amdgcn_s_setprio(0); } while (0)
; #define PG8_WAIT_V(n) asm volatile("s_waitcnt vmcnt(" #n ")" ::: "memory")
; #define PG8_WAIT_L(n) asm volatile("s_waitcnt lgkmcnt(" #n ")" ::: "memory")
; #define PG8_BAR __builtin_amdgcn_s_barrier()
; #define PG8_SCHED __builtin_amdgcn_sched_barrier(0)
; template <class Epi, class Sched, bool ALIGN_EPI = false, bool SP2 = false>
; __device__ __forceinline__ void gemm_phase(PG8_LAS unsigned char* lds, const Gemm g, const Sched& S, const Epi& E) {
;     ...
;             PG8_WAIT_V(8); PG8_WAIT_L(0); PG8_BAR; PG8_MMA(1, 0, At, B0); PG8_MMA(1, 1, At, B1); PG8_BAR; PG8_SCHED;
;             PG8_LDB(B0, 1, 0); PG8_LDB(B1, 1, 1); PG8_SCHED; PG8_LDA(At, 1, 0); PG8_STAGE(PG8_SA(0, 1), a2 + hstep, voffA);
;             PG8_WAIT_V(8); PG8_WAIT_L(0); PG8_BAR; PG8_MMA(0, 0, At, B0); PG8_MMA(0, 1, At, B1); PG8_BAR; PG8_SCHED;
	s_setprio 1
	s_waitcnt lgkmcnt(0)
	v_mfma_f32_16x16x32_bf16 v[62:65], v[130:133], v[184:187], v[62:65]
	v_mfma_f32_16x16x32_bf16 v[58:61], v[156:159], v[184:187], v[58:61]
	v_mfma_f32_16x16x32_bf16 v[46:49], v[130:133], v[192:195], v[46:49]
	v_mfma_f32_16x16x32_bf16 v[42:45], v[156:159], v[192:195], v[42:45]
	v_mfma_f32_16x16x32_bf16 v[38:41], v[130:133], v[200:203], v[38:41]
	v_mfma_f32_16x16x32_bf16 v[30:33], v[156:159], v[200:203], v[30:33]
	v_mfma_f32_16x16x32_bf16 v[22:25], v[130:133], v[208:211], v[22:25]
	v_mfma_f32_16x16x32_bf16 v[14:17], v[156:159], v[208:211], v[14:17]
	v_mfma_f32_16x16x32_bf16 v[62:65], v[134:137], v[188:191], v[62:65]
	v_mfma_f32_16x16x32_bf16 v[58:61], v[164:167], v[188:191], v[58:61]
	v_mfma_f32_16x16x32_bf16 v[46:49], v[134:137], v[196:199], v[46:49]
	v_mfma_f32_16x16x32_bf16 v[42:45], v[164:167], v[196:199], v[42:45]
	v_mfma_f32_16x16x32_bf16 v[38:41], v[134:137], v[204:207], v[38:41]
	v_mfma_f32_16x16x32_bf16 v[30:33], v[164:167], v[204:207], v[30:33]
	v_mfma_f32_16x16x32_bf16 v[22:25], v[134:137], v[212:215], v[22:25]
	v_mfma_f32_16x16x32_bf16 v[14:17], v[164:167], v[212:215], v[14:17]
	s_setprio 0
	s_setprio 1
	v_mfma_f32_16x16x32_bf16 v[54:57], v[168:171], v[184:187], v[54:57]
	v_mfma_f32_16x16x32_bf16 v[50:53], v[176:179], v[184:187], v[50:53]
	v_mfma_f32_16x16x32_bf16 v[34:37], v[168:171], v[192:195], v[34:37]
	v_mfma_f32_16x16x32_bf16 v[26:29], v[176:179], v[192:195], v[26:29]
	v_mfma_f32_16x16x32_bf16 v[18:21], v[168:171], v[200:203], v[18:21]
	v_mfma_f32_16x16x32_bf16 v[10:13], v[176:179], v[200:203], v[10:13]
	v_mfma_f32_16x16x32_bf16 v[6:9], v[168:171], v[208:211], v[6:9]
	v_mfma_f32_16x16x32_bf16 v[2:5], v[176:179], v[208:211], v[2:5]
	v_mfma_f32_16x16x32_bf16 v[54:57], v[172:175], v[188:191], v[54:57]
	v_mfma_f32_16x16x32_bf16 v[50:53], v[180:183], v[188:191], v[50:53]
	v_mfma_f32_16x16x32_bf16 v[34:37], v[172:175], v[196:199], v[34:37]
	v_mfma_f32_16x16x32_bf16 v[26:29], v[180:183], v[196:199], v[26:29]
	v_mfma_f32_16x16x32_bf16 v[18:21], v[172:175], v[204:207], v[18:21]
	v_mfma_f32_16x16x32_bf16 v[10:13], v[180:183], v[204:207], v[10:13]
	v_mfma_f32_16x16x32_bf16 v[6:9], v[172:175], v[212:215], v[6:9]
	v_mfma_f32_16x16x32_bf16 v[2:5], v[180:183], v[212:215], v[2:5]
	s_setprio 0
	s_barrier
	s_add_i32 s45, 0, 0x18000
	s_add_i32 s46, 0, 0x1c000
	v_add_u32_e32 v164, s45, v1
	v_add_u32_e32 v180, s46, v1
	ds_read_b128 v[130:133], v164
	ds_read_b128 v[134:137], v164 offset:1024
	ds_read_b128 v[156:159], v164 offset:2048
	ds_read_b128 v[164:167], v164 offset:3072
	ds_read_b128 v[168:171], v180
	ds_read_b128 v[172:175], v180 offset:1024
	ds_read_b128 v[176:179], v180 offset:2048
	ds_read_b128 v[180:183], v180 offset:3072
	s_add_u32 s26, s26, 0x40000
	s_addc_u32 s27, s27, 0
	s_mov_b32 m0, s30
	v_lshl_add_u64 v[222:223], s[26:27], 0, v[138:139]
	ds_read_b128 v[184:187], v163 offset:32768
	ds_read_b128 v[188:191], v163 offset:33792
	ds_read_b128 v[192:195], v163 offset:34816
	ds_read_b128 v[196:199], v163 offset:35840
	ds_read_b128 v[200:203], v163 offset:36864
	ds_read_b128 v[204:207], v163 offset:37888
	ds_read_b128 v[208:211], v163 offset:38912
	ds_read_b128 v[212:215], v163 offset:39936
	global_load_lds_dwordx4 v[222:223], off
	v_lshl_add_u64 v[222:223], s[26:27], 0, v[142:143]
	s_mov_b32 m0, s31
	s_nop 0
	global_load_lds_dwordx4 v[222:223], off
	s_waitcnt vmcnt(8)
	s_waitcnt lgkmcnt(0)
	s_barrier
	s_setprio 1
	s_waitcnt lgkmcnt(0)
	v_mfma_f32_16x16x32_bf16 v[126:129], v[130:133], v[184:187], v[126:129]
	v_mfma_f32_16x16x32_bf16 v[122:125], v[156:159], v[184:187], v[122:125]
	v_mfma_f32_16x16x32_bf16 v[118:121], v[130:133], v[192:195], v[118:121]
	v_mfma_f32_16x16x32_bf16 v[114:117], v[156:159], v[192:195], v[114:117]
	v_mfma_f32_16x16x32_bf16 v[94:97], v[130:133], v[200:203], v[94:97]
	v_mfma_f32_16x16x32_bf16 v[90:93], v[156:159], v[200:203], v[90:93]
	v_mfma_f32_16x16x32_bf16 v[82:85], v[130:133], v[208:211], v[82:85]
	v_mfma_f32_16x16x32_bf16 v[74:77], v[156:159], v[208:211], v[74:77]
	v_mfma_f32_16x16x32_bf16 v[126:129], v[134:137], v[188:191], v[126:129]
	v_mfma_f32_16x16x32_bf16 v[122:125], v[164:167], v[188:191], v[122:125]
	v_mfma_f32_16x16x32_bf16 v[118:121], v[134:137], v[196:199], v[118:121]
	v_mfma_f32_16x16x32_bf16 v[114:117], v[164:167], v[196:199], v[114:117]
	v_mfma_f32_16x16x32_bf16 v[94:97], v[134:137], v[204:207], v[94:97]
	v_mfma_f32_16x16x32_bf16 v[90:93], v[164:167], v[204:207], v[90:93]
	v_mfma_f32_16x16x32_bf16 v[82:85], v[134:137], v[212:215], v[82:85]
	v_mfma_f32_16x16x32_bf16 v[74:77], v[164:167], v[212:215], v[74:77]
	s_setprio 0
	s_setprio 1
	v_mfma_f32_16x16x32_bf16 v[110:113], v[168:171], v[184:187], v[110:113]
	v_mfma_f32_16x16x32_bf16 v[106:109], v[176:179], v[184:187], v[106:109]
	v_mfma_f32_16x16x32_bf16 v[102:105], v[168:171], v[192:195], v[102:105]
	v_mfma_f32_16x16x32_bf16 v[98:101], v[176:179], v[192:195], v[98:101]
	v_mfma_f32_16x16x32_bf16 v[86:89], v[168:171], v[200:203], v[86:89]
	v_mfma_f32_16x16x32_bf16 v[78:81], v[176:179], v[200:203], v[78:81]
	v_mfma_f32_16x16x32_bf16 v[70:73], v[168:171], v[208:211], v[70:73]
	v_mfma_f32_16x16x32_bf16 v[66:69], v[176:179], v[208:211], v[66:69]
	v_mfma_f32_16x16x32_bf16 v[110:113], v[172:175], v[188:191], v[110:113]
	v_mfma_f32_16x16x32_bf16 v[106:109], v[180:183], v[188:191], v[106:109]
	v_mfma_f32_16x16x32_bf16 v[102:105], v[172:175], v[196:199], v[102:105]
	v_mfma_f32_16x16x32_bf16 v[98:101], v[180:183], v[196:199], v[98:101]
	v_mfma_f32_16x16x32_bf16 v[86:89], v[172:175], v[204:207], v[86:89]
	v_mfma_f32_16x16x32_bf16 v[78:81], v[180:183], v[204:207], v[78:81]
	v_mfma_f32_16x16x32_bf16 v[70:73], v[172:175], v[212:215], v[70:73]
	v_mfma_f32_16x16x32_bf16 v[66:69], v[180:183], v[212:215], v[66:69]
	s_setprio 0
	s_barrier
; #define PG8_STAGE(bufoff, gbase, voff) do { _Pragma("unroll") for (int _i = 0; _i < 2; ++_i) \
;         __builtin_amdgcn_global_load_lds((const unsigned*)((const char*)(gbase) + (voff)[_i]), (PG8_LAS unsigned*)(lds + (bufoff) + ldsw + _i * 8192), 16, 0, 0); } while (0)
; #define PG8_LDA(dst, b, h) do { _Pragma("unroll") for (int m = 0; m < 4; ++m) _Pragma("unroll") for (int k = 0; k < 2; ++k) dst[m][k] = *(const PG8_LAS bf16x8*)(lds + PG8_SA(b, h) + aoff + m * 2048 + k * 1024); } while (0)
; #define PG8_MMA(ai, bj, At, Bt) do { __builtin_amdgcn_s_setprio(1); _Pragma("unroll") for (int m = 0; m < 4; ++m) _Pragma("unroll") for (int n = 0; n < 2; ++n) _Pragma("unroll") for (int k = 0; k < 2; ++k) \
;         acc[ai][bj][m][n] = __builtin_amdgcn_mfma_f32_16x16x32_bf16(Bt[n][k], At[m][k], acc[ai][bj][m][n], 0, 0, 0); __builtin_amdgcn_s_setprio(0); } while (0)
; #define PG8_WAIT_V(n) asm volatile("s_waitcnt vmcnt(" #n ")" ::: "memory")
; #define PG8_WAIT_L(n) asm volatile("s_waitcnt lgkmcnt(" #n ")" ::: "memory")
; #define PG8_BAR __builtin_amdgcn_s_barrier()
; #define PG8_SCHED __builtin_amdgcn_sched_barrier(0)
; template <class Epi, class Sched, bool ALIGN_EPI = false, bool SP2 = false>
; __device__ __forceinline__ void gemm_phase(PG8_LAS unsigned char* lds, const Gemm g, const Sched& S, const Epi& E) {
;     ...
;         for (int t = 0; t < nt; t += 2) {
;             const bool last = (t == nt - 2);
;             const char* a1 = cA + (size_t)(t + 1) * kstep;
;             const char* a2 = last ? nA : cA + (size_t)(t + 2) * kstep; const char* b2 = last ? nB : cB + (size_t)(t + 2) * kstep;
;             const char* a3 = a2 + kstep; const char* b3 = b2 + kstep;
;     ...
;             PG8_LDA(At, 1, 1); PG8_STAGE(PG8_SB(1, 0), b3, voffB); PG8_STAGE(PG8_SB(1, 1), b3 + hstep, voffB); PG8_STAGE(PG8_SA(1, 0), a3, voffA);
;             PG8_WAIT_V(8); PG8_WAIT_L(0); PG8_BAR; PG8_MMA(1, 0, At, B0); PG8_MMA(1, 1, At, B1); PG8_BAR; PG8_SCHED;
	s_add_i32 s26, s45, s28
	v_lshl_add_u64 v[160:161], v[160:161], 0, s[8:9]
	s_mov_b32 m0, s26
	ds_read_b128 v[184:187], v163 offset:49152
	ds_read_b128 v[188:191], v163 offset:50176
	ds_read_b128 v[192:195], v163 offset:51200
	ds_read_b128 v[196:199], v163 offset:52224
	ds_read_b128 v[200:203], v163 offset:53248
	ds_read_b128 v[204:207], v163 offset:54272
	ds_read_b128 v[208:211], v163 offset:55296
	ds_read_b128 v[212:215], v163 offset:56320
	global_load_lds_dwordx4 v[160:161], off
	s_add_i32 m0, s26, 0x2000
	s_add_u32 s24, s24, 0x40080
	v_lshl_add_u64 v[160:161], v[216:217], 0, s[8:9]
	s_addc_u32 s25, s25, 0
	s_add_i32 s26, s46, s28
	global_load_lds_dwordx4 v[160:161], off
	v_lshl_add_u64 v[160:161], s[24:25], 0, v[140:141]
	s_mov_b32 m0, s26
	s_nop 0
	global_load_lds_dwordx4 v[160:161], off
	v_lshl_add_u64 v[160:161], s[24:25], 0, v[144:145]
	s_add_i32 m0, s26, 0x2000
	s_nop 0
	global_load_lds_dwordx4 v[160:161], off
	v_lshl_add_u64 v[160:161], v[218:219], 0, s[8:9]
	s_mov_b32 m0, s34
	s_nop 0
	global_load_lds_dwordx4 v[160:161], off
	v_lshl_add_u64 v[160:161], v[220:221], 0, s[8:9]
	s_mov_b32 m0, s35
	s_nop 0
	global_load_lds_dwordx4 v[160:161], off
	s_waitcnt vmcnt(8)
	s_waitcnt lgkmcnt(0)
	s_barrier
	s_setprio 1
	s_waitcnt lgkmcnt(0)
	v_mfma_f32_16x16x32_bf16 v[62:65], v[130:133], v[184:187], v[62:65]
	v_mfma_f32_16x16x32_bf16 v[58:61], v[156:159], v[184:187], v[58:61]
	v_mfma_f32_16x16x32_bf16 v[46:49], v[130:133], v[192:195], v[46:49]
	v_mfma_f32_16x16x32_bf16 v[42:45], v[156:159], v[192:195], v[42:45]
	v_mfma_f32_16x16x32_bf16 v[38:41], v[130:133], v[200:203], v[38:41]
	v_mfma_f32_16x16x32_bf16 v[30:33], v[156:159], v[200:203], v[30:33]
	v_mfma_f32_16x16x32_bf16 v[22:25], v[130:133], v[208:211], v[22:25]
	v_mfma_f32_16x16x32_bf16 v[14:17], v[156:159], v[208:211], v[14:17]
	v_mfma_f32_16x16x32_bf16 v[62:65], v[134:137], v[188:191], v[62:65]
	v_mfma_f32_16x16x32_bf16 v[58:61], v[164:167], v[188:191], v[58:61]
	v_mfma_f32_16x16x32_bf16 v[46:49], v[134:137], v[196:199], v[46:49]
	v_mfma_f32_16x16x32_bf16 v[42:45], v[164:167], v[196:199], v[42:45]
	v_mfma_f32_16x16x32_bf16 v[38:41], v[134:137], v[204:207], v[38:41]
	v_mfma_f32_16x16x32_bf16 v[30:33], v[164:167], v[204:207], v[30:33]
	v_mfma_f32_16x16x32_bf16 v[22:25], v[134:137], v[212:215], v[22:25]
	v_mfma_f32_16x16x32_bf16 v[14:17], v[164:167], v[212:215], v[14:17]
	s_setprio 0
	s_setprio 1
	v_mfma_f32_16x16x32_bf16 v[54:57], v[168:171], v[184:187], v[54:57]
	v_mfma_f32_16x16x32_bf16 v[50:53], v[176:179], v[184:187], v[50:53]
	v_mfma_f32_16x16x32_bf16 v[34:37], v[168:171], v[192:195], v[34:37]
	v_mfma_f32_16x16x32_bf16 v[26:29], v[176:179], v[192:195], v[26:29]
	v_mfma_f32_16x16x32_bf16 v[18:21], v[168:171], v[200:203], v[18:21]
	v_mfma_f32_16x16x32_bf16 v[10:13], v[176:179], v[200:203], v[10:13]
	v_mfma_f32_16x16x32_bf16 v[6:9], v[168:171], v[208:211], v[6:9]
	v_mfma_f32_16x16x32_bf16 v[2:5], v[176:179], v[208:211], v[2:5]
	v_mfma_f32_16x16x32_bf16 v[54:57], v[172:175], v[188:191], v[54:57]
	v_mfma_f32_16x16x32_bf16 v[50:53], v[180:183], v[188:191], v[50:53]
	v_mfma_f32_16x16x32_bf16 v[34:37], v[172:175], v[196:199], v[34:37]
	v_mfma_f32_16x16x32_bf16 v[26:29], v[180:183], v[196:199], v[26:29]
	v_mfma_f32_16x16x32_bf16 v[18:21], v[172:175], v[204:207], v[18:21]
	v_mfma_f32_16x16x32_bf16 v[10:13], v[180:183], v[204:207], v[10:13]
	v_mfma_f32_16x16x32_bf16 v[6:9], v[172:175], v[212:215], v[6:9]
	v_mfma_f32_16x16x32_bf16 v[2:5], v[180:183], v[212:215], v[2:5]
	s_setprio 0
	s_add_i32 s44, s44, 2
	s_add_u32 s22, s22, 0x100
	s_addc_u32 s23, s23, 0
	s_add_u32 s42, s42, 0x100
	s_addc_u32 s43, s43, 0
	s_cmp_gt_u32 s44, 13
	s_barrier
	s_cbranch_scc0 .LBB0_2528
	s_and_b64 vcc, exec, s[10:11]
	s_cbranch_vccz .LBB0_2531
	s_barrier

; #define PG8_STAGE(bufoff, gbase, voff) do { _Pragma("unroll") for (int _i = 0; _i < 2; ++_i) \
;         __builtin_amdgcn_global_load_lds((const unsigned*)((const char*)(gbase) + (voff)[_i]), (PG8_LAS unsigned*)(lds + (bufoff) + ldsw + _i * 8192), 16, 0, 0); } while (0)
; #define PG8_LDA(dst, b, h) do { _Pragma("unroll") for (int m = 0; m < 4; ++m) _Pragma("unroll") for (int k = 0; k < 2; ++k) dst[m][k] = *(const PG8_LAS bf16x8*)(lds + PG8_SA(b, h) + aoff + m * 2048 + k * 1024); } while (0)
; #define PG8_LDB(dst, b, h) do { _Pragma("unroll") for (int n = 0; n < 2; ++n) _Pragma("unroll") for (int k = 0; k < 2; ++k) dst[n][k] = *(const PG8_LAS bf16x8*)(lds + PG8_SB(b, h) + boff + n * 2048 + k * 1024); } while (0)
; #define PG8_MMA(ai, bj, At, Bt) do { __builtin_amdgcn_s_setprio(1); _Pragma("unroll") for (int m = 0; m < 4; ++m) _Pragma("unroll") for (int n = 0; n < 2; ++n) _Pragma("unroll") for (int k = 0; k < 2; ++k) \
;         acc[ai][bj][m][n] = __builtin_amdgcn_mfma_f32_16x16x32_bf16(Bt[n][k], At[m][k], acc[ai][bj][m][n], 0, 0, 0); __builtin_amdgcn_s_setprio(0); } while (0)
; #define PG8_WAIT_V(n) asm volatile("s_waitcnt vmcnt(" #n ")" ::: "memory")
; #define PG8_WAIT_L(n) asm volatile("s_waitcnt lgkmcnt(" #n ")" ::: "memory")
; #define PG8_BAR __builtin_amdgcn_s_barrier()
; #define PG8_SCHED __builtin_amdgcn_sched_barrier(0)
; template <class Epi, class Sched, bool ALIGN_EPI = false, bool SP2 = false>
; __device__ __forceinline__ void gemm_phase(PG8_LAS unsigned char* lds, const Gemm g, const Sched& S, const Epi& E) {
;     ...
;             if constexpr (SP2) {
;             PG8_LDB(B0, 0, 0); PG8_LDB(B1, 0, 1); PG8_SCHED; PG8_LDA(At, 0, 0); PG8_STAGE(PG8_SA(1, 1), a1 + hstep, voffA);
;             PG8_WAIT_V(8); PG8_WAIT_L(0); PG8_BAR; PG8_MMA(0, 0, At, B0); PG8_MMA(0, 1, At, B1); PG8_BAR; PG8_SCHED;
;             PG8_LDA(At, 0, 1); PG8_STAGE(PG8_SB(0, 0), b2, voffB); PG8_STAGE(PG8_SB(0, 1), b2 + hstep, voffB); PG8_STAGE(PG8_SA(0, 0), a2, voffA);
;             PG8_WAIT_V(8); PG8_WAIT_L(0); PG8_BAR; PG8_MMA(1, 0, At, B0); PG8_MMA(1, 1, At, B1); PG8_BAR; PG8_SCHED;
.LBB0_2559:
	ds_read_b128 v[148:151], v156
	ds_read_b128 v[160:163], v156 offset:1024
	ds_read_b128 v[164:167], v156 offset:2048
	ds_read_b128 v[168:171], v156 offset:3072
	ds_read_b128 v[172:175], v157
	ds_read_b128 v[176:179], v157 offset:1024
	ds_read_b128 v[180:183], v157 offset:2048
	ds_read_b128 v[184:187], v157 offset:3072
	s_add_u32 s26, s24, 0xfffc0080
	s_addc_u32 s27, s25, -1
	s_cmp_eq_u32 s44, 12
	s_cselect_b32 s29, s17, s27
	s_cselect_b32 s28, s40, s26
	s_cselect_b32 s27, s15, s43
	s_cselect_b32 s26, s41, s42
	v_lshl_add_u64 v[152:153], s[24:25], 0, v[140:141]
	s_add_i32 m0, s3, 0xc000
	ds_read_b128 v[188:191], v158
	ds_read_b128 v[192:195], v158 offset:1024
	ds_read_b128 v[196:199], v158 offset:2048
	ds_read_b128 v[200:203], v158 offset:3072
	ds_read_b128 v[204:207], v158 offset:4096
	ds_read_b128 v[208:211], v158 offset:5120
	ds_read_b128 v[212:215], v158 offset:6144
	ds_read_b128 v[216:219], v158 offset:7168
	global_load_lds_dwordx4 v[152:153], off
	v_lshl_add_u64 v[152:153], s[24:25], 0, v[142:143]
	s_add_i32 m0, s3, 0xe000
	s_nop 0
	global_load_lds_dwordx4 v[152:153], off
	s_waitcnt vmcnt(8)
	s_waitcnt lgkmcnt(0)
	s_barrier
	s_setprio 1
	s_waitcnt lgkmcnt(0)
	v_mfma_f32_16x16x32_bf16 v[126:129], v[148:151], v[188:191], v[126:129]
	v_mfma_f32_16x16x32_bf16 v[122:125], v[164:167], v[188:191], v[122:125]
	v_mfma_f32_16x16x32_bf16 v[110:113], v[148:151], v[196:199], v[110:113]
	v_mfma_f32_16x16x32_bf16 v[106:109], v[164:167], v[196:199], v[106:109]
	v_mfma_f32_16x16x32_bf16 v[94:97], v[148:151], v[204:207], v[94:97]
	v_mfma_f32_16x16x32_bf16 v[90:93], v[164:167], v[204:207], v[90:93]
	v_mfma_f32_16x16x32_bf16 v[78:81], v[148:151], v[212:215], v[78:81]
	v_mfma_f32_16x16x32_bf16 v[74:77], v[164:167], v[212:215], v[74:77]
	v_mfma_f32_16x16x32_bf16 v[126:129], v[160:163], v[192:195], v[126:129]
	v_mfma_f32_16x16x32_bf16 v[122:125], v[168:171], v[192:195], v[122:125]
	v_mfma_f32_16x16x32_bf16 v[110:113], v[160:163], v[200:203], v[110:113]
	v_mfma_f32_16x16x32_bf16 v[106:109], v[168:171], v[200:203], v[106:109]
	v_mfma_f32_16x16x32_bf16 v[94:97], v[160:163], v[208:211], v[94:97]
	v_mfma_f32_16x16x32_bf16 v[90:93], v[168:171], v[208:211], v[90:93]
	v_mfma_f32_16x16x32_bf16 v[78:81], v[160:163], v[216:219], v[78:81]
	v_mfma_f32_16x16x32_bf16 v[74:77], v[168:171], v[216:219], v[74:77]
	s_setprio 0
	s_setprio 1
	v_mfma_f32_16x16x32_bf16 v[118:121], v[172:175], v[188:191], v[118:121]
	v_mfma_f32_16x16x32_bf16 v[114:117], v[180:183], v[188:191], v[114:117]
	v_mfma_f32_16x16x32_bf16 v[102:105], v[172:175], v[196:199], v[102:105]
	v_mfma_f32_16x16x32_bf16 v[98:101], v[180:183], v[196:199], v[98:101]
	v_mfma_f32_16x16x32_bf16 v[86:89], v[172:175], v[204:207], v[86:89]
	v_mfma_f32_16x16x32_bf16 v[82:85], v[180:183], v[204:207], v[82:85]
	v_mfma_f32_16x16x32_bf16 v[70:73], v[172:175], v[212:215], v[70:73]
	v_mfma_f32_16x16x32_bf16 v[66:69], v[180:183], v[212:215], v[66:69]
	v_mfma_f32_16x16x32_bf16 v[118:121], v[176:179], v[192:195], v[118:121]
	v_mfma_f32_16x16x32_bf16 v[114:117], v[184:187], v[192:195], v[114:117]
	v_mfma_f32_16x16x32_bf16 v[102:105], v[176:179], v[200:203], v[102:105]
	v_mfma_f32_16x16x32_bf16 v[98:101], v[184:187], v[200:203], v[98:101]
	v_mfma_f32_16x16x32_bf16 v[86:89], v[176:179], v[208:211], v[86:89]
	v_mfma_f32_16x16x32_bf16 v[82:85], v[184:187], v[208:211], v[82:85]
	v_mfma_f32_16x16x32_bf16 v[70:73], v[176:179], v[216:219], v[70:73]
	v_mfma_f32_16x16x32_bf16 v[66:69], v[184:187], v[216:219], v[66:69]
	s_setprio 0
	s_barrier
	s_add_i32 s45, s38, s2
	v_lshl_add_u64 v[152:153], s[26:27], 0, v[132:133]
	s_mov_b32 m0, s45
	ds_read_b128 v[188:191], v158 offset:16384
	ds_read_b128 v[192:195], v158 offset:17408
	ds_read_b128 v[196:199], v158 offset:18432
	ds_read_b128 v[200:203], v158 offset:19456
	ds_read_b128 v[204:207], v158 offset:20480
	ds_read_b128 v[208:211], v158 offset:21504
	ds_read_b128 v[212:215], v158 offset:22528
	ds_read_b128 v[216:219], v158 offset:23552
	global_load_lds_dwordx4 v[152:153], off
	s_add_i32 m0, s45, 0x2000
	s_add_u32 s46, s26, 0x40000
	v_lshl_add_u64 v[220:221], s[26:27], 0, v[136:137]
	s_addc_u32 s47, s27, 0
	s_add_i32 s45, s39, s2
	global_load_lds_dwordx4 v[220:221], off
	v_lshl_add_u64 v[222:223], s[46:47], 0, v[132:133]
	s_mov_b32 m0, s45
	v_lshl_add_u64 v[224:225], s[28:29], 0, v[134:135]
	global_load_lds_dwordx4 v[222:223], off
	v_lshl_add_u64 v[222:223], s[46:47], 0, v[136:137]
	s_add_i32 m0, s45, 0x2000
	s_nop 0
	global_load_lds_dwordx4 v[222:223], off
	v_lshl_add_u64 v[222:223], s[28:29], 0, v[130:131]
	s_mov_b32 m0, s3
	s_nop 0
	global_load_lds_dwordx4 v[222:223], off
	s_mov_b32 m0, s30
	s_nop 0
	global_load_lds_dwordx4 v[224:225], off
	s_waitcnt vmcnt(8)
	s_waitcnt lgkmcnt(0)
	s_barrier
; #define PG8_STAGE(bufoff, gbase, voff) do { _Pragma("unroll") for (int _i = 0; _i < 2; ++_i) \
;         __builtin_amdgcn_global_load_lds((const unsigned*)((const char*)(gbase) + (voff)[_i]), (PG8_LAS unsigned*)(lds + (bufoff) + ldsw + _i * 8192), 16, 0, 0); } while (0)
; #define PG8_LDA(dst, b, h) do { _Pragma("unroll") for (int m = 0; m < 4; ++m) _Pragma("unroll") for (int k = 0; k < 2; ++k) dst[m][k] = *(const PG8_LAS bf16x8*)(lds + PG8_SA(b, h) + aoff + m * 2048 + k * 1024); } while (0)
; #define PG8_LDB(dst, b, h) do { _Pragma("unroll") for (int n = 0; n < 2; ++n) _Pragma("unroll") for (int k = 0; k < 2; ++k) dst[n][k] = *(const PG8_LAS bf16x8*)(lds + PG8_SB(b, h) + boff + n * 2048 + k * 1024); } while (0)
; #define PG8_MMA(ai, bj, At, Bt) do { __builtin_amdgcn_s_setprio(1); _Pragma("unroll") for (int m = 0; m < 4; ++m) _Pragma("unroll") for (int n = 0; n < 2; ++n) _Pragma("unroll") for (int k = 0; k < 2; ++k) \
;         acc[ai][bj][m][n] = __builtin_amdgcn_mfma_f32_16x16x32_bf16(Bt[n][k], At[m][k], acc[ai][bj][m][n], 0, 0, 0); __builtin_amdgcn_s_setprio(0); } while (0)
; #define PG8_WAIT_V(n) asm volatile("s_waitcnt vmcnt(" #n ")" ::: "memory")
; #define PG8_WAIT_L(n) asm volatile("s_waitcnt lgkmcnt(" #n ")" ::: "memory")
; #define PG8_BAR __builtin_amdgcn_s_barrier()
; #define PG8_SCHED __builtin_amdgcn_sched_barrier(0)
; template <class Epi, class Sched, bool ALIGN_EPI = false, bool SP2 = false>
; __device__ __forceinline__ void gemm_phase(PG8_LAS unsigned char* lds, const Gemm g, const Sched& S, const Epi& E) {
;     ...
;             PG8_WAIT_V(8); PG8_WAIT_L(0); PG8_BAR; PG8_MMA(1, 0, At, B0); PG8_MMA(1, 1, At, B1); PG8_BAR; PG8_SCHED;
;             PG8_LDB(B0, 1, 0); PG8_LDB(B1, 1, 1); PG8_SCHED; PG8_LDA(At, 1, 0); PG8_STAGE(PG8_SA(0, 1), a2 + hstep, voffA);
;             PG8_WAIT_V(8); PG8_WAIT_L(0); PG8_BAR; PG8_MMA(0, 0, At, B0); PG8_MMA(0, 1, At, B1); PG8_BAR; PG8_SCHED;
	s_setprio 1
	s_waitcnt lgkmcnt(0)
	v_mfma_f32_16x16x32_bf16 v[62:65], v[148:151], v[188:191], v[62:65]
	v_mfma_f32_16x16x32_bf16 v[58:61], v[164:167], v[188:191], v[58:61]
	v_mfma_f32_16x16x32_bf16 v[46:49], v[148:151], v[196:199], v[46:49]
	v_mfma_f32_16x16x32_bf16 v[42:45], v[164:167], v[196:199], v[42:45]
	v_mfma_f32_16x16x32_bf16 v[30:33], v[148:151], v[204:207], v[30:33]
	v_mfma_f32_16x16x32_bf16 v[26:29], v[164:167], v[204:207], v[26:29]
	v_mfma_f32_16x16x32_bf16 v[14:17], v[148:151], v[212:215], v[14:17]
	v_mfma_f32_16x16x32_bf16 v[10:13], v[164:167], v[212:215], v[10:13]
	v_mfma_f32_16x16x32_bf16 v[62:65], v[160:163], v[192:195], v[62:65]
	v_mfma_f32_16x16x32_bf16 v[58:61], v[168:171], v[192:195], v[58:61]
	v_mfma_f32_16x16x32_bf16 v[46:49], v[160:163], v[200:203], v[46:49]
	v_mfma_f32_16x16x32_bf16 v[42:45], v[168:171], v[200:203], v[42:45]
	v_mfma_f32_16x16x32_bf16 v[30:33], v[160:163], v[208:211], v[30:33]
	v_mfma_f32_16x16x32_bf16 v[26:29], v[168:171], v[208:211], v[26:29]
	v_mfma_f32_16x16x32_bf16 v[14:17], v[160:163], v[216:219], v[14:17]
	v_mfma_f32_16x16x32_bf16 v[10:13], v[168:171], v[216:219], v[10:13]
	s_setprio 0
	s_setprio 1
	v_mfma_f32_16x16x32_bf16 v[54:57], v[172:175], v[188:191], v[54:57]
	v_mfma_f32_16x16x32_bf16 v[50:53], v[180:183], v[188:191], v[50:53]
	v_mfma_f32_16x16x32_bf16 v[38:41], v[172:175], v[196:199], v[38:41]
	v_mfma_f32_16x16x32_bf16 v[34:37], v[180:183], v[196:199], v[34:37]
	v_mfma_f32_16x16x32_bf16 v[22:25], v[172:175], v[204:207], v[22:25]
	v_mfma_f32_16x16x32_bf16 v[18:21], v[180:183], v[204:207], v[18:21]
	v_mfma_f32_16x16x32_bf16 v[6:9], v[172:175], v[212:215], v[6:9]
	v_mfma_f32_16x16x32_bf16 v[2:5], v[180:183], v[212:215], v[2:5]
	v_mfma_f32_16x16x32_bf16 v[54:57], v[176:179], v[192:195], v[54:57]
	v_mfma_f32_16x16x32_bf16 v[50:53], v[184:187], v[192:195], v[50:53]
	v_mfma_f32_16x16x32_bf16 v[38:41], v[176:179], v[200:203], v[38:41]
	v_mfma_f32_16x16x32_bf16 v[34:37], v[184:187], v[200:203], v[34:37]
	v_mfma_f32_16x16x32_bf16 v[22:25], v[176:179], v[208:211], v[22:25]
	v_mfma_f32_16x16x32_bf16 v[18:21], v[184:187], v[208:211], v[18:21]
	v_mfma_f32_16x16x32_bf16 v[6:9], v[176:179], v[216:219], v[6:9]
	v_mfma_f32_16x16x32_bf16 v[2:5], v[184:187], v[216:219], v[2:5]
	s_setprio 0
	s_barrier
	s_add_i32 s45, 0, 0x18000
	v_add_u32_e32 v159, s45, v1
	s_add_i32 s46, 0, 0x1c000
	ds_read_b128 v[148:151], v159
	ds_read_b128 v[160:163], v159 offset:1024
	ds_read_b128 v[164:167], v159 offset:2048
	ds_read_b128 v[168:171], v159 offset:3072
	v_add_u32_e32 v159, s46, v1
	ds_read_b128 v[172:175], v159
	ds_read_b128 v[176:179], v159 offset:1024
	ds_read_b128 v[180:183], v159 offset:2048
	ds_read_b128 v[184:187], v159 offset:3072
	s_add_u32 s28, s28, 0x40000
	s_addc_u32 s29, s29, 0
	s_mov_b32 m0, s31
	v_lshl_add_u64 v[226:227], s[28:29], 0, v[130:131]
	ds_read_b128 v[188:191], v158 offset:32768
	ds_read_b128 v[192:195], v158 offset:33792
	ds_read_b128 v[196:199], v158 offset:34816
	ds_read_b128 v[200:203], v158 offset:35840
	ds_read_b128 v[204:207], v158 offset:36864
	ds_read_b128 v[208:211], v158 offset:37888
	ds_read_b128 v[212:215], v158 offset:38912
	ds_read_b128 v[216:219], v158 offset:39936
	global_load_lds_dwordx4 v[226:227], off
	v_lshl_add_u64 v[226:227], s[28:29], 0, v[134:135]
	s_mov_b32 m0, s33
	s_nop 0
	global_load_lds_dwordx4 v[226:227], off
	s_waitcnt vmcnt(8)
	s_waitcnt lgkmcnt(0)
	s_barrier
	s_setprio 1
	s_waitcnt lgkmcnt(0)
	v_mfma_f32_16x16x32_bf16 v[126:129], v[148:151], v[188:191], v[126:129]
	v_mfma_f32_16x16x32_bf16 v[122:125], v[164:167], v[188:191], v[122:125]
	v_mfma_f32_16x16x32_bf16 v[110:113], v[148:151], v[196:199], v[110:113]
	v_mfma_f32_16x16x32_bf16 v[106:109], v[164:167], v[196:199], v[106:109]
	v_mfma_f32_16x16x32_bf16 v[94:97], v[148:151], v[204:207], v[94:97]
	v_mfma_f32_16x16x32_bf16 v[90:93], v[164:167], v[204:207], v[90:93]
	v_mfma_f32_16x16x32_bf16 v[78:81], v[148:151], v[212:215], v[78:81]
	v_mfma_f32_16x16x32_bf16 v[74:77], v[164:167], v[212:215], v[74:77]
	v_mfma_f32_16x16x32_bf16 v[126:129], v[160:163], v[192:195], v[126:129]
	v_mfma_f32_16x16x32_bf16 v[122:125], v[168:171], v[192:195], v[122:125]
	v_mfma_f32_16x16x32_bf16 v[110:113], v[160:163], v[200:203], v[110:113]
	v_mfma_f32_16x16x32_bf16 v[106:109], v[168:171], v[200:203], v[106:109]
	v_mfma_f32_16x16x32_bf16 v[94:97], v[160:163], v[208:211], v[94:97]
	v_mfma_f32_16x16x32_bf16 v[90:93], v[168:171], v[208:211], v[90:93]
	v_mfma_f32_16x16x32_bf16 v[78:81], v[160:163], v[216:219], v[78:81]
	v_mfma_f32_16x16x32_bf16 v[74:77], v[168:171], v[216:219], v[74:77]
	s_setprio 0
	s_setprio 1
	v_mfma_f32_16x16x32_bf16 v[118:121], v[172:175], v[188:191], v[118:121]
	v_mfma_f32_16x16x32_bf16 v[114:117], v[180:183], v[188:191], v[114:117]
	v_mfma_f32_16x16x32_bf16 v[102:105], v[172:175], v[196:199], v[102:105]
	v_mfma_f32_16x16x32_bf16 v[98:101], v[180:183], v[196:199], v[98:101]
	v_mfma_f32_16x16x32_bf16 v[86:89], v[172:175], v[204:207], v[86:89]
	v_mfma_f32_16x16x32_bf16 v[82:85], v[180:183], v[204:207], v[82:85]
	v_mfma_f32_16x16x32_bf16 v[70:73], v[172:175], v[212:215], v[70:73]
	v_mfma_f32_16x16x32_bf16 v[66:69], v[180:183], v[212:215], v[66:69]
	v_mfma_f32_16x16x32_bf16 v[118:121], v[176:179], v[192:195], v[118:121]
	v_mfma_f32_16x16x32_bf16 v[114:117], v[184:187], v[192:195], v[114:117]
	v_mfma_f32_16x16x32_bf16 v[102:105], v[176:179], v[200:203], v[102:105]
	v_mfma_f32_16x16x32_bf16 v[98:101], v[184:187], v[200:203], v[98:101]
	v_mfma_f32_16x16x32_bf16 v[86:89], v[176:179], v[208:211], v[86:89]
	v_mfma_f32_16x16x32_bf16 v[82:85], v[184:187], v[208:211], v[82:85]
	v_mfma_f32_16x16x32_bf16 v[70:73], v[176:179], v[216:219], v[70:73]
	v_mfma_f32_16x16x32_bf16 v[66:69], v[184:187], v[216:219], v[66:69]
	s_setprio 0
	s_barrier
; #define PG8_STAGE(bufoff, gbase, voff) do { _Pragma("unroll") for (int _i = 0; _i < 2; ++_i) \
;         __builtin_amdgcn_global_load_lds((const unsigned*)((const char*)(gbase) + (voff)[_i]), (PG8_LAS unsigned*)(lds + (bufoff) + ldsw + _i * 8192), 16, 0, 0); } while (0)
; #define PG8_LDA(dst, b, h) do { _Pragma("unroll") for (int m = 0; m < 4; ++m) _Pragma("unroll") for (int k = 0; k < 2; ++k) dst[m][k] = *(const PG8_LAS bf16x8*)(lds + PG8_SA(b, h) + aoff + m * 2048 + k * 1024); } while (0)
; #define PG8_MMA(ai, bj, At, Bt) do { __builtin_amdgcn_s_setprio(1); _Pragma("unroll") for (int m = 0; m < 4; ++m) _Pragma("unroll") for (int n = 0; n < 2; ++n) _Pragma("unroll") for (int k = 0; k < 2; ++k) \
;         acc[ai][bj][m][n] = __builtin_amdgcn_mfma_f32_16x16x32_bf16(Bt[n][k], At[m][k], acc[ai][bj][m][n], 0, 0, 0); __builtin_amdgcn_s_setprio(0); } while (0)
; #define PG8_WAIT_V(n) asm volatile("s_waitcnt vmcnt(" #n ")" ::: "memory")
; #define PG8_WAIT_L(n) asm volatile("s_waitcnt lgkmcnt(" #n ")" ::: "memory")
; #define PG8_BAR __builtin_amdgcn_s_barrier()
; #define PG8_SCHED __builtin_amdgcn_sched_barrier(0)
; template <class Epi, class Sched, bool ALIGN_EPI = false, bool SP2 = false>
; __device__ __forceinline__ void gemm_phase(PG8_LAS unsigned char* lds, const Gemm g, const Sched& S, const Epi& E) {
;     ...
;         for (int t = 0; t < nt; t += 2) {
;             const bool last = (t == nt - 2);
;             const char* a1 = cA + (size_t)(t + 1) * kstep;
;             const char* a2 = last ? nA : cA + (size_t)(t + 2) * kstep; const char* b2 = last ? nB : cB + (size_t)(t + 2) * kstep;
;             const char* a3 = a2 + kstep; const char* b3 = b2 + kstep;
;     ...
;             PG8_LDA(At, 1, 1); PG8_STAGE(PG8_SB(1, 0), b3, voffB); PG8_STAGE(PG8_SB(1, 1), b3 + hstep, voffB); PG8_STAGE(PG8_SA(1, 0), a3, voffA);
;             PG8_WAIT_V(8); PG8_WAIT_L(0); PG8_BAR; PG8_MMA(1, 0, At, B0); PG8_MMA(1, 1, At, B1); PG8_BAR; PG8_SCHED;
	s_add_i32 s28, s45, s2
	v_lshl_add_u64 v[152:153], v[152:153], 0, s[10:11]
	s_mov_b32 m0, s28
	ds_read_b128 v[188:191], v158 offset:49152
	ds_read_b128 v[192:195], v158 offset:50176
	ds_read_b128 v[196:199], v158 offset:51200
	ds_read_b128 v[200:203], v158 offset:52224
	ds_read_b128 v[204:207], v158 offset:53248
	ds_read_b128 v[208:211], v158 offset:54272
	ds_read_b128 v[212:215], v158 offset:55296
	ds_read_b128 v[216:219], v158 offset:56320
	global_load_lds_dwordx4 v[152:153], off
	s_add_i32 m0, s28, 0x2000
	s_add_u32 s26, s26, 0x40080
	v_lshl_add_u64 v[152:153], v[220:221], 0, s[10:11]
	s_addc_u32 s27, s27, 0
	s_add_i32 s28, s46, s2
	global_load_lds_dwordx4 v[152:153], off
	v_lshl_add_u64 v[152:153], s[26:27], 0, v[132:133]
	s_mov_b32 m0, s28
	s_nop 0
	global_load_lds_dwordx4 v[152:153], off
	v_lshl_add_u64 v[152:153], s[26:27], 0, v[136:137]
	s_add_i32 m0, s28, 0x2000
	s_nop 0
	global_load_lds_dwordx4 v[152:153], off
	v_lshl_add_u64 v[152:153], v[222:223], 0, s[10:11]
	s_mov_b32 m0, s35
	s_nop 0
	global_load_lds_dwordx4 v[152:153], off
	v_lshl_add_u64 v[152:153], v[224:225], 0, s[10:11]
	s_mov_b32 m0, s36
	s_nop 0
	global_load_lds_dwordx4 v[152:153], off
	s_waitcnt vmcnt(8)
	s_waitcnt lgkmcnt(0)
	s_barrier
	s_setprio 1
	s_waitcnt lgkmcnt(0)
	v_mfma_f32_16x16x32_bf16 v[62:65], v[148:151], v[188:191], v[62:65]
	v_mfma_f32_16x16x32_bf16 v[58:61], v[164:167], v[188:191], v[58:61]
	v_mfma_f32_16x16x32_bf16 v[46:49], v[148:151], v[196:199], v[46:49]
	v_mfma_f32_16x16x32_bf16 v[42:45], v[164:167], v[196:199], v[42:45]
	v_mfma_f32_16x16x32_bf16 v[30:33], v[148:151], v[204:207], v[30:33]
	v_mfma_f32_16x16x32_bf16 v[26:29], v[164:167], v[204:207], v[26:29]
	v_mfma_f32_16x16x32_bf16 v[14:17], v[148:151], v[212:215], v[14:17]
	v_mfma_f32_16x16x32_bf16 v[10:13], v[164:167], v[212:215], v[10:13]
	v_mfma_f32_16x16x32_bf16 v[62:65], v[160:163], v[192:195], v[62:65]
	v_mfma_f32_16x16x32_bf16 v[58:61], v[168:171], v[192:195], v[58:61]
	v_mfma_f32_16x16x32_bf16 v[46:49], v[160:163], v[200:203], v[46:49]
	v_mfma_f32_16x16x32_bf16 v[42:45], v[168:171], v[200:203], v[42:45]
	v_mfma_f32_16x16x32_bf16 v[30:33], v[160:163], v[208:211], v[30:33]
	v_mfma_f32_16x16x32_bf16 v[26:29], v[168:171], v[208:211], v[26:29]
	v_mfma_f32_16x16x32_bf16 v[14:17], v[160:163], v[216:219], v[14:17]
	v_mfma_f32_16x16x32_bf16 v[10:13], v[168:171], v[216:219], v[10:13]
	s_setprio 0
	s_setprio 1
	v_mfma_f32_16x16x32_bf16 v[54:57], v[172:175], v[188:191], v[54:57]
	v_mfma_f32_16x16x32_bf16 v[50:53], v[180:183], v[188:191], v[50:53]
	v_mfma_f32_16x16x32_bf16 v[38:41], v[172:175], v[196:199], v[38:41]
	v_mfma_f32_16x16x32_bf16 v[34:37], v[180:183], v[196:199], v[34:37]
	v_mfma_f32_16x16x32_bf16 v[22:25], v[172:175], v[204:207], v[22:25]
	v_mfma_f32_16x16x32_bf16 v[18:21], v[180:183], v[204:207], v[18:21]
	v_mfma_f32_16x16x32_bf16 v[6:9], v[172:175], v[212:215], v[6:9]
	v_mfma_f32_16x16x32_bf16 v[2:5], v[180:183], v[212:215], v[2:5]
	v_mfma_f32_16x16x32_bf16 v[54:57], v[176:179], v[192:195], v[54:57]
	v_mfma_f32_16x16x32_bf16 v[50:53], v[184:187], v[192:195], v[50:53]
	v_mfma_f32_16x16x32_bf16 v[38:41], v[176:179], v[200:203], v[38:41]
	v_mfma_f32_16x16x32_bf16 v[34:37], v[184:187], v[200:203], v[34:37]
	v_mfma_f32_16x16x32_bf16 v[22:25], v[176:179], v[208:211], v[22:25]
	v_mfma_f32_16x16x32_bf16 v[18:21], v[184:187], v[208:211], v[18:21]
	v_mfma_f32_16x16x32_bf16 v[6:9], v[176:179], v[216:219], v[6:9]
	v_mfma_f32_16x16x32_bf16 v[2:5], v[184:187], v[216:219], v[2:5]
	s_setprio 0
	s_add_i32 s44, s44, 2
	s_add_u32 s24, s24, 0x100
	s_addc_u32 s25, s25, 0
	s_add_u32 s42, s42, 0x100
	s_addc_u32 s43, s43, 0
	s_cmp_gt_u32 s44, 13
	s_barrier
	s_cbranch_scc0 .LBB0_2559
	s_and_b64 vcc, exec, s[12:13]
	s_cbranch_vccz .LBB0_2562
	s_barrier

; #define PG8_STAGE(bufoff, gbase, voff) do { _Pragma("unroll") for (int _i = 0; _i < 2; ++_i) \
;         __builtin_amdgcn_global_load_lds((const unsigned*)((const char*)(gbase) + (voff)[_i]), (PG8_LAS unsigned*)(lds + (bufoff) + ldsw + _i * 8192), 16, 0, 0); } while (0)
; #define PG8_LDA(dst, b, h) do { _Pragma("unroll") for (int m = 0; m < 4; ++m) _Pragma("unroll") for (int k = 0; k < 2; ++k) dst[m][k] = *(const PG8_LAS bf16x8*)(lds + PG8_SA(b, h) + aoff + m * 2048 + k * 1024); } while (0)
; #define PG8_LDB(dst, b, h) do { _Pragma("unroll") for (int n = 0; n < 2; ++n) _Pragma("unroll") for (int k = 0; k < 2; ++k) dst[n][k] = *(const PG8_LAS bf16x8*)(lds + PG8_SB(b, h) + boff + n * 2048 + k * 1024); } while (0)
; #define PG8_MMA(ai, bj, At, Bt) do { __builtin_amdgcn_s_setprio(1); _Pragma("unroll") for (int m = 0; m < 4; ++m) _Pragma("unroll") for (int n = 0; n < 2; ++n) _Pragma("unroll") for (int k = 0; k < 2; ++k) \
;         acc[ai][bj][m][n] = __builtin_amdgcn_mfma_f32_16x16x32_bf16(Bt[n][k], At[m][k], acc[ai][bj][m][n], 0, 0, 0); __builtin_amdgcn_s_setprio(0); } while (0)
; #define PG8_WAIT_V(n) asm volatile("s_waitcnt vmcnt(" #n ")" ::: "memory")
; #define PG8_WAIT_L(n) asm volatile("s_waitcnt lgkmcnt(" #n ")" ::: "memory")
; #define PG8_BAR __builtin_amdgcn_s_barrier()
; #define PG8_SCHED __builtin_amdgcn_sched_barrier(0)
; template <class Epi, class Sched, bool ALIGN_EPI = false, bool SP2 = false>
; __device__ __forceinline__ void gemm_phase(PG8_LAS unsigned char* lds, const Gemm g, const Sched& S, const Epi& E) {
;     ...
;             if constexpr (SP2) {
;             PG8_LDB(B0, 0, 0); PG8_LDB(B1, 0, 1); PG8_SCHED; PG8_LDA(At, 0, 0); PG8_STAGE(PG8_SA(1, 1), a1 + hstep, voffA);
;             PG8_WAIT_V(8); PG8_WAIT_L(0); PG8_BAR; PG8_MMA(0, 0, At, B0); PG8_MMA(0, 1, At, B1); PG8_BAR; PG8_SCHED;
;             PG8_LDA(At, 0, 1); PG8_STAGE(PG8_SB(0, 0), b2, voffB); PG8_STAGE(PG8_SB(0, 1), b2 + hstep, voffB); PG8_STAGE(PG8_SA(0, 0), a2, voffA);
;             PG8_WAIT_V(8); PG8_WAIT_L(0); PG8_BAR; PG8_MMA(1, 0, At, B0); PG8_MMA(1, 1, At, B1); PG8_BAR; PG8_SCHED;
.LBB0_2642:
	ds_read_b128 v[152:155], v149
	ds_read_b128 v[156:159], v149 offset:1024
	ds_read_b128 v[160:163], v149 offset:2048
	ds_read_b128 v[164:167], v149 offset:3072
	ds_read_b128 v[168:171], v150
	ds_read_b128 v[172:175], v150 offset:1024
	ds_read_b128 v[176:179], v150 offset:2048
	ds_read_b128 v[180:183], v150 offset:3072
	s_add_u32 s30, s28, 0xfff80080
	s_addc_u32 s31, s29, -1
	s_cmp_eq_u32 s51, 28
	s_cselect_b32 s35, s21, s31
	s_cselect_b32 s34, s45, s30
	s_cselect_b32 s31, s19, s50
	s_cselect_b32 s30, s46, s47
	v_lshl_add_u64 v[216:217], s[28:29], 0, v[138:139]
	s_add_i32 m0, s3, 0xc000
	ds_read_b128 v[184:187], v151
	ds_read_b128 v[188:191], v151 offset:1024
	ds_read_b128 v[192:195], v151 offset:2048
	ds_read_b128 v[196:199], v151 offset:3072
	ds_read_b128 v[200:203], v151 offset:4096
	ds_read_b128 v[204:207], v151 offset:5120
	ds_read_b128 v[208:211], v151 offset:6144
	ds_read_b128 v[212:215], v151 offset:7168
	global_load_lds_dwordx4 v[216:217], off
	v_lshl_add_u64 v[216:217], s[28:29], 0, v[140:141]
	s_add_i32 m0, s3, 0xe000
	s_nop 0
	global_load_lds_dwordx4 v[216:217], off
	s_waitcnt vmcnt(8)
	s_waitcnt lgkmcnt(0)
	s_barrier
	s_setprio 1
	s_waitcnt lgkmcnt(0)
	v_mfma_f32_16x16x32_bf16 v[126:129], v[152:155], v[184:187], v[126:129]
	v_mfma_f32_16x16x32_bf16 v[122:125], v[160:163], v[184:187], v[122:125]
	v_mfma_f32_16x16x32_bf16 v[118:121], v[152:155], v[192:195], v[118:121]
	v_mfma_f32_16x16x32_bf16 v[110:113], v[160:163], v[192:195], v[110:113]
	v_mfma_f32_16x16x32_bf16 v[102:105], v[152:155], v[200:203], v[102:105]
	v_mfma_f32_16x16x32_bf16 v[94:97], v[160:163], v[200:203], v[94:97]
	v_mfma_f32_16x16x32_bf16 v[86:89], v[152:155], v[208:211], v[86:89]
	v_mfma_f32_16x16x32_bf16 v[78:81], v[160:163], v[208:211], v[78:81]
	v_mfma_f32_16x16x32_bf16 v[126:129], v[156:159], v[188:191], v[126:129]
	v_mfma_f32_16x16x32_bf16 v[122:125], v[164:167], v[188:191], v[122:125]
	v_mfma_f32_16x16x32_bf16 v[118:121], v[156:159], v[196:199], v[118:121]
	v_mfma_f32_16x16x32_bf16 v[110:113], v[164:167], v[196:199], v[110:113]
	v_mfma_f32_16x16x32_bf16 v[102:105], v[156:159], v[204:207], v[102:105]
	v_mfma_f32_16x16x32_bf16 v[94:97], v[164:167], v[204:207], v[94:97]
	v_mfma_f32_16x16x32_bf16 v[86:89], v[156:159], v[212:215], v[86:89]
	v_mfma_f32_16x16x32_bf16 v[78:81], v[164:167], v[212:215], v[78:81]
	s_setprio 0
	s_setprio 1
	v_mfma_f32_16x16x32_bf16 v[114:117], v[168:171], v[184:187], v[114:117]
	v_mfma_f32_16x16x32_bf16 v[106:109], v[176:179], v[184:187], v[106:109]
	v_mfma_f32_16x16x32_bf16 v[98:101], v[168:171], v[192:195], v[98:101]
	v_mfma_f32_16x16x32_bf16 v[90:93], v[176:179], v[192:195], v[90:93]
	v_mfma_f32_16x16x32_bf16 v[82:85], v[168:171], v[200:203], v[82:85]
	v_mfma_f32_16x16x32_bf16 v[74:77], v[176:179], v[200:203], v[74:77]
	v_mfma_f32_16x16x32_bf16 v[70:73], v[168:171], v[208:211], v[70:73]
	v_mfma_f32_16x16x32_bf16 v[66:69], v[176:179], v[208:211], v[66:69]
	v_mfma_f32_16x16x32_bf16 v[114:117], v[172:175], v[188:191], v[114:117]
	v_mfma_f32_16x16x32_bf16 v[106:109], v[180:183], v[188:191], v[106:109]
	v_mfma_f32_16x16x32_bf16 v[98:101], v[172:175], v[196:199], v[98:101]
	v_mfma_f32_16x16x32_bf16 v[90:93], v[180:183], v[196:199], v[90:93]
	v_mfma_f32_16x16x32_bf16 v[82:85], v[172:175], v[204:207], v[82:85]
	v_mfma_f32_16x16x32_bf16 v[74:77], v[180:183], v[204:207], v[74:77]
	v_mfma_f32_16x16x32_bf16 v[70:73], v[172:175], v[212:215], v[70:73]
	v_mfma_f32_16x16x32_bf16 v[66:69], v[180:183], v[212:215], v[66:69]
	s_setprio 0
	s_barrier
	s_add_i32 s52, s40, s2
	v_lshl_add_u64 v[216:217], s[30:31], 0, v[132:133]
	s_mov_b32 m0, s52
	ds_read_b128 v[184:187], v151 offset:16384
	ds_read_b128 v[188:191], v151 offset:17408
	ds_read_b128 v[192:195], v151 offset:18432
	ds_read_b128 v[196:199], v151 offset:19456
	ds_read_b128 v[200:203], v151 offset:20480
	ds_read_b128 v[204:207], v151 offset:21504
	ds_read_b128 v[208:211], v151 offset:22528
	ds_read_b128 v[212:215], v151 offset:23552
	global_load_lds_dwordx4 v[216:217], off
	s_add_i32 m0, s52, 0x2000
	s_add_u32 s52, s30, 0x80000
	v_lshl_add_u64 v[218:219], s[30:31], 0, v[136:137]
	s_addc_u32 s53, s31, 0
	s_add_i32 s54, s41, s2
	global_load_lds_dwordx4 v[218:219], off
	v_lshl_add_u64 v[220:221], s[52:53], 0, v[132:133]
	s_mov_b32 m0, s54
	v_lshl_add_u64 v[222:223], s[34:35], 0, v[134:135]
	global_load_lds_dwordx4 v[220:221], off
	v_lshl_add_u64 v[220:221], s[52:53], 0, v[136:137]
	s_add_i32 m0, s54, 0x2000
	s_nop 0
	global_load_lds_dwordx4 v[220:221], off
	v_lshl_add_u64 v[220:221], s[34:35], 0, v[130:131]
	s_mov_b32 m0, s3
	s_nop 0
	global_load_lds_dwordx4 v[220:221], off
	s_mov_b32 m0, s27
	s_nop 0
	global_load_lds_dwordx4 v[222:223], off
	s_waitcnt vmcnt(8)
	s_waitcnt lgkmcnt(0)
	s_barrier
; #define PG8_STAGE(bufoff, gbase, voff) do { _Pragma("unroll") for (int _i = 0; _i < 2; ++_i) \
;         __builtin_amdgcn_global_load_lds((const unsigned*)((const char*)(gbase) + (voff)[_i]), (PG8_LAS unsigned*)(lds + (bufoff) + ldsw + _i * 8192), 16, 0, 0); } while (0)
; #define PG8_LDA(dst, b, h) do { _Pragma("unroll") for (int m = 0; m < 4; ++m) _Pragma("unroll") for (int k = 0; k < 2; ++k) dst[m][k] = *(const PG8_LAS bf16x8*)(lds + PG8_SA(b, h) + aoff + m * 2048 + k * 1024); } while (0)
; #define PG8_LDB(dst, b, h) do { _Pragma("unroll") for (int n = 0; n < 2; ++n) _Pragma("unroll") for (int k = 0; k < 2; ++k) dst[n][k] = *(const PG8_LAS bf16x8*)(lds + PG8_SB(b, h) + boff + n * 2048 + k * 1024); } while (0)
; #define PG8_MMA(ai, bj, At, Bt) do { __builtin_amdgcn_s_setprio(1); _Pragma("unroll") for (int m = 0; m < 4; ++m) _Pragma("unroll") for (int n = 0; n < 2; ++n) _Pragma("unroll") for (int k = 0; k < 2; ++k) \
;         acc[ai][bj][m][n] = __builtin_amdgcn_mfma_f32_16x16x32_bf16(Bt[n][k], At[m][k], acc[ai][bj][m][n], 0, 0, 0); __builtin_amdgcn_s_setprio(0); } while (0)
; #define PG8_WAIT_V(n) asm volatile("s_waitcnt vmcnt(" #n ")" ::: "memory")
; #define PG8_WAIT_L(n) asm volatile("s_waitcnt lgkmcnt(" #n ")" ::: "memory")
; #define PG8_BAR __builtin_amdgcn_s_barrier()
; #define PG8_SCHED __builtin_amdgcn_sched_barrier(0)
; template <class Epi, class Sched, bool ALIGN_EPI = false, bool SP2 = false>
; __device__ __forceinline__ void gemm_phase(PG8_LAS unsigned char* lds, const Gemm g, const Sched& S, const Epi& E) {
;     ...
;             PG8_WAIT_V(8); PG8_WAIT_L(0); PG8_BAR; PG8_MMA(1, 0, At, B0); PG8_MMA(1, 1, At, B1); PG8_BAR; PG8_SCHED;
;             PG8_LDB(B0, 1, 0); PG8_LDB(B1, 1, 1); PG8_SCHED; PG8_LDA(At, 1, 0); PG8_STAGE(PG8_SA(0, 1), a2 + hstep, voffA);
;             PG8_WAIT_V(8); PG8_WAIT_L(0); PG8_BAR; PG8_MMA(0, 0, At, B0); PG8_MMA(0, 1, At, B1); PG8_BAR; PG8_SCHED;
	s_setprio 1
	s_waitcnt lgkmcnt(0)
	v_mfma_f32_16x16x32_bf16 v[62:65], v[152:155], v[184:187], v[62:65]
	v_mfma_f32_16x16x32_bf16 v[58:61], v[160:163], v[184:187], v[58:61]
	v_mfma_f32_16x16x32_bf16 v[54:57], v[152:155], v[192:195], v[54:57]
	v_mfma_f32_16x16x32_bf16 v[46:49], v[160:163], v[192:195], v[46:49]
	v_mfma_f32_16x16x32_bf16 v[38:41], v[152:155], v[200:203], v[38:41]
	v_mfma_f32_16x16x32_bf16 v[34:37], v[160:163], v[200:203], v[34:37]
	v_mfma_f32_16x16x32_bf16 v[22:25], v[152:155], v[208:211], v[22:25]
	v_mfma_f32_16x16x32_bf16 v[18:21], v[160:163], v[208:211], v[18:21]
	v_mfma_f32_16x16x32_bf16 v[62:65], v[156:159], v[188:191], v[62:65]
	v_mfma_f32_16x16x32_bf16 v[58:61], v[164:167], v[188:191], v[58:61]
	v_mfma_f32_16x16x32_bf16 v[54:57], v[156:159], v[196:199], v[54:57]
	v_mfma_f32_16x16x32_bf16 v[46:49], v[164:167], v[196:199], v[46:49]
	v_mfma_f32_16x16x32_bf16 v[38:41], v[156:159], v[204:207], v[38:41]
	v_mfma_f32_16x16x32_bf16 v[34:37], v[164:167], v[204:207], v[34:37]
	v_mfma_f32_16x16x32_bf16 v[22:25], v[156:159], v[212:215], v[22:25]
	v_mfma_f32_16x16x32_bf16 v[18:21], v[164:167], v[212:215], v[18:21]
	s_setprio 0
	s_setprio 1
	v_mfma_f32_16x16x32_bf16 v[50:53], v[168:171], v[184:187], v[50:53]
	v_mfma_f32_16x16x32_bf16 v[42:45], v[176:179], v[184:187], v[42:45]
	v_mfma_f32_16x16x32_bf16 v[30:33], v[168:171], v[192:195], v[30:33]
	v_mfma_f32_16x16x32_bf16 v[26:29], v[176:179], v[192:195], v[26:29]
	v_mfma_f32_16x16x32_bf16 v[14:17], v[168:171], v[200:203], v[14:17]
	v_mfma_f32_16x16x32_bf16 v[10:13], v[176:179], v[200:203], v[10:13]
	v_mfma_f32_16x16x32_bf16 v[6:9], v[168:171], v[208:211], v[6:9]
	v_mfma_f32_16x16x32_bf16 v[2:5], v[176:179], v[208:211], v[2:5]
	v_mfma_f32_16x16x32_bf16 v[50:53], v[172:175], v[188:191], v[50:53]
	v_mfma_f32_16x16x32_bf16 v[42:45], v[180:183], v[188:191], v[42:45]
	v_mfma_f32_16x16x32_bf16 v[30:33], v[172:175], v[196:199], v[30:33]
	v_mfma_f32_16x16x32_bf16 v[26:29], v[180:183], v[196:199], v[26:29]
	v_mfma_f32_16x16x32_bf16 v[14:17], v[172:175], v[204:207], v[14:17]
	v_mfma_f32_16x16x32_bf16 v[10:13], v[180:183], v[204:207], v[10:13]
	v_mfma_f32_16x16x32_bf16 v[6:9], v[172:175], v[212:215], v[6:9]
	v_mfma_f32_16x16x32_bf16 v[2:5], v[180:183], v[212:215], v[2:5]
	s_setprio 0
	s_barrier
	s_add_i32 s52, 0, 0x18000
	s_add_i32 s53, 0, 0x1c000
	v_add_u32_e32 v164, s52, v1
	v_add_u32_e32 v180, s53, v1
	ds_read_b128 v[152:155], v164
	ds_read_b128 v[156:159], v164 offset:1024
	ds_read_b128 v[160:163], v164 offset:2048
	ds_read_b128 v[164:167], v164 offset:3072
	ds_read_b128 v[168:171], v180
	ds_read_b128 v[172:175], v180 offset:1024
	ds_read_b128 v[176:179], v180 offset:2048
	ds_read_b128 v[180:183], v180 offset:3072
	s_add_u32 s34, s34, 0x80000
	s_addc_u32 s35, s35, 0
	s_mov_b32 m0, s33
	v_lshl_add_u64 v[224:225], s[34:35], 0, v[130:131]
	ds_read_b128 v[184:187], v151 offset:32768
	ds_read_b128 v[188:191], v151 offset:33792
	ds_read_b128 v[192:195], v151 offset:34816
	ds_read_b128 v[196:199], v151 offset:35840
	ds_read_b128 v[200:203], v151 offset:36864
	ds_read_b128 v[204:207], v151 offset:37888
	ds_read_b128 v[208:211], v151 offset:38912
	ds_read_b128 v[212:215], v151 offset:39936
	global_load_lds_dwordx4 v[224:225], off
	v_lshl_add_u64 v[224:225], s[34:35], 0, v[134:135]
	s_mov_b32 m0, s36
	s_nop 0
	global_load_lds_dwordx4 v[224:225], off
	s_waitcnt vmcnt(8)
	s_waitcnt lgkmcnt(0)
	s_barrier
	s_setprio 1
	s_waitcnt lgkmcnt(0)
	v_mfma_f32_16x16x32_bf16 v[126:129], v[152:155], v[184:187], v[126:129]
	v_mfma_f32_16x16x32_bf16 v[122:125], v[160:163], v[184:187], v[122:125]
	v_mfma_f32_16x16x32_bf16 v[118:121], v[152:155], v[192:195], v[118:121]
	v_mfma_f32_16x16x32_bf16 v[110:113], v[160:163], v[192:195], v[110:113]
	v_mfma_f32_16x16x32_bf16 v[102:105], v[152:155], v[200:203], v[102:105]
	v_mfma_f32_16x16x32_bf16 v[94:97], v[160:163], v[200:203], v[94:97]
	v_mfma_f32_16x16x32_bf16 v[86:89], v[152:155], v[208:211], v[86:89]
	v_mfma_f32_16x16x32_bf16 v[78:81], v[160:163], v[208:211], v[78:81]
	v_mfma_f32_16x16x32_bf16 v[126:129], v[156:159], v[188:191], v[126:129]
	v_mfma_f32_16x16x32_bf16 v[122:125], v[164:167], v[188:191], v[122:125]
	v_mfma_f32_16x16x32_bf16 v[118:121], v[156:159], v[196:199], v[118:121]
	v_mfma_f32_16x16x32_bf16 v[110:113], v[164:167], v[196:199], v[110:113]
	v_mfma_f32_16x16x32_bf16 v[102:105], v[156:159], v[204:207], v[102:105]
	v_mfma_f32_16x16x32_bf16 v[94:97], v[164:167], v[204:207], v[94:97]
	v_mfma_f32_16x16x32_bf16 v[86:89], v[156:159], v[212:215], v[86:89]
	v_mfma_f32_16x16x32_bf16 v[78:81], v[164:167], v[212:215], v[78:81]
	s_setprio 0
	s_setprio 1
	v_mfma_f32_16x16x32_bf16 v[114:117], v[168:171], v[184:187], v[114:117]
	v_mfma_f32_16x16x32_bf16 v[106:109], v[176:179], v[184:187], v[106:109]
	v_mfma_f32_16x16x32_bf16 v[98:101], v[168:171], v[192:195], v[98:101]
	v_mfma_f32_16x16x32_bf16 v[90:93], v[176:179], v[192:195], v[90:93]
	v_mfma_f32_16x16x32_bf16 v[82:85], v[168:171], v[200:203], v[82:85]
	v_mfma_f32_16x16x32_bf16 v[74:77], v[176:179], v[200:203], v[74:77]
	v_mfma_f32_16x16x32_bf16 v[70:73], v[168:171], v[208:211], v[70:73]
	v_mfma_f32_16x16x32_bf16 v[66:69], v[176:179], v[208:211], v[66:69]
	v_mfma_f32_16x16x32_bf16 v[114:117], v[172:175], v[188:191], v[114:117]
	v_mfma_f32_16x16x32_bf16 v[106:109], v[180:183], v[188:191], v[106:109]
	v_mfma_f32_16x16x32_bf16 v[98:101], v[172:175], v[196:199], v[98:101]
	v_mfma_f32_16x16x32_bf16 v[90:93], v[180:183], v[196:199], v[90:93]
	v_mfma_f32_16x16x32_bf16 v[82:85], v[172:175], v[204:207], v[82:85]
	v_mfma_f32_16x16x32_bf16 v[74:77], v[180:183], v[204:207], v[74:77]
	v_mfma_f32_16x16x32_bf16 v[70:73], v[172:175], v[212:215], v[70:73]
	v_mfma_f32_16x16x32_bf16 v[66:69], v[180:183], v[212:215], v[66:69]
	s_setprio 0
	s_barrier
; #define PG8_STAGE(bufoff, gbase, voff) do { _Pragma("unroll") for (int _i = 0; _i < 2; ++_i) \
;         __builtin_amdgcn_global_load_lds((const unsigned*)((const char*)(gbase) + (voff)[_i]), (PG8_LAS unsigned*)(lds + (bufoff) + ldsw + _i * 8192), 16, 0, 0); } while (0)
; #define PG8_LDA(dst, b, h) do { _Pragma("unroll") for (int m = 0; m < 4; ++m) _Pragma("unroll") for (int k = 0; k < 2; ++k) dst[m][k] = *(const PG8_LAS bf16x8*)(lds + PG8_SA(b, h) + aoff + m * 2048 + k * 1024); } while (0)
; #define PG8_MMA(ai, bj, At, Bt) do { __builtin_amdgcn_s_setprio(1); _Pragma("unroll") for (int m = 0; m < 4; ++m) _Pragma("unroll") for (int n = 0; n < 2; ++n) _Pragma("unroll") for (int k = 0; k < 2; ++k) \
;         acc[ai][bj][m][n] = __builtin_amdgcn_mfma_f32_16x16x32_bf16(Bt[n][k], At[m][k], acc[ai][bj][m][n], 0, 0, 0); __builtin_amdgcn_s_setprio(0); } while (0)
; #define PG8_WAIT_V(n) asm volatile("s_waitcnt vmcnt(" #n ")" ::: "memory")
; #define PG8_WAIT_L(n) asm volatile("s_waitcnt lgkmcnt(" #n ")" ::: "memory")
; #define PG8_BAR __builtin_amdgcn_s_barrier()
; #define PG8_SCHED __builtin_amdgcn_sched_barrier(0)
; template <class Epi, class Sched, bool ALIGN_EPI = false, bool SP2 = false>
; __device__ __forceinline__ void gemm_phase(PG8_LAS unsigned char* lds, const Gemm g, const Sched& S, const Epi& E) {
;     ...
;         for (int t = 0; t < nt; t += 2) {
;             const bool last = (t == nt - 2);
;             const char* a1 = cA + (size_t)(t + 1) * kstep;
;             const char* a2 = last ? nA : cA + (size_t)(t + 2) * kstep; const char* b2 = last ? nB : cB + (size_t)(t + 2) * kstep;
;             const char* a3 = a2 + kstep; const char* b3 = b2 + kstep;
;     ...
;             PG8_LDA(At, 1, 1); PG8_STAGE(PG8_SB(1, 0), b3, voffB); PG8_STAGE(PG8_SB(1, 1), b3 + hstep, voffB); PG8_STAGE(PG8_SA(1, 0), a3, voffA);
;             PG8_WAIT_V(8); PG8_WAIT_L(0); PG8_BAR; PG8_MMA(1, 0, At, B0); PG8_MMA(1, 1, At, B1); PG8_BAR; PG8_SCHED;
	s_add_i32 s34, s52, s2
	v_lshl_add_u64 v[216:217], v[216:217], 0, s[10:11]
	s_mov_b32 m0, s34
	ds_read_b128 v[184:187], v151 offset:49152
	ds_read_b128 v[188:191], v151 offset:50176
	ds_read_b128 v[192:195], v151 offset:51200
	ds_read_b128 v[196:199], v151 offset:52224
	ds_read_b128 v[200:203], v151 offset:53248
	ds_read_b128 v[204:207], v151 offset:54272
	ds_read_b128 v[208:211], v151 offset:55296
	ds_read_b128 v[212:215], v151 offset:56320
	global_load_lds_dwordx4 v[216:217], off
	s_add_i32 m0, s34, 0x2000
	s_add_u32 s30, s30, 0x80080
	v_lshl_add_u64 v[216:217], v[218:219], 0, s[10:11]
	s_addc_u32 s31, s31, 0
	s_add_i32 s34, s53, s2
	global_load_lds_dwordx4 v[216:217], off
	v_lshl_add_u64 v[216:217], s[30:31], 0, v[132:133]
	s_mov_b32 m0, s34
	s_nop 0
	global_load_lds_dwordx4 v[216:217], off
	v_lshl_add_u64 v[216:217], s[30:31], 0, v[136:137]
	s_add_i32 m0, s34, 0x2000
	s_nop 0
	global_load_lds_dwordx4 v[216:217], off
	v_lshl_add_u64 v[216:217], v[220:221], 0, s[10:11]
	s_mov_b32 m0, s38
	s_nop 0
	global_load_lds_dwordx4 v[216:217], off
	v_lshl_add_u64 v[216:217], v[222:223], 0, s[10:11]
	s_mov_b32 m0, s39
	s_nop 0
	global_load_lds_dwordx4 v[216:217], off
	s_waitcnt vmcnt(8)
	s_waitcnt lgkmcnt(0)
	s_barrier
	s_setprio 1
	s_waitcnt lgkmcnt(0)
	v_mfma_f32_16x16x32_bf16 v[62:65], v[152:155], v[184:187], v[62:65]
	v_mfma_f32_16x16x32_bf16 v[58:61], v[160:163], v[184:187], v[58:61]
	v_mfma_f32_16x16x32_bf16 v[54:57], v[152:155], v[192:195], v[54:57]
	v_mfma_f32_16x16x32_bf16 v[46:49], v[160:163], v[192:195], v[46:49]
	v_mfma_f32_16x16x32_bf16 v[38:41], v[152:155], v[200:203], v[38:41]
	v_mfma_f32_16x16x32_bf16 v[34:37], v[160:163], v[200:203], v[34:37]
	v_mfma_f32_16x16x32_bf16 v[22:25], v[152:155], v[208:211], v[22:25]
	v_mfma_f32_16x16x32_bf16 v[18:21], v[160:163], v[208:211], v[18:21]
	v_mfma_f32_16x16x32_bf16 v[62:65], v[156:159], v[188:191], v[62:65]
	v_mfma_f32_16x16x32_bf16 v[58:61], v[164:167], v[188:191], v[58:61]
	v_mfma_f32_16x16x32_bf16 v[54:57], v[156:159], v[196:199], v[54:57]
	v_mfma_f32_16x16x32_bf16 v[46:49], v[164:167], v[196:199], v[46:49]
	v_mfma_f32_16x16x32_bf16 v[38:41], v[156:159], v[204:207], v[38:41]
	v_mfma_f32_16x16x32_bf16 v[34:37], v[164:167], v[204:207], v[34:37]
	v_mfma_f32_16x16x32_bf16 v[22:25], v[156:159], v[212:215], v[22:25]
	v_mfma_f32_16x16x32_bf16 v[18:21], v[164:167], v[212:215], v[18:21]
	s_setprio 0
	s_setprio 1
	v_mfma_f32_16x16x32_bf16 v[50:53], v[168:171], v[184:187], v[50:53]
	v_mfma_f32_16x16x32_bf16 v[42:45], v[176:179], v[184:187], v[42:45]
	v_mfma_f32_16x16x32_bf16 v[30:33], v[168:171], v[192:195], v[30:33]
	v_mfma_f32_16x16x32_bf16 v[26:29], v[176:179], v[192:195], v[26:29]
	v_mfma_f32_16x16x32_bf16 v[14:17], v[168:171], v[200:203], v[14:17]
	v_mfma_f32_16x16x32_bf16 v[10:13], v[176:179], v[200:203], v[10:13]
	v_mfma_f32_16x16x32_bf16 v[6:9], v[168:171], v[208:211], v[6:9]
	v_mfma_f32_16x16x32_bf16 v[2:5], v[176:179], v[208:211], v[2:5]
	v_mfma_f32_16x16x32_bf16 v[50:53], v[172:175], v[188:191], v[50:53]
	v_mfma_f32_16x16x32_bf16 v[42:45], v[180:183], v[188:191], v[42:45]
	v_mfma_f32_16x16x32_bf16 v[30:33], v[172:175], v[196:199], v[30:33]
	v_mfma_f32_16x16x32_bf16 v[26:29], v[180:183], v[196:199], v[26:29]
	v_mfma_f32_16x16x32_bf16 v[14:17], v[172:175], v[204:207], v[14:17]
	v_mfma_f32_16x16x32_bf16 v[10:13], v[180:183], v[204:207], v[10:13]
	v_mfma_f32_16x16x32_bf16 v[6:9], v[172:175], v[212:215], v[6:9]
	v_mfma_f32_16x16x32_bf16 v[2:5], v[180:183], v[212:215], v[2:5]
	s_setprio 0
	s_add_i32 s51, s51, 2
	s_add_u32 s28, s28, 0x100
	s_addc_u32 s29, s29, 0
	s_add_u32 s47, s47, 0x100
	s_addc_u32 s50, s50, 0
	s_cmp_gt_u32 s51, 29
	s_barrier
	s_cbranch_scc0 .LBB0_2642
	s_and_b64 vcc, exec, s[12:13]
	s_cbranch_vccz .LBB0_2645
	s_barrier

; #define PG8_STAGE(bufoff, gbase, voff) do { _Pragma("unroll") for (int _i = 0; _i < 2; ++_i) \
;         __builtin_amdgcn_global_load_lds((const unsigned*)((const char*)(gbase) + (voff)[_i]), (PG8_LAS unsigned*)(lds + (bufoff) + ldsw + _i * 8192), 16, 0, 0); } while (0)
; #define PG8_LDA(dst, b, h) do { _Pragma("unroll") for (int m = 0; m < 4; ++m) _Pragma("unroll") for (int k = 0; k < 2; ++k) dst[m][k] = *(const PG8_LAS bf16x8*)(lds + PG8_SA(b, h) + aoff + m * 2048 + k * 1024); } while (0)
; #define PG8_LDB(dst, b, h) do { _Pragma("unroll") for (int n = 0; n < 2; ++n) _Pragma("unroll") for (int k = 0; k < 2; ++k) dst[n][k] = *(const PG8_LAS bf16x8*)(lds + PG8_SB(b, h) + boff + n * 2048 + k * 1024); } while (0)
; #define PG8_MMA(ai, bj, At, Bt) do { __builtin_amdgcn_s_setprio(1); _Pragma("unroll") for (int m = 0; m < 4; ++m) _Pragma("unroll") for (int n = 0; n < 2; ++n) _Pragma("unroll") for (int k = 0; k < 2; ++k) \
;         acc[ai][bj][m][n] = __builtin_amdgcn_mfma_f32_16x16x32_bf16(Bt[n][k], At[m][k], acc[ai][bj][m][n], 0, 0, 0); __builtin_amdgcn_s_setprio(0); } while (0)
; #define PG8_WAIT_V(n) asm volatile("s_waitcnt vmcnt(" #n ")" ::: "memory")
; #define PG8_WAIT_L(n) asm volatile("s_waitcnt lgkmcnt(" #n ")" ::: "memory")
; #define PG8_BAR __builtin_amdgcn_s_barrier()
; #define PG8_SCHED __builtin_amdgcn_sched_barrier(0)
; template <class Epi, class Sched, bool ALIGN_EPI = false, bool SP2 = false>
; __device__ __forceinline__ void gemm_phase(PG8_LAS unsigned char* lds, const Gemm g, const Sched& S, const Epi& E) {
;     ...
;             if constexpr (SP2) {
;             PG8_LDB(B0, 0, 0); PG8_LDB(B1, 0, 1); PG8_SCHED; PG8_LDA(At, 0, 0); PG8_STAGE(PG8_SA(1, 1), a1 + hstep, voffA);
;             PG8_WAIT_V(8); PG8_WAIT_L(0); PG8_BAR; PG8_MMA(0, 0, At, B0); PG8_MMA(0, 1, At, B1); PG8_BAR; PG8_SCHED;
;             PG8_LDA(At, 0, 1); PG8_STAGE(PG8_SB(0, 0), b2, voffB); PG8_STAGE(PG8_SB(0, 1), b2 + hstep, voffB); PG8_STAGE(PG8_SA(0, 0), a2, voffA);
;             PG8_WAIT_V(8); PG8_WAIT_L(0); PG8_BAR; PG8_MMA(1, 0, At, B0); PG8_MMA(1, 1, At, B1); PG8_BAR; PG8_SCHED;
.LBB0_2774:
	ds_read_b128 v[146:149], v153
	ds_read_b128 v[156:159], v153 offset:1024
	ds_read_b128 v[160:163], v153 offset:2048
	ds_read_b128 v[164:167], v153 offset:3072
	ds_read_b128 v[168:171], v154
	ds_read_b128 v[172:175], v154 offset:1024
	ds_read_b128 v[176:179], v154 offset:2048
	ds_read_b128 v[180:183], v154 offset:3072
	s_add_u32 s24, s22, 0xfff80080
	s_addc_u32 s25, s23, -1
	s_cmp_eq_u32 s44, 28
	s_cselect_b32 s27, s15, s25
	s_cselect_b32 s26, s40, s24
	s_cselect_b32 s25, s13, s43
	s_cselect_b32 s24, s41, s42
	v_lshl_add_u64 v[216:217], s[22:23], 0, v[138:139]
	s_add_i32 m0, s21, 0xc000
	ds_read_b128 v[184:187], v155
	ds_read_b128 v[188:191], v155 offset:1024
	ds_read_b128 v[192:195], v155 offset:2048
	ds_read_b128 v[196:199], v155 offset:3072
	ds_read_b128 v[200:203], v155 offset:4096
	ds_read_b128 v[204:207], v155 offset:5120
	ds_read_b128 v[208:211], v155 offset:6144
	ds_read_b128 v[212:215], v155 offset:7168
	global_load_lds_dwordx4 v[216:217], off
	v_lshl_add_u64 v[216:217], s[22:23], 0, v[140:141]
	s_add_i32 m0, s21, 0xe000
	s_nop 0
	global_load_lds_dwordx4 v[216:217], off
	s_waitcnt vmcnt(8)
	s_waitcnt lgkmcnt(0)
	s_barrier
	s_setprio 1
	s_waitcnt lgkmcnt(0)
	v_mfma_f32_16x16x32_bf16 v[126:129], v[146:149], v[184:187], v[126:129]
	v_mfma_f32_16x16x32_bf16 v[122:125], v[160:163], v[184:187], v[122:125]
	v_mfma_f32_16x16x32_bf16 v[110:113], v[146:149], v[192:195], v[110:113]
	v_mfma_f32_16x16x32_bf16 v[106:109], v[160:163], v[192:195], v[106:109]
	v_mfma_f32_16x16x32_bf16 v[94:97], v[146:149], v[200:203], v[94:97]
	v_mfma_f32_16x16x32_bf16 v[90:93], v[160:163], v[200:203], v[90:93]
	v_mfma_f32_16x16x32_bf16 v[78:81], v[146:149], v[208:211], v[78:81]
	v_mfma_f32_16x16x32_bf16 v[74:77], v[160:163], v[208:211], v[74:77]
	v_mfma_f32_16x16x32_bf16 v[126:129], v[156:159], v[188:191], v[126:129]
	v_mfma_f32_16x16x32_bf16 v[122:125], v[164:167], v[188:191], v[122:125]
	v_mfma_f32_16x16x32_bf16 v[110:113], v[156:159], v[196:199], v[110:113]
	v_mfma_f32_16x16x32_bf16 v[106:109], v[164:167], v[196:199], v[106:109]
	v_mfma_f32_16x16x32_bf16 v[94:97], v[156:159], v[204:207], v[94:97]
	v_mfma_f32_16x16x32_bf16 v[90:93], v[164:167], v[204:207], v[90:93]
	v_mfma_f32_16x16x32_bf16 v[78:81], v[156:159], v[212:215], v[78:81]
	v_mfma_f32_16x16x32_bf16 v[74:77], v[164:167], v[212:215], v[74:77]
	s_setprio 0
	s_setprio 1
	v_mfma_f32_16x16x32_bf16 v[118:121], v[168:171], v[184:187], v[118:121]
	v_mfma_f32_16x16x32_bf16 v[114:117], v[176:179], v[184:187], v[114:117]
	v_mfma_f32_16x16x32_bf16 v[102:105], v[168:171], v[192:195], v[102:105]
	v_mfma_f32_16x16x32_bf16 v[98:101], v[176:179], v[192:195], v[98:101]
	v_mfma_f32_16x16x32_bf16 v[86:89], v[168:171], v[200:203], v[86:89]
	v_mfma_f32_16x16x32_bf16 v[82:85], v[176:179], v[200:203], v[82:85]
	v_mfma_f32_16x16x32_bf16 v[70:73], v[168:171], v[208:211], v[70:73]
	v_mfma_f32_16x16x32_bf16 v[66:69], v[176:179], v[208:211], v[66:69]
	v_mfma_f32_16x16x32_bf16 v[118:121], v[172:175], v[188:191], v[118:121]
	v_mfma_f32_16x16x32_bf16 v[114:117], v[180:183], v[188:191], v[114:117]
	v_mfma_f32_16x16x32_bf16 v[102:105], v[172:175], v[196:199], v[102:105]
	v_mfma_f32_16x16x32_bf16 v[98:101], v[180:183], v[196:199], v[98:101]
	v_mfma_f32_16x16x32_bf16 v[86:89], v[172:175], v[204:207], v[86:89]
	v_mfma_f32_16x16x32_bf16 v[82:85], v[180:183], v[204:207], v[82:85]
	v_mfma_f32_16x16x32_bf16 v[70:73], v[172:175], v[212:215], v[70:73]
	v_mfma_f32_16x16x32_bf16 v[66:69], v[180:183], v[212:215], v[66:69]
	s_setprio 0
	s_barrier
	s_add_i32 s45, s36, s2
	v_lshl_add_u64 v[216:217], s[24:25], 0, v[134:135]
	s_mov_b32 m0, s45
	ds_read_b128 v[184:187], v155 offset:16384
	ds_read_b128 v[188:191], v155 offset:17408
	ds_read_b128 v[192:195], v155 offset:18432
	ds_read_b128 v[196:199], v155 offset:19456
	ds_read_b128 v[200:203], v155 offset:20480
	ds_read_b128 v[204:207], v155 offset:21504
	ds_read_b128 v[208:211], v155 offset:22528
	ds_read_b128 v[212:215], v155 offset:23552
	global_load_lds_dwordx4 v[216:217], off
	s_add_i32 m0, s45, 0x2000
	s_add_u32 s46, s24, 0x80000
	v_lshl_add_u64 v[218:219], s[24:25], 0, v[130:131]
	s_addc_u32 s47, s25, 0
	s_add_i32 s45, s37, s2
	global_load_lds_dwordx4 v[218:219], off
	v_lshl_add_u64 v[220:221], s[46:47], 0, v[134:135]
	s_mov_b32 m0, s45
	v_lshl_add_u64 v[222:223], s[26:27], 0, v[132:133]
	global_load_lds_dwordx4 v[220:221], off
	v_lshl_add_u64 v[220:221], s[46:47], 0, v[130:131]
	s_add_i32 m0, s45, 0x2000
	s_nop 0
	global_load_lds_dwordx4 v[220:221], off
	v_lshl_add_u64 v[220:221], s[26:27], 0, v[136:137]
	s_mov_b32 m0, s21
	s_nop 0
	global_load_lds_dwordx4 v[220:221], off
	s_mov_b32 m0, s28
	s_nop 0
	global_load_lds_dwordx4 v[222:223], off
	s_waitcnt vmcnt(8)
	s_waitcnt lgkmcnt(0)
	s_barrier
; #define PG8_STAGE(bufoff, gbase, voff) do { _Pragma("unroll") for (int _i = 0; _i < 2; ++_i) \
;         __builtin_amdgcn_global_load_lds((const unsigned*)((const char*)(gbase) + (voff)[_i]), (PG8_LAS unsigned*)(lds + (bufoff) + ldsw + _i * 8192), 16, 0, 0); } while (0)
; #define PG8_LDA(dst, b, h) do { _Pragma("unroll") for (int m = 0; m < 4; ++m) _Pragma("unroll") for (int k = 0; k < 2; ++k) dst[m][k] = *(const PG8_LAS bf16x8*)(lds + PG8_SA(b, h) + aoff + m * 2048 + k * 1024); } while (0)
; #define PG8_LDB(dst, b, h) do { _Pragma("unroll") for (int n = 0; n < 2; ++n) _Pragma("unroll") for (int k = 0; k < 2; ++k) dst[n][k] = *(const PG8_LAS bf16x8*)(lds + PG8_SB(b, h) + boff + n * 2048 + k * 1024); } while (0)
; #define PG8_MMA(ai, bj, At, Bt) do { __builtin_amdgcn_s_setprio(1); _Pragma("unroll") for (int m = 0; m < 4; ++m) _Pragma("unroll") for (int n = 0; n < 2; ++n) _Pragma("unroll") for (int k = 0; k < 2; ++k) \
;         acc[ai][bj][m][n] = __builtin_amdgcn_mfma_f32_16x16x32_bf16(Bt[n][k], At[m][k], acc[ai][bj][m][n], 0, 0, 0); __builtin_amdgcn_s_setprio(0); } while (0)
; #define PG8_WAIT_V(n) asm volatile("s_waitcnt vmcnt(" #n ")" ::: "memory")
; #define PG8_WAIT_L(n) asm volatile("s_waitcnt lgkmcnt(" #n ")" ::: "memory")
; #define PG8_BAR __builtin_amdgcn_s_barrier()
; #define PG8_SCHED __builtin_amdgcn_sched_barrier(0)
; template <class Epi, class Sched, bool ALIGN_EPI = false, bool SP2 = false>
; __device__ __forceinline__ void gemm_phase(PG8_LAS unsigned char* lds, const Gemm g, const Sched& S, const Epi& E) {
;     ...
;             PG8_WAIT_V(8); PG8_WAIT_L(0); PG8_BAR; PG8_MMA(1, 0, At, B0); PG8_MMA(1, 1, At, B1); PG8_BAR; PG8_SCHED;
;             PG8_LDB(B0, 1, 0); PG8_LDB(B1, 1, 1); PG8_SCHED; PG8_LDA(At, 1, 0); PG8_STAGE(PG8_SA(0, 1), a2 + hstep, voffA);
;             PG8_WAIT_V(8); PG8_WAIT_L(0); PG8_BAR; PG8_MMA(0, 0, At, B0); PG8_MMA(0, 1, At, B1); PG8_BAR; PG8_SCHED;
	s_setprio 1
	s_waitcnt lgkmcnt(0)
	v_mfma_f32_16x16x32_bf16 v[62:65], v[146:149], v[184:187], v[62:65]
	v_mfma_f32_16x16x32_bf16 v[58:61], v[160:163], v[184:187], v[58:61]
	v_mfma_f32_16x16x32_bf16 v[46:49], v[146:149], v[192:195], v[46:49]
	v_mfma_f32_16x16x32_bf16 v[42:45], v[160:163], v[192:195], v[42:45]
	v_mfma_f32_16x16x32_bf16 v[30:33], v[146:149], v[200:203], v[30:33]
	v_mfma_f32_16x16x32_bf16 v[26:29], v[160:163], v[200:203], v[26:29]
	v_mfma_f32_16x16x32_bf16 v[14:17], v[146:149], v[208:211], v[14:17]
	v_mfma_f32_16x16x32_bf16 v[10:13], v[160:163], v[208:211], v[10:13]
	v_mfma_f32_16x16x32_bf16 v[62:65], v[156:159], v[188:191], v[62:65]
	v_mfma_f32_16x16x32_bf16 v[58:61], v[164:167], v[188:191], v[58:61]
	v_mfma_f32_16x16x32_bf16 v[46:49], v[156:159], v[196:199], v[46:49]
	v_mfma_f32_16x16x32_bf16 v[42:45], v[164:167], v[196:199], v[42:45]
	v_mfma_f32_16x16x32_bf16 v[30:33], v[156:159], v[204:207], v[30:33]
	v_mfma_f32_16x16x32_bf16 v[26:29], v[164:167], v[204:207], v[26:29]
	v_mfma_f32_16x16x32_bf16 v[14:17], v[156:159], v[212:215], v[14:17]
	v_mfma_f32_16x16x32_bf16 v[10:13], v[164:167], v[212:215], v[10:13]
	s_setprio 0
	s_setprio 1
	v_mfma_f32_16x16x32_bf16 v[54:57], v[168:171], v[184:187], v[54:57]
	v_mfma_f32_16x16x32_bf16 v[50:53], v[176:179], v[184:187], v[50:53]
	v_mfma_f32_16x16x32_bf16 v[38:41], v[168:171], v[192:195], v[38:41]
	v_mfma_f32_16x16x32_bf16 v[34:37], v[176:179], v[192:195], v[34:37]
	v_mfma_f32_16x16x32_bf16 v[22:25], v[168:171], v[200:203], v[22:25]
	v_mfma_f32_16x16x32_bf16 v[18:21], v[176:179], v[200:203], v[18:21]
	v_mfma_f32_16x16x32_bf16 v[6:9], v[168:171], v[208:211], v[6:9]
	v_mfma_f32_16x16x32_bf16 v[2:5], v[176:179], v[208:211], v[2:5]
	v_mfma_f32_16x16x32_bf16 v[54:57], v[172:175], v[188:191], v[54:57]
	v_mfma_f32_16x16x32_bf16 v[50:53], v[180:183], v[188:191], v[50:53]
	v_mfma_f32_16x16x32_bf16 v[38:41], v[172:175], v[196:199], v[38:41]
	v_mfma_f32_16x16x32_bf16 v[34:37], v[180:183], v[196:199], v[34:37]
	v_mfma_f32_16x16x32_bf16 v[22:25], v[172:175], v[204:207], v[22:25]
	v_mfma_f32_16x16x32_bf16 v[18:21], v[180:183], v[204:207], v[18:21]
	v_mfma_f32_16x16x32_bf16 v[6:9], v[172:175], v[212:215], v[6:9]
	v_mfma_f32_16x16x32_bf16 v[2:5], v[180:183], v[212:215], v[2:5]
	s_setprio 0
	s_barrier
	s_add_i32 s45, 0, 0x18000
	s_add_i32 s46, 0, 0x1c000
	v_add_u32_e32 v164, s45, v1
	v_add_u32_e32 v180, s46, v1
	ds_read_b128 v[146:149], v164
	ds_read_b128 v[156:159], v164 offset:1024
	ds_read_b128 v[160:163], v164 offset:2048
	ds_read_b128 v[164:167], v164 offset:3072
	ds_read_b128 v[168:171], v180
	ds_read_b128 v[172:175], v180 offset:1024
	ds_read_b128 v[176:179], v180 offset:2048
	ds_read_b128 v[180:183], v180 offset:3072
	s_add_u32 s26, s26, 0x80000
	s_addc_u32 s27, s27, 0
	s_mov_b32 m0, s29
	v_lshl_add_u64 v[224:225], s[26:27], 0, v[136:137]
	ds_read_b128 v[184:187], v155 offset:32768
	ds_read_b128 v[188:191], v155 offset:33792
	ds_read_b128 v[192:195], v155 offset:34816
	ds_read_b128 v[196:199], v155 offset:35840
	ds_read_b128 v[200:203], v155 offset:36864
	ds_read_b128 v[204:207], v155 offset:37888
	ds_read_b128 v[208:211], v155 offset:38912
	ds_read_b128 v[212:215], v155 offset:39936
	global_load_lds_dwordx4 v[224:225], off
	v_lshl_add_u64 v[224:225], s[26:27], 0, v[132:133]
	s_mov_b32 m0, s30
	s_nop 0
	global_load_lds_dwordx4 v[224:225], off
	s_waitcnt vmcnt(8)
	s_waitcnt lgkmcnt(0)
	s_barrier
	s_setprio 1
	s_waitcnt lgkmcnt(0)
	v_mfma_f32_16x16x32_bf16 v[126:129], v[146:149], v[184:187], v[126:129]
	v_mfma_f32_16x16x32_bf16 v[122:125], v[160:163], v[184:187], v[122:125]
	v_mfma_f32_16x16x32_bf16 v[110:113], v[146:149], v[192:195], v[110:113]
	v_mfma_f32_16x16x32_bf16 v[106:109], v[160:163], v[192:195], v[106:109]
	v_mfma_f32_16x16x32_bf16 v[94:97], v[146:149], v[200:203], v[94:97]
	v_mfma_f32_16x16x32_bf16 v[90:93], v[160:163], v[200:203], v[90:93]
	v_mfma_f32_16x16x32_bf16 v[78:81], v[146:149], v[208:211], v[78:81]
	v_mfma_f32_16x16x32_bf16 v[74:77], v[160:163], v[208:211], v[74:77]
	v_mfma_f32_16x16x32_bf16 v[126:129], v[156:159], v[188:191], v[126:129]
	v_mfma_f32_16x16x32_bf16 v[122:125], v[164:167], v[188:191], v[122:125]
	v_mfma_f32_16x16x32_bf16 v[110:113], v[156:159], v[196:199], v[110:113]
	v_mfma_f32_16x16x32_bf16 v[106:109], v[164:167], v[196:199], v[106:109]
	v_mfma_f32_16x16x32_bf16 v[94:97], v[156:159], v[204:207], v[94:97]
	v_mfma_f32_16x16x32_bf16 v[90:93], v[164:167], v[204:207], v[90:93]
	v_mfma_f32_16x16x32_bf16 v[78:81], v[156:159], v[212:215], v[78:81]
	v_mfma_f32_16x16x32_bf16 v[74:77], v[164:167], v[212:215], v[74:77]
	s_setprio 0
	s_setprio 1
	v_mfma_f32_16x16x32_bf16 v[118:121], v[168:171], v[184:187], v[118:121]
	v_mfma_f32_16x16x32_bf16 v[114:117], v[176:179], v[184:187], v[114:117]
	v_mfma_f32_16x16x32_bf16 v[102:105], v[168:171], v[192:195], v[102:105]
	v_mfma_f32_16x16x32_bf16 v[98:101], v[176:179], v[192:195], v[98:101]
	v_mfma_f32_16x16x32_bf16 v[86:89], v[168:171], v[200:203], v[86:89]
	v_mfma_f32_16x16x32_bf16 v[82:85], v[176:179], v[200:203], v[82:85]
	v_mfma_f32_16x16x32_bf16 v[70:73], v[168:171], v[208:211], v[70:73]
	v_mfma_f32_16x16x32_bf16 v[66:69], v[176:179], v[208:211], v[66:69]
	v_mfma_f32_16x16x32_bf16 v[118:121], v[172:175], v[188:191], v[118:121]
	v_mfma_f32_16x16x32_bf16 v[114:117], v[180:183], v[188:191], v[114:117]
	v_mfma_f32_16x16x32_bf16 v[102:105], v[172:175], v[196:199], v[102:105]
	v_mfma_f32_16x16x32_bf16 v[98:101], v[180:183], v[196:199], v[98:101]
	v_mfma_f32_16x16x32_bf16 v[86:89], v[172:175], v[204:207], v[86:89]
	v_mfma_f32_16x16x32_bf16 v[82:85], v[180:183], v[204:207], v[82:85]
	v_mfma_f32_16x16x32_bf16 v[70:73], v[172:175], v[212:215], v[70:73]
	v_mfma_f32_16x16x32_bf16 v[66:69], v[180:183], v[212:215], v[66:69]
	s_setprio 0
	s_barrier
; #define PG8_STAGE(bufoff, gbase, voff) do { _Pragma("unroll") for (int _i = 0; _i < 2; ++_i) \
;         __builtin_amdgcn_global_load_lds((const unsigned*)((const char*)(gbase) + (voff)[_i]), (PG8_LAS unsigned*)(lds + (bufoff) + ldsw + _i * 8192), 16, 0, 0); } while (0)
; #define PG8_LDA(dst, b, h) do { _Pragma("unroll") for (int m = 0; m < 4; ++m) _Pragma("unroll") for (int k = 0; k < 2; ++k) dst[m][k] = *(const PG8_LAS bf16x8*)(lds + PG8_SA(b, h) + aoff + m * 2048 + k * 1024); } while (0)
; #define PG8_MMA(ai, bj, At, Bt) do { __builtin_amdgcn_s_setprio(1); _Pragma("unroll") for (int m = 0; m < 4; ++m) _Pragma("unroll") for (int n = 0; n < 2; ++n) _Pragma("unroll") for (int k = 0; k < 2; ++k) \
;         acc[ai][bj][m][n] = __builtin_amdgcn_mfma_f32_16x16x32_bf16(Bt[n][k], At[m][k], acc[ai][bj][m][n], 0, 0, 0); __builtin_amdgcn_s_setprio(0); } while (0)
; #define PG8_WAIT_V(n) asm volatile("s_waitcnt vmcnt(" #n ")" ::: "memory")
; #define PG8_WAIT_L(n) asm volatile("s_waitcnt lgkmcnt(" #n ")" ::: "memory")
; #define PG8_BAR __builtin_amdgcn_s_barrier()
; #define PG8_SCHED __builtin_amdgcn_sched_barrier(0)
; template <class Epi, class Sched, bool ALIGN_EPI = false, bool SP2 = false>
; __device__ __forceinline__ void gemm_phase(PG8_LAS unsigned char* lds, const Gemm g, const Sched& S, const Epi& E) {
;     ...
;         for (int t = 0; t < nt; t += 2) {
;             const bool last = (t == nt - 2);
;             const char* a1 = cA + (size_t)(t + 1) * kstep;
;             const char* a2 = last ? nA : cA + (size_t)(t + 2) * kstep; const char* b2 = last ? nB : cB + (size_t)(t + 2) * kstep;
;             const char* a3 = a2 + kstep; const char* b3 = b2 + kstep;
;     ...
;             PG8_LDA(At, 1, 1); PG8_STAGE(PG8_SB(1, 0), b3, voffB); PG8_STAGE(PG8_SB(1, 1), b3 + hstep, voffB); PG8_STAGE(PG8_SA(1, 0), a3, voffA);
;             PG8_WAIT_V(8); PG8_WAIT_L(0); PG8_BAR; PG8_MMA(1, 0, At, B0); PG8_MMA(1, 1, At, B1); PG8_BAR; PG8_SCHED;
	s_add_i32 s26, s45, s2
	v_lshl_add_u64 v[216:217], v[216:217], 0, s[8:9]
	s_mov_b32 m0, s26
	ds_read_b128 v[184:187], v155 offset:49152
	ds_read_b128 v[188:191], v155 offset:50176
	ds_read_b128 v[192:195], v155 offset:51200
	ds_read_b128 v[196:199], v155 offset:52224
	ds_read_b128 v[200:203], v155 offset:53248
	ds_read_b128 v[204:207], v155 offset:54272
	ds_read_b128 v[208:211], v155 offset:55296
	ds_read_b128 v[212:215], v155 offset:56320
	global_load_lds_dwordx4 v[216:217], off
	s_add_i32 m0, s26, 0x2000
	s_add_u32 s24, s24, 0x80080
	v_lshl_add_u64 v[216:217], v[218:219], 0, s[8:9]
	s_addc_u32 s25, s25, 0
	s_add_i32 s26, s46, s2
	global_load_lds_dwordx4 v[216:217], off
	v_lshl_add_u64 v[216:217], s[24:25], 0, v[134:135]
	s_mov_b32 m0, s26
	s_nop 0
	global_load_lds_dwordx4 v[216:217], off
	v_lshl_add_u64 v[216:217], s[24:25], 0, v[130:131]
	s_add_i32 m0, s26, 0x2000
	s_nop 0
	global_load_lds_dwordx4 v[216:217], off
	v_lshl_add_u64 v[216:217], v[220:221], 0, s[8:9]
	s_mov_b32 m0, s34
	s_nop 0
	global_load_lds_dwordx4 v[216:217], off
	v_lshl_add_u64 v[216:217], v[222:223], 0, s[8:9]
	s_mov_b32 m0, s35
	s_nop 0
	global_load_lds_dwordx4 v[216:217], off
	s_waitcnt vmcnt(8)
	s_waitcnt lgkmcnt(0)
	s_barrier
	s_setprio 1
	s_waitcnt lgkmcnt(0)
	v_mfma_f32_16x16x32_bf16 v[62:65], v[146:149], v[184:187], v[62:65]
	v_mfma_f32_16x16x32_bf16 v[58:61], v[160:163], v[184:187], v[58:61]
	v_mfma_f32_16x16x32_bf16 v[46:49], v[146:149], v[192:195], v[46:49]
	v_mfma_f32_16x16x32_bf16 v[42:45], v[160:163], v[192:195], v[42:45]
	v_mfma_f32_16x16x32_bf16 v[30:33], v[146:149], v[200:203], v[30:33]
	v_mfma_f32_16x16x32_bf16 v[26:29], v[160:163], v[200:203], v[26:29]
	v_mfma_f32_16x16x32_bf16 v[14:17], v[146:149], v[208:211], v[14:17]
	v_mfma_f32_16x16x32_bf16 v[10:13], v[160:163], v[208:211], v[10:13]
	v_mfma_f32_16x16x32_bf16 v[62:65], v[156:159], v[188:191], v[62:65]
	v_mfma_f32_16x16x32_bf16 v[58:61], v[164:167], v[188:191], v[58:61]
	v_mfma_f32_16x16x32_bf16 v[46:49], v[156:159], v[196:199], v[46:49]
	v_mfma_f32_16x16x32_bf16 v[42:45], v[164:167], v[196:199], v[42:45]
	v_mfma_f32_16x16x32_bf16 v[30:33], v[156:159], v[204:207], v[30:33]
	v_mfma_f32_16x16x32_bf16 v[26:29], v[164:167], v[204:207], v[26:29]
	v_mfma_f32_16x16x32_bf16 v[14:17], v[156:159], v[212:215], v[14:17]
	v_mfma_f32_16x16x32_bf16 v[10:13], v[164:167], v[212:215], v[10:13]
	s_setprio 0
	s_setprio 1
	v_mfma_f32_16x16x32_bf16 v[54:57], v[168:171], v[184:187], v[54:57]
	v_mfma_f32_16x16x32_bf16 v[50:53], v[176:179], v[184:187], v[50:53]
	v_mfma_f32_16x16x32_bf16 v[38:41], v[168:171], v[192:195], v[38:41]
	v_mfma_f32_16x16x32_bf16 v[34:37], v[176:179], v[192:195], v[34:37]
	v_mfma_f32_16x16x32_bf16 v[22:25], v[168:171], v[200:203], v[22:25]
	v_mfma_f32_16x16x32_bf16 v[18:21], v[176:179], v[200:203], v[18:21]
	v_mfma_f32_16x16x32_bf16 v[6:9], v[168:171], v[208:211], v[6:9]
	v_mfma_f32_16x16x32_bf16 v[2:5], v[176:179], v[208:211], v[2:5]
	v_mfma_f32_16x16x32_bf16 v[54:57], v[172:175], v[188:191], v[54:57]
	v_mfma_f32_16x16x32_bf16 v[50:53], v[180:183], v[188:191], v[50:53]
	v_mfma_f32_16x16x32_bf16 v[38:41], v[172:175], v[196:199], v[38:41]
	v_mfma_f32_16x16x32_bf16 v[34:37], v[180:183], v[196:199], v[34:37]
	v_mfma_f32_16x16x32_bf16 v[22:25], v[172:175], v[204:207], v[22:25]
	v_mfma_f32_16x16x32_bf16 v[18:21], v[180:183], v[204:207], v[18:21]
	v_mfma_f32_16x16x32_bf16 v[6:9], v[172:175], v[212:215], v[6:9]
	v_mfma_f32_16x16x32_bf16 v[2:5], v[180:183], v[212:215], v[2:5]
	s_setprio 0
	s_add_i32 s44, s44, 2
	s_add_u32 s22, s22, 0x100
	s_addc_u32 s23, s23, 0
	s_add_u32 s42, s42, 0x100
	s_addc_u32 s43, s43, 0
	s_cmp_gt_u32 s44, 29
	s_barrier
	s_cbranch_scc0 .LBB0_2774
	s_and_b64 vcc, exec, s[10:11]
	s_cbranch_vccz .LBB0_2777
	s_barrier

; #define PG8_STAGE(bufoff, gbase, voff) do { _Pragma("unroll") for (int _i = 0; _i < 2; ++_i) \
;         __builtin_amdgcn_global_load_lds((const unsigned*)((const char*)(gbase) + (voff)[_i]), (PG8_LAS unsigned*)(lds + (bufoff) + ldsw + _i * 8192), 16, 0, 0); } while (0)
; #define PG8_LDA(dst, b, h) do { _Pragma("unroll") for (int m = 0; m < 4; ++m) _Pragma("unroll") for (int k = 0; k < 2; ++k) dst[m][k] = *(const PG8_LAS bf16x8*)(lds + PG8_SA(b, h) + aoff + m * 2048 + k * 1024); } while (0)
; #define PG8_LDB(dst, b, h) do { _Pragma("unroll") for (int n = 0; n < 2; ++n) _Pragma("unroll") for (int k = 0; k < 2; ++k) dst[n][k] = *(const PG8_LAS bf16x8*)(lds + PG8_SB(b, h) + boff + n * 2048 + k * 1024); } while (0)
; #define PG8_MMA(ai, bj, At, Bt) do { __builtin_amdgcn_s_setprio(1); _Pragma("unroll") for (int m = 0; m < 4; ++m) _Pragma("unroll") for (int n = 0; n < 2; ++n) _Pragma("unroll") for (int k = 0; k < 2; ++k) \
;         acc[ai][bj][m][n] = __builtin_amdgcn_mfma_f32_16x16x32_bf16(Bt[n][k], At[m][k], acc[ai][bj][m][n], 0, 0, 0); __builtin_amdgcn_s_setprio(0); } while (0)
; #define PG8_WAIT_V(n) asm volatile("s_waitcnt vmcnt(" #n ")" ::: "memory")
; #define PG8_WAIT_L(n) asm volatile("s_waitcnt lgkmcnt(" #n ")" ::: "memory")
; #define PG8_BAR __builtin_amdgcn_s_barrier()
; #define PG8_SCHED __builtin_amdgcn_sched_barrier(0)
; template <class Epi, class Sched, bool ALIGN_EPI = false, bool SP2 = false>
; __device__ __forceinline__ void gemm_phase(PG8_LAS unsigned char* lds, const Gemm g, const Sched& S, const Epi& E) {
;     ...
;             if constexpr (SP2) {
;             PG8_LDB(B0, 0, 0); PG8_LDB(B1, 0, 1); PG8_SCHED; PG8_LDA(At, 0, 0); PG8_STAGE(PG8_SA(1, 1), a1 + hstep, voffA);
;             PG8_WAIT_V(8); PG8_WAIT_L(0); PG8_BAR; PG8_MMA(0, 0, At, B0); PG8_MMA(0, 1, At, B1); PG8_BAR; PG8_SCHED;
;             PG8_LDA(At, 0, 1); PG8_STAGE(PG8_SB(0, 0), b2, voffB); PG8_STAGE(PG8_SB(0, 1), b2 + hstep, voffB); PG8_STAGE(PG8_SA(0, 0), a2, voffA);
;             PG8_WAIT_V(8); PG8_WAIT_L(0); PG8_BAR; PG8_MMA(1, 0, At, B0); PG8_MMA(1, 1, At, B1); PG8_BAR; PG8_SCHED;
.LBB0_2871:
	ds_read_b128 v[152:155], v149
	ds_read_b128 v[156:159], v149 offset:1024
	ds_read_b128 v[160:163], v149 offset:2048
	ds_read_b128 v[164:167], v149 offset:3072
	ds_read_b128 v[168:171], v150
	ds_read_b128 v[172:175], v150 offset:1024
	ds_read_b128 v[176:179], v150 offset:2048
	ds_read_b128 v[180:183], v150 offset:3072
	s_add_u32 s24, s22, 0x100
	s_addc_u32 s25, s23, 0
	s_cmpk_eq_i32 s51, 0x54
	s_cselect_b32 s29, s7, s25
	s_cselect_b32 s28, s6, s24
	s_cselect_b32 s27, s21, s49
	s_cselect_b32 s26, s20, s48
	v_lshl_add_u64 v[216:217], s[22:23], 0, v[138:139]
	s_add_i32 m0, s3, 0xc000
	ds_read_b128 v[184:187], v151
	ds_read_b128 v[188:191], v151 offset:1024
	ds_read_b128 v[192:195], v151 offset:2048
	ds_read_b128 v[196:199], v151 offset:3072
	ds_read_b128 v[200:203], v151 offset:4096
	ds_read_b128 v[204:207], v151 offset:5120
	ds_read_b128 v[208:211], v151 offset:6144
	ds_read_b128 v[212:215], v151 offset:7168
	global_load_lds_dwordx4 v[216:217], off
	v_lshl_add_u64 v[216:217], s[22:23], 0, v[140:141]
	s_add_i32 m0, s3, 0xe000
	s_nop 0
	global_load_lds_dwordx4 v[216:217], off
	s_waitcnt vmcnt(8)
	s_waitcnt lgkmcnt(0)
	s_barrier
	s_setprio 1
	s_waitcnt lgkmcnt(0)
	v_mfma_f32_16x16x32_bf16 v[126:129], v[152:155], v[184:187], v[126:129]
	v_mfma_f32_16x16x32_bf16 v[122:125], v[160:163], v[184:187], v[122:125]
	v_mfma_f32_16x16x32_bf16 v[118:121], v[152:155], v[192:195], v[118:121]
	v_mfma_f32_16x16x32_bf16 v[110:113], v[160:163], v[192:195], v[110:113]
	v_mfma_f32_16x16x32_bf16 v[102:105], v[152:155], v[200:203], v[102:105]
	v_mfma_f32_16x16x32_bf16 v[94:97], v[160:163], v[200:203], v[94:97]
	v_mfma_f32_16x16x32_bf16 v[86:89], v[152:155], v[208:211], v[86:89]
	v_mfma_f32_16x16x32_bf16 v[78:81], v[160:163], v[208:211], v[78:81]
	v_mfma_f32_16x16x32_bf16 v[126:129], v[156:159], v[188:191], v[126:129]
	v_mfma_f32_16x16x32_bf16 v[122:125], v[164:167], v[188:191], v[122:125]
	v_mfma_f32_16x16x32_bf16 v[118:121], v[156:159], v[196:199], v[118:121]
	v_mfma_f32_16x16x32_bf16 v[110:113], v[164:167], v[196:199], v[110:113]
	v_mfma_f32_16x16x32_bf16 v[102:105], v[156:159], v[204:207], v[102:105]
	v_mfma_f32_16x16x32_bf16 v[94:97], v[164:167], v[204:207], v[94:97]
	v_mfma_f32_16x16x32_bf16 v[86:89], v[156:159], v[212:215], v[86:89]
	v_mfma_f32_16x16x32_bf16 v[78:81], v[164:167], v[212:215], v[78:81]
	s_setprio 0
	s_setprio 1
	v_mfma_f32_16x16x32_bf16 v[114:117], v[168:171], v[184:187], v[114:117]
	v_mfma_f32_16x16x32_bf16 v[106:109], v[176:179], v[184:187], v[106:109]
	v_mfma_f32_16x16x32_bf16 v[98:101], v[168:171], v[192:195], v[98:101]
	v_mfma_f32_16x16x32_bf16 v[90:93], v[176:179], v[192:195], v[90:93]
	v_mfma_f32_16x16x32_bf16 v[82:85], v[168:171], v[200:203], v[82:85]
	v_mfma_f32_16x16x32_bf16 v[74:77], v[176:179], v[200:203], v[74:77]
	v_mfma_f32_16x16x32_bf16 v[70:73], v[168:171], v[208:211], v[70:73]
	v_mfma_f32_16x16x32_bf16 v[66:69], v[176:179], v[208:211], v[66:69]
	v_mfma_f32_16x16x32_bf16 v[114:117], v[172:175], v[188:191], v[114:117]
	v_mfma_f32_16x16x32_bf16 v[106:109], v[180:183], v[188:191], v[106:109]
	v_mfma_f32_16x16x32_bf16 v[98:101], v[172:175], v[196:199], v[98:101]
	v_mfma_f32_16x16x32_bf16 v[90:93], v[180:183], v[196:199], v[90:93]
	v_mfma_f32_16x16x32_bf16 v[82:85], v[172:175], v[204:207], v[82:85]
	v_mfma_f32_16x16x32_bf16 v[74:77], v[180:183], v[204:207], v[74:77]
	v_mfma_f32_16x16x32_bf16 v[70:73], v[172:175], v[212:215], v[70:73]
	v_mfma_f32_16x16x32_bf16 v[66:69], v[180:183], v[212:215], v[66:69]
	s_setprio 0
	s_barrier
	s_add_i32 s22, s38, s2
	v_lshl_add_u64 v[216:217], s[26:27], 0, v[132:133]
	s_mov_b32 m0, s22
	ds_read_b128 v[184:187], v151 offset:16384
	ds_read_b128 v[188:191], v151 offset:17408
	ds_read_b128 v[192:195], v151 offset:18432
	ds_read_b128 v[196:199], v151 offset:19456
	ds_read_b128 v[200:203], v151 offset:20480
	ds_read_b128 v[204:207], v151 offset:21504
	ds_read_b128 v[208:211], v151 offset:22528
	ds_read_b128 v[212:215], v151 offset:23552
	global_load_lds_dwordx4 v[216:217], off
	s_add_i32 m0, s22, 0x2000
	s_add_u32 s22, s26, 0x160000
	v_lshl_add_u64 v[218:219], s[26:27], 0, v[136:137]
	s_addc_u32 s23, s27, 0
	s_add_i32 s52, s39, s2
	global_load_lds_dwordx4 v[218:219], off
	v_lshl_add_u64 v[220:221], s[22:23], 0, v[132:133]
	s_mov_b32 m0, s52
	v_lshl_add_u64 v[222:223], s[28:29], 0, v[134:135]
	global_load_lds_dwordx4 v[220:221], off
	v_lshl_add_u64 v[220:221], s[22:23], 0, v[136:137]
	s_add_i32 m0, s52, 0x2000
	s_nop 0
	global_load_lds_dwordx4 v[220:221], off
	v_lshl_add_u64 v[220:221], s[28:29], 0, v[130:131]
	s_mov_b32 m0, s3
	s_nop 0
	global_load_lds_dwordx4 v[220:221], off
	s_mov_b32 m0, s30
	s_nop 0
	global_load_lds_dwordx4 v[222:223], off
	s_waitcnt vmcnt(8)
	s_waitcnt lgkmcnt(0)
	s_barrier
; #define PG8_STAGE(bufoff, gbase, voff) do { _Pragma("unroll") for (int _i = 0; _i < 2; ++_i) \
;         __builtin_amdgcn_global_load_lds((const unsigned*)((const char*)(gbase) + (voff)[_i]), (PG8_LAS unsigned*)(lds + (bufoff) + ldsw + _i * 8192), 16, 0, 0); } while (0)
; #define PG8_LDA(dst, b, h) do { _Pragma("unroll") for (int m = 0; m < 4; ++m) _Pragma("unroll") for (int k = 0; k < 2; ++k) dst[m][k] = *(const PG8_LAS bf16x8*)(lds + PG8_SA(b, h) + aoff + m * 2048 + k * 1024); } while (0)
; #define PG8_LDB(dst, b, h) do { _Pragma("unroll") for (int n = 0; n < 2; ++n) _Pragma("unroll") for (int k = 0; k < 2; ++k) dst[n][k] = *(const PG8_LAS bf16x8*)(lds + PG8_SB(b, h) + boff + n * 2048 + k * 1024); } while (0)
; #define PG8_MMA(ai, bj, At, Bt) do { __builtin_amdgcn_s_setprio(1); _Pragma("unroll") for (int m = 0; m < 4; ++m) _Pragma("unroll") for (int n = 0; n < 2; ++n) _Pragma("unroll") for (int k = 0; k < 2; ++k) \
;         acc[ai][bj][m][n] = __builtin_amdgcn_mfma_f32_16x16x32_bf16(Bt[n][k], At[m][k], acc[ai][bj][m][n], 0, 0, 0); __builtin_amdgcn_s_setprio(0); } while (0)
; #define PG8_WAIT_V(n) asm volatile("s_waitcnt vmcnt(" #n ")" ::: "memory")
; #define PG8_WAIT_L(n) asm volatile("s_waitcnt lgkmcnt(" #n ")" ::: "memory")
; #define PG8_BAR __builtin_amdgcn_s_barrier()
; #define PG8_SCHED __builtin_amdgcn_sched_barrier(0)
; template <class Epi, class Sched, bool ALIGN_EPI = false, bool SP2 = false>
; __device__ __forceinline__ void gemm_phase(PG8_LAS unsigned char* lds, const Gemm g, const Sched& S, const Epi& E) {
;     ...
;             PG8_WAIT_V(8); PG8_WAIT_L(0); PG8_BAR; PG8_MMA(1, 0, At, B0); PG8_MMA(1, 1, At, B1); PG8_BAR; PG8_SCHED;
;             PG8_LDB(B0, 1, 0); PG8_LDB(B1, 1, 1); PG8_SCHED; PG8_LDA(At, 1, 0); PG8_STAGE(PG8_SA(0, 1), a2 + hstep, voffA);
;             PG8_WAIT_V(8); PG8_WAIT_L(0); PG8_BAR; PG8_MMA(0, 0, At, B0); PG8_MMA(0, 1, At, B1); PG8_BAR; PG8_SCHED;
	s_setprio 1
	s_waitcnt lgkmcnt(0)
	v_mfma_f32_16x16x32_bf16 v[62:65], v[152:155], v[184:187], v[62:65]
	v_mfma_f32_16x16x32_bf16 v[58:61], v[160:163], v[184:187], v[58:61]
	v_mfma_f32_16x16x32_bf16 v[54:57], v[152:155], v[192:195], v[54:57]
	v_mfma_f32_16x16x32_bf16 v[50:53], v[160:163], v[192:195], v[50:53]
	v_mfma_f32_16x16x32_bf16 v[38:41], v[152:155], v[200:203], v[38:41]
	v_mfma_f32_16x16x32_bf16 v[34:37], v[160:163], v[200:203], v[34:37]
	v_mfma_f32_16x16x32_bf16 v[22:25], v[152:155], v[208:211], v[22:25]
	v_mfma_f32_16x16x32_bf16 v[18:21], v[160:163], v[208:211], v[18:21]
	v_mfma_f32_16x16x32_bf16 v[62:65], v[156:159], v[188:191], v[62:65]
	v_mfma_f32_16x16x32_bf16 v[58:61], v[164:167], v[188:191], v[58:61]
	v_mfma_f32_16x16x32_bf16 v[54:57], v[156:159], v[196:199], v[54:57]
	v_mfma_f32_16x16x32_bf16 v[50:53], v[164:167], v[196:199], v[50:53]
	v_mfma_f32_16x16x32_bf16 v[38:41], v[156:159], v[204:207], v[38:41]
	v_mfma_f32_16x16x32_bf16 v[34:37], v[164:167], v[204:207], v[34:37]
	v_mfma_f32_16x16x32_bf16 v[22:25], v[156:159], v[212:215], v[22:25]
	v_mfma_f32_16x16x32_bf16 v[18:21], v[164:167], v[212:215], v[18:21]
	s_setprio 0
	s_setprio 1
	v_mfma_f32_16x16x32_bf16 v[46:49], v[168:171], v[184:187], v[46:49]
	v_mfma_f32_16x16x32_bf16 v[42:45], v[176:179], v[184:187], v[42:45]
	v_mfma_f32_16x16x32_bf16 v[30:33], v[168:171], v[192:195], v[30:33]
	v_mfma_f32_16x16x32_bf16 v[26:29], v[176:179], v[192:195], v[26:29]
	v_mfma_f32_16x16x32_bf16 v[14:17], v[168:171], v[200:203], v[14:17]
	v_mfma_f32_16x16x32_bf16 v[10:13], v[176:179], v[200:203], v[10:13]
	v_mfma_f32_16x16x32_bf16 v[6:9], v[168:171], v[208:211], v[6:9]
	v_mfma_f32_16x16x32_bf16 v[2:5], v[176:179], v[208:211], v[2:5]
	v_mfma_f32_16x16x32_bf16 v[46:49], v[172:175], v[188:191], v[46:49]
	v_mfma_f32_16x16x32_bf16 v[42:45], v[180:183], v[188:191], v[42:45]
	v_mfma_f32_16x16x32_bf16 v[30:33], v[172:175], v[196:199], v[30:33]
	v_mfma_f32_16x16x32_bf16 v[26:29], v[180:183], v[196:199], v[26:29]
	v_mfma_f32_16x16x32_bf16 v[14:17], v[172:175], v[204:207], v[14:17]
	v_mfma_f32_16x16x32_bf16 v[10:13], v[180:183], v[204:207], v[10:13]
	v_mfma_f32_16x16x32_bf16 v[6:9], v[172:175], v[212:215], v[6:9]
	v_mfma_f32_16x16x32_bf16 v[2:5], v[180:183], v[212:215], v[2:5]
	s_setprio 0
	s_barrier
	s_add_i32 s52, 0, 0x18000
	s_add_i32 s53, 0, 0x1c000
	v_add_u32_e32 v164, s52, v1
	v_add_u32_e32 v180, s53, v1
	ds_read_b128 v[152:155], v164
	ds_read_b128 v[156:159], v164 offset:1024
	ds_read_b128 v[160:163], v164 offset:2048
	ds_read_b128 v[164:167], v164 offset:3072
	ds_read_b128 v[168:171], v180
	ds_read_b128 v[172:175], v180 offset:1024
	ds_read_b128 v[176:179], v180 offset:2048
	ds_read_b128 v[180:183], v180 offset:3072
	s_add_u32 s22, s28, 0x160000
	s_addc_u32 s23, s29, 0
	s_mov_b32 m0, s31
	v_lshl_add_u64 v[224:225], s[22:23], 0, v[130:131]
	ds_read_b128 v[184:187], v151 offset:32768
	ds_read_b128 v[188:191], v151 offset:33792
	ds_read_b128 v[192:195], v151 offset:34816
	ds_read_b128 v[196:199], v151 offset:35840
	ds_read_b128 v[200:203], v151 offset:36864
	ds_read_b128 v[204:207], v151 offset:37888
	ds_read_b128 v[208:211], v151 offset:38912
	ds_read_b128 v[212:215], v151 offset:39936
	global_load_lds_dwordx4 v[224:225], off
	v_lshl_add_u64 v[224:225], s[22:23], 0, v[134:135]
	s_mov_b32 m0, s34
	s_nop 0
	global_load_lds_dwordx4 v[224:225], off
	s_waitcnt vmcnt(8)
	s_waitcnt lgkmcnt(0)
	s_barrier
	s_setprio 1
	s_waitcnt lgkmcnt(0)
	v_mfma_f32_16x16x32_bf16 v[126:129], v[152:155], v[184:187], v[126:129]
	v_mfma_f32_16x16x32_bf16 v[122:125], v[160:163], v[184:187], v[122:125]
	v_mfma_f32_16x16x32_bf16 v[118:121], v[152:155], v[192:195], v[118:121]
	v_mfma_f32_16x16x32_bf16 v[110:113], v[160:163], v[192:195], v[110:113]
	v_mfma_f32_16x16x32_bf16 v[102:105], v[152:155], v[200:203], v[102:105]
	v_mfma_f32_16x16x32_bf16 v[94:97], v[160:163], v[200:203], v[94:97]
	v_mfma_f32_16x16x32_bf16 v[86:89], v[152:155], v[208:211], v[86:89]
	v_mfma_f32_16x16x32_bf16 v[78:81], v[160:163], v[208:211], v[78:81]
	v_mfma_f32_16x16x32_bf16 v[126:129], v[156:159], v[188:191], v[126:129]
	v_mfma_f32_16x16x32_bf16 v[122:125], v[164:167], v[188:191], v[122:125]
	v_mfma_f32_16x16x32_bf16 v[118:121], v[156:159], v[196:199], v[118:121]
	v_mfma_f32_16x16x32_bf16 v[110:113], v[164:167], v[196:199], v[110:113]
	v_mfma_f32_16x16x32_bf16 v[102:105], v[156:159], v[204:207], v[102:105]
	v_mfma_f32_16x16x32_bf16 v[94:97], v[164:167], v[204:207], v[94:97]
	v_mfma_f32_16x16x32_bf16 v[86:89], v[156:159], v[212:215], v[86:89]
	v_mfma_f32_16x16x32_bf16 v[78:81], v[164:167], v[212:215], v[78:81]
	s_setprio 0
	s_setprio 1
	v_mfma_f32_16x16x32_bf16 v[114:117], v[168:171], v[184:187], v[114:117]
	v_mfma_f32_16x16x32_bf16 v[106:109], v[176:179], v[184:187], v[106:109]
	v_mfma_f32_16x16x32_bf16 v[98:101], v[168:171], v[192:195], v[98:101]
	v_mfma_f32_16x16x32_bf16 v[90:93], v[176:179], v[192:195], v[90:93]
	v_mfma_f32_16x16x32_bf16 v[82:85], v[168:171], v[200:203], v[82:85]
	v_mfma_f32_16x16x32_bf16 v[74:77], v[176:179], v[200:203], v[74:77]
	v_mfma_f32_16x16x32_bf16 v[70:73], v[168:171], v[208:211], v[70:73]
	v_mfma_f32_16x16x32_bf16 v[66:69], v[176:179], v[208:211], v[66:69]
	v_mfma_f32_16x16x32_bf16 v[114:117], v[172:175], v[188:191], v[114:117]
	v_mfma_f32_16x16x32_bf16 v[106:109], v[180:183], v[188:191], v[106:109]
	v_mfma_f32_16x16x32_bf16 v[98:101], v[172:175], v[196:199], v[98:101]
	v_mfma_f32_16x16x32_bf16 v[90:93], v[180:183], v[196:199], v[90:93]
	v_mfma_f32_16x16x32_bf16 v[82:85], v[172:175], v[204:207], v[82:85]
	v_mfma_f32_16x16x32_bf16 v[74:77], v[180:183], v[204:207], v[74:77]
	v_mfma_f32_16x16x32_bf16 v[70:73], v[172:175], v[212:215], v[70:73]
	v_mfma_f32_16x16x32_bf16 v[66:69], v[180:183], v[212:215], v[66:69]
	s_setprio 0
	s_barrier
; #define PG8_STAGE(bufoff, gbase, voff) do { _Pragma("unroll") for (int _i = 0; _i < 2; ++_i) \
;         __builtin_amdgcn_global_load_lds((const unsigned*)((const char*)(gbase) + (voff)[_i]), (PG8_LAS unsigned*)(lds + (bufoff) + ldsw + _i * 8192), 16, 0, 0); } while (0)
; #define PG8_LDA(dst, b, h) do { _Pragma("unroll") for (int m = 0; m < 4; ++m) _Pragma("unroll") for (int k = 0; k < 2; ++k) dst[m][k] = *(const PG8_LAS bf16x8*)(lds + PG8_SA(b, h) + aoff + m * 2048 + k * 1024); } while (0)
; #define PG8_MMA(ai, bj, At, Bt) do { __builtin_amdgcn_s_setprio(1); _Pragma("unroll") for (int m = 0; m < 4; ++m) _Pragma("unroll") for (int n = 0; n < 2; ++n) _Pragma("unroll") for (int k = 0; k < 2; ++k) \
;         acc[ai][bj][m][n] = __builtin_amdgcn_mfma_f32_16x16x32_bf16(Bt[n][k], At[m][k], acc[ai][bj][m][n], 0, 0, 0); __builtin_amdgcn_s_setprio(0); } while (0)
; #define PG8_WAIT_V(n) asm volatile("s_waitcnt vmcnt(" #n ")" ::: "memory")
; #define PG8_WAIT_L(n) asm volatile("s_waitcnt lgkmcnt(" #n ")" ::: "memory")
; #define PG8_BAR __builtin_amdgcn_s_barrier()
; #define PG8_SCHED __builtin_amdgcn_sched_barrier(0)
; template <class Epi, class Sched, bool ALIGN_EPI = false, bool SP2 = false>
; __device__ __forceinline__ void gemm_phase(PG8_LAS unsigned char* lds, const Gemm g, const Sched& S, const Epi& E) {
;     ...
;         for (int t = 0; t < nt; t += 2) {
;             const bool last = (t == nt - 2);
;             const char* a1 = cA + (size_t)(t + 1) * kstep;
;             const char* a2 = last ? nA : cA + (size_t)(t + 2) * kstep; const char* b2 = last ? nB : cB + (size_t)(t + 2) * kstep;
;             const char* a3 = a2 + kstep; const char* b3 = b2 + kstep;
;     ...
;             PG8_LDA(At, 1, 1); PG8_STAGE(PG8_SB(1, 0), b3, voffB); PG8_STAGE(PG8_SB(1, 1), b3 + hstep, voffB); PG8_STAGE(PG8_SA(1, 0), a3, voffA);
;             PG8_WAIT_V(8); PG8_WAIT_L(0); PG8_BAR; PG8_MMA(1, 0, At, B0); PG8_MMA(1, 1, At, B1); PG8_BAR; PG8_SCHED;
	s_add_i32 s22, s52, s2
	v_lshl_add_u64 v[216:217], v[216:217], 0, s[8:9]
	s_mov_b32 m0, s22
	ds_read_b128 v[184:187], v151 offset:49152
	ds_read_b128 v[188:191], v151 offset:50176
	ds_read_b128 v[192:195], v151 offset:51200
	ds_read_b128 v[196:199], v151 offset:52224
	ds_read_b128 v[200:203], v151 offset:53248
	ds_read_b128 v[204:207], v151 offset:54272
	ds_read_b128 v[208:211], v151 offset:55296
	ds_read_b128 v[212:215], v151 offset:56320
	global_load_lds_dwordx4 v[216:217], off
	s_add_i32 m0, s22, 0x2000
	s_add_u32 s22, s26, 0x160080
	v_lshl_add_u64 v[216:217], v[218:219], 0, s[8:9]
	s_addc_u32 s23, s27, 0
	s_add_i32 s26, s53, s2
	global_load_lds_dwordx4 v[216:217], off
	v_lshl_add_u64 v[216:217], s[22:23], 0, v[132:133]
	s_mov_b32 m0, s26
	s_nop 0
	global_load_lds_dwordx4 v[216:217], off
	v_lshl_add_u64 v[216:217], s[22:23], 0, v[136:137]
	s_add_i32 m0, s26, 0x2000
	s_nop 0
	global_load_lds_dwordx4 v[216:217], off
	v_lshl_add_u64 v[216:217], v[220:221], 0, s[8:9]
	s_mov_b32 m0, s36
	s_nop 0
	global_load_lds_dwordx4 v[216:217], off
	v_lshl_add_u64 v[216:217], v[222:223], 0, s[8:9]
	s_mov_b32 m0, s37
	s_nop 0
	global_load_lds_dwordx4 v[216:217], off
	s_waitcnt vmcnt(8)
	s_waitcnt lgkmcnt(0)
	s_barrier
	s_setprio 1
	s_waitcnt lgkmcnt(0)
	v_mfma_f32_16x16x32_bf16 v[62:65], v[152:155], v[184:187], v[62:65]
	v_mfma_f32_16x16x32_bf16 v[58:61], v[160:163], v[184:187], v[58:61]
	v_mfma_f32_16x16x32_bf16 v[54:57], v[152:155], v[192:195], v[54:57]
	v_mfma_f32_16x16x32_bf16 v[50:53], v[160:163], v[192:195], v[50:53]
	v_mfma_f32_16x16x32_bf16 v[38:41], v[152:155], v[200:203], v[38:41]
	v_mfma_f32_16x16x32_bf16 v[34:37], v[160:163], v[200:203], v[34:37]
	v_mfma_f32_16x16x32_bf16 v[22:25], v[152:155], v[208:211], v[22:25]
	v_mfma_f32_16x16x32_bf16 v[18:21], v[160:163], v[208:211], v[18:21]
	v_mfma_f32_16x16x32_bf16 v[62:65], v[156:159], v[188:191], v[62:65]
	v_mfma_f32_16x16x32_bf16 v[58:61], v[164:167], v[188:191], v[58:61]
	v_mfma_f32_16x16x32_bf16 v[54:57], v[156:159], v[196:199], v[54:57]
	v_mfma_f32_16x16x32_bf16 v[50:53], v[164:167], v[196:199], v[50:53]
	v_mfma_f32_16x16x32_bf16 v[38:41], v[156:159], v[204:207], v[38:41]
	v_mfma_f32_16x16x32_bf16 v[34:37], v[164:167], v[204:207], v[34:37]
	v_mfma_f32_16x16x32_bf16 v[22:25], v[156:159], v[212:215], v[22:25]
	v_mfma_f32_16x16x32_bf16 v[18:21], v[164:167], v[212:215], v[18:21]
	s_setprio 0
	s_setprio 1
	v_mfma_f32_16x16x32_bf16 v[46:49], v[168:171], v[184:187], v[46:49]
	v_mfma_f32_16x16x32_bf16 v[42:45], v[176:179], v[184:187], v[42:45]
	v_mfma_f32_16x16x32_bf16 v[30:33], v[168:171], v[192:195], v[30:33]
	v_mfma_f32_16x16x32_bf16 v[26:29], v[176:179], v[192:195], v[26:29]
	v_mfma_f32_16x16x32_bf16 v[14:17], v[168:171], v[200:203], v[14:17]
	v_mfma_f32_16x16x32_bf16 v[10:13], v[176:179], v[200:203], v[10:13]
	v_mfma_f32_16x16x32_bf16 v[6:9], v[168:171], v[208:211], v[6:9]
	v_mfma_f32_16x16x32_bf16 v[2:5], v[176:179], v[208:211], v[2:5]
	v_mfma_f32_16x16x32_bf16 v[46:49], v[172:175], v[188:191], v[46:49]
	v_mfma_f32_16x16x32_bf16 v[42:45], v[180:183], v[188:191], v[42:45]
	v_mfma_f32_16x16x32_bf16 v[30:33], v[172:175], v[196:199], v[30:33]
	v_mfma_f32_16x16x32_bf16 v[26:29], v[180:183], v[196:199], v[26:29]
	v_mfma_f32_16x16x32_bf16 v[14:17], v[172:175], v[204:207], v[14:17]
	v_mfma_f32_16x16x32_bf16 v[10:13], v[180:183], v[204:207], v[10:13]
	v_mfma_f32_16x16x32_bf16 v[6:9], v[172:175], v[212:215], v[6:9]
	v_mfma_f32_16x16x32_bf16 v[2:5], v[180:183], v[212:215], v[2:5]
	s_setprio 0
	s_add_i32 s51, s51, 2
	s_add_u32 s48, s48, 0x100
	s_addc_u32 s49, s49, 0
	s_cmpk_gt_u32 s51, 0x55
	s_mov_b64 s[22:23], s[24:25]
	s_barrier
	s_cbranch_scc0 .LBB0_2871
	s_and_b64 vcc, exec, s[10:11]
	s_cbranch_vccz .LBB0_2874
	s_barrier
